# phase2 conformer conv tile rewritten by hand: pipelined GLU staging, row-major conv from registers (62 LDS reads instead of 992), one transposed butterfly for all 64 LN sums, hardware bf16 pack
# speedup vs baseline: 1.1388x; 1.0189x over previous
; DEVI int launder(int x) { asm volatile("" : "+v"(x)); return x; }
; DEVI void conv_tile(const Params& p, unsigned char* smem, int ct) {
;   u16* sU = (u16*)smem;
;   float2* sRed = (float2*)(smem + 62 * 512 * 2);
;   const int tid = launder(threadIdx.x), lane = tid & 63, w = tid >> 6;
;   const int b = ct >> 6, t0 = (ct & 63) * 32;
;   __syncthreads();
;   for (int it = tid; it < 62 * 64; it += 256) {
;     const int r = it >> 6, c8 = it & 63;
;     const int t = t0 - 30 + r;
;     uint4 pk = {0u, 0u, 0u, 0u};
;     if (t >= 0) {
;       const u16* src = p.proj + ((size_t)b * T + t) * LDP + c8 * 8;
;       const uint4 a = *(const uint4*)src, bb = *(const uint4*)(src + 512);
;     ...
;   const int c = 2 * tid;
;   float w0[31], w1[31];
; #pragma unroll
;   for (int j = 0; j < 31; ++j) { w0[j] = p.conv_w[j * 512 + c]; w1[j] = p.conv_w[j * 512 + c + 1]; }
;   const float bd0 = p.conv_b[c], bd1 = p.conv_b[c + 1];
.LBB0_555:
	s_sub_i32 s33, s35, 64
	s_lshr_b32 s8, s33, 6
	s_lshl_b32 s33, s33, 5
	s_and_b32 s22, s33, 0x7e0
	s_load_dwordx2 s[0:1], s[68:69], 0xe8
	s_load_dwordx2 s[2:3], s[68:69], 0xf0
	s_load_dwordx2 s[4:5], s[68:69], 0x28
	s_load_dwordx2 s[36:37], s[68:69], 0x30
	s_load_dwordx2 s[38:39], s[68:69], 0x38
	s_load_dwordx2 s[72:73], s[68:69], 0x40
	v_and_b32_e32 v32, 63, v210
	v_lshlrev_b32_e32 v211, 4, v32
	v_lshrrev_b32_e32 v212, 6, v210
	v_lshlrev_b32_e32 v209, 2, v210
	v_xor_b32_e32 v213, 16, v32
	v_lshlrev_b32_e32 v213, 2, v213
	v_xor_b32_e32 v214, 4, v32
	v_lshlrev_b32_e32 v214, 2, v214
	s_waitcnt lgkmcnt(0)
	s_mul_i32 s33, s8, 0x920000
	s_add_u32 s0, s0, s33
	s_addc_u32 s1, s1, 0
	s_lshl_b32 s33, s8, 11
	s_add_u32 s33, s33, s22
	s_mul_i32 s33, s33, 0x880
	s_add_u32 s2, s2, s33
	s_addc_u32 s3, s3, 0
	s_barrier
	v_lshlrev_b32_e32 v33, 1, v209
	global_load_dwordx2 v[66:67], v33, s[4:5]
	s_add_u32 s4, s4, 0x800
	s_addc_u32 s5, s5, 0
	global_load_dwordx2 v[68:69], v33, s[4:5]
	s_add_u32 s4, s4, 0x800
	s_addc_u32 s5, s5, 0
	global_load_dwordx2 v[70:71], v33, s[4:5]
	s_add_u32 s4, s4, 0x800
	s_addc_u32 s5, s5, 0
	global_load_dwordx2 v[72:73], v33, s[4:5]
	s_add_u32 s4, s4, 0x800
	s_addc_u32 s5, s5, 0
	global_load_dwordx2 v[74:75], v33, s[4:5]
	s_add_u32 s4, s4, 0x800
	s_addc_u32 s5, s5, 0
	global_load_dwordx2 v[76:77], v33, s[4:5]
	s_add_u32 s4, s4, 0x800
	s_addc_u32 s5, s5, 0
	global_load_dwordx2 v[78:79], v33, s[4:5]
	s_add_u32 s4, s4, 0x800
	s_addc_u32 s5, s5, 0
	global_load_dwordx2 v[80:81], v33, s[4:5]
	s_add_u32 s4, s4, 0x800
	s_addc_u32 s5, s5, 0
	global_load_dwordx2 v[82:83], v33, s[4:5]
	s_add_u32 s4, s4, 0x800
	s_addc_u32 s5, s5, 0
	global_load_dwordx2 v[84:85], v33, s[4:5]
	s_add_u32 s4, s4, 0x800
	s_addc_u32 s5, s5, 0
	global_load_dwordx2 v[86:87], v33, s[4:5]
	s_add_u32 s4, s4, 0x800
	s_addc_u32 s5, s5, 0
	global_load_dwordx2 v[88:89], v33, s[4:5]
	s_add_u32 s4, s4, 0x800
	s_addc_u32 s5, s5, 0
	global_load_dwordx2 v[90:91], v33, s[4:5]
	s_add_u32 s4, s4, 0x800
	s_addc_u32 s5, s5, 0
	global_load_dwordx2 v[92:93], v33, s[4:5]
	s_add_u32 s4, s4, 0x800
	s_addc_u32 s5, s5, 0
	global_load_dwordx2 v[94:95], v33, s[4:5]
	s_add_u32 s4, s4, 0x800
	s_addc_u32 s5, s5, 0
	global_load_dwordx2 v[96:97], v33, s[4:5]
	s_add_u32 s4, s4, 0x800
	s_addc_u32 s5, s5, 0
	global_load_dwordx2 v[98:99], v33, s[4:5]
	s_add_u32 s4, s4, 0x800
	s_addc_u32 s5, s5, 0
	global_load_dwordx2 v[100:101], v33, s[4:5]
	s_add_u32 s4, s4, 0x800
	s_addc_u32 s5, s5, 0
	global_load_dwordx2 v[102:103], v33, s[4:5]
	s_add_u32 s4, s4, 0x800
	s_addc_u32 s5, s5, 0
	global_load_dwordx2 v[104:105], v33, s[4:5]
	s_add_u32 s4, s4, 0x800
	s_addc_u32 s5, s5, 0
	global_load_dwordx2 v[106:107], v33, s[4:5]
	s_add_u32 s4, s4, 0x800
	s_addc_u32 s5, s5, 0
	global_load_dwordx2 v[108:109], v33, s[4:5]
	s_add_u32 s4, s4, 0x800
	s_addc_u32 s5, s5, 0
	global_load_dwordx2 v[110:111], v33, s[4:5]
	s_add_u32 s4, s4, 0x800
	s_addc_u32 s5, s5, 0
	global_load_dwordx2 v[112:113], v33, s[4:5]
	s_add_u32 s4, s4, 0x800
	s_addc_u32 s5, s5, 0
	global_load_dwordx2 v[114:115], v33, s[4:5]
	s_add_u32 s4, s4, 0x800
	s_addc_u32 s5, s5, 0
	global_load_dwordx2 v[116:117], v33, s[4:5]
	s_add_u32 s4, s4, 0x800
	s_addc_u32 s5, s5, 0
	global_load_dwordx2 v[118:119], v33, s[4:5]
	s_add_u32 s4, s4, 0x800
	s_addc_u32 s5, s5, 0
	global_load_dwordx2 v[120:121], v33, s[4:5]
	s_add_u32 s4, s4, 0x800
	s_addc_u32 s5, s5, 0
	global_load_dwordx2 v[122:123], v33, s[4:5]
	s_add_u32 s4, s4, 0x800
	s_addc_u32 s5, s5, 0
	global_load_dwordx2 v[124:125], v33, s[4:5]
	s_add_u32 s4, s4, 0x800
	s_addc_u32 s5, s5, 0
	global_load_dwordx2 v[126:127], v33, s[4:5]
	global_load_dwordx2 v[192:193], v33, s[36:37]
	global_load_dwordx2 v[194:195], v33, s[38:39]
	global_load_dwordx2 v[196:197], v33, s[72:73]
	v_add_u32_e32 v34, 0, v212
	v_min_u32_e32 v34, 61, v34
	v_add_u32_e32 v35, s22, v34
	v_subrev_u32_e32 v35, 30, v35
	v_max_i32_e32 v38, 0, v35
	v_mul_u32_u24_e32 v36, 0x1240, v38
	v_add_u32_e32 v36, v211, v36
	v_mov_b32_e32 v42, v35
	v_mov_b32_e32 v46, v34
	global_load_dwordx4 v[0:3], v36, s[0:1]
	global_load_dwordx4 v[4:7], v36, s[0:1] offset:1024
	v_add_u32_e32 v34, 4, v212
	v_min_u32_e32 v34, 61, v34
	v_add_u32_e32 v35, s22, v34
	v_subrev_u32_e32 v35, 30, v35
	v_max_i32_e32 v39, 0, v35
	v_mul_u32_u24_e32 v36, 0x1240, v39
	v_add_u32_e32 v36, v211, v36
	v_mov_b32_e32 v43, v35
	v_mov_b32_e32 v47, v34
	global_load_dwordx4 v[8:11], v36, s[0:1]
	global_load_dwordx4 v[12:15], v36, s[0:1] offset:1024
	v_add_u32_e32 v34, 8, v212
	v_min_u32_e32 v34, 61, v34
	v_add_u32_e32 v35, s22, v34
	v_subrev_u32_e32 v35, 30, v35
	v_max_i32_e32 v40, 0, v35
	v_mul_u32_u24_e32 v36, 0x1240, v40
	v_add_u32_e32 v36, v211, v36
	v_mov_b32_e32 v44, v35
	v_mov_b32_e32 v48, v34
	global_load_dwordx4 v[16:19], v36, s[0:1]
	global_load_dwordx4 v[20:23], v36, s[0:1] offset:1024
	v_add_u32_e32 v34, 12, v212
	v_min_u32_e32 v34, 61, v34
	v_add_u32_e32 v35, s22, v34
	v_subrev_u32_e32 v35, 30, v35
	v_max_i32_e32 v41, 0, v35
	v_mul_u32_u24_e32 v36, 0x1240, v41
	v_add_u32_e32 v36, v211, v36
	v_mov_b32_e32 v45, v35
	v_mov_b32_e32 v49, v34
	global_load_dwordx4 v[24:27], v36, s[0:1]
	global_load_dwordx4 v[28:31], v36, s[0:1] offset:1024
	s_waitcnt vmcnt(6)
; DEVI unsigned pack2(float a, float b) { return (unsigned)f2bf(a) | ((unsigned)f2bf(b) << 16); }
; DEVI float sigmoidf_(float x) { return __builtin_amdgcn_rcpf(1.f + __expf(-x)); }
; DEVI void conv_tile(const Params& p, unsigned char* smem, int ct) {
;     ...
;   for (int it = tid; it < 62 * 64; it += 256) {
;     const int r = it >> 6, c8 = it & 63;
;     const int t = t0 - 30 + r;
;     uint4 pk = {0u, 0u, 0u, 0u};
;     if (t >= 0) {
;       const u16* src = p.proj + ((size_t)b * T + t) * LDP + c8 * 8;
;       const uint4 a = *(const uint4*)src, bb = *(const uint4*)(src + 512);
;       const unsigned au[4] = {a.x, a.y, a.z, a.w}, bu[4] = {bb.x, bb.y, bb.z, bb.w};
;       unsigned o[4];
; #pragma unroll
;       for (int j = 0; j < 4; ++j) {
;         const float a0 = __uint_as_float(au[j] << 16), a1 = __uint_as_float(au[j] & 0xffff0000u);
;         const float b0 = __uint_as_float(bu[j] << 16), b1 = __uint_as_float(bu[j] & 0xffff0000u);
;         o[j] = pack2(a0 * sigmoidf_(b0), a1 * sigmoidf_(b1));
;       }
;       pk.x = o[0]; pk.y = o[1]; pk.z = o[2]; pk.w = o[3];
;     }
;     *(uint4*)(sU + r * 512 + c8 * 8) = pk;
;   }
	v_lshlrev_b32_e32 v50, 16, v0
	v_and_b32_e32 v51, 0xffff0000, v0
	v_lshlrev_b32_e32 v52, 16, v4
	v_and_b32_e32 v53, 0xffff0000, v4
	v_mul_f32_e32 v54, 0xbfb8aa3b, v52
	v_exp_f32_e32 v54, v54
	s_nop 0
	v_add_f32_e32 v54, 0x3f800000, v54
	v_rcp_f32_e32 v54, v54
	s_nop 0
	v_mul_f32_e32 v50, v50, v54
	v_mul_f32_e32 v55, 0xbfb8aa3b, v53
	v_exp_f32_e32 v55, v55
	s_nop 0
	v_add_f32_e32 v55, 0x3f800000, v55
	v_rcp_f32_e32 v55, v55
	s_nop 0
	v_mul_f32_e32 v51, v51, v55
	v_cvt_pk_bf16_f32 v240, v50, v51
	v_lshlrev_b32_e32 v50, 16, v1
	v_and_b32_e32 v51, 0xffff0000, v1
	v_lshlrev_b32_e32 v52, 16, v5
	v_and_b32_e32 v53, 0xffff0000, v5
	v_mul_f32_e32 v54, 0xbfb8aa3b, v52
	v_exp_f32_e32 v54, v54
	s_nop 0
	v_add_f32_e32 v54, 0x3f800000, v54
	v_rcp_f32_e32 v54, v54
	s_nop 0
	v_mul_f32_e32 v50, v50, v54
	v_mul_f32_e32 v55, 0xbfb8aa3b, v53
	v_exp_f32_e32 v55, v55
	s_nop 0
	v_add_f32_e32 v55, 0x3f800000, v55
	v_rcp_f32_e32 v55, v55
	s_nop 0
	v_mul_f32_e32 v51, v51, v55
	v_cvt_pk_bf16_f32 v241, v50, v51
	v_lshlrev_b32_e32 v50, 16, v2
	v_and_b32_e32 v51, 0xffff0000, v2
	v_lshlrev_b32_e32 v52, 16, v6
	v_and_b32_e32 v53, 0xffff0000, v6
	v_mul_f32_e32 v54, 0xbfb8aa3b, v52
	v_exp_f32_e32 v54, v54
	s_nop 0
	v_add_f32_e32 v54, 0x3f800000, v54
	v_rcp_f32_e32 v54, v54
	s_nop 0
	v_mul_f32_e32 v50, v50, v54
	v_mul_f32_e32 v55, 0xbfb8aa3b, v53
	v_exp_f32_e32 v55, v55
	s_nop 0
	v_add_f32_e32 v55, 0x3f800000, v55
	v_rcp_f32_e32 v55, v55
	s_nop 0
	v_mul_f32_e32 v51, v51, v55
	v_cvt_pk_bf16_f32 v242, v50, v51
	v_lshlrev_b32_e32 v50, 16, v3
	v_and_b32_e32 v51, 0xffff0000, v3
	v_lshlrev_b32_e32 v52, 16, v7
	v_and_b32_e32 v53, 0xffff0000, v7
	v_mul_f32_e32 v54, 0xbfb8aa3b, v52
	v_exp_f32_e32 v54, v54
	s_nop 0
	v_add_f32_e32 v54, 0x3f800000, v54
	v_rcp_f32_e32 v54, v54
	s_nop 0
	v_mul_f32_e32 v50, v50, v54
	v_mul_f32_e32 v55, 0xbfb8aa3b, v53
	v_exp_f32_e32 v55, v55
	s_nop 0
	v_add_f32_e32 v55, 0x3f800000, v55
	v_rcp_f32_e32 v55, v55
	s_nop 0
	v_mul_f32_e32 v51, v51, v55
	v_cvt_pk_bf16_f32 v243, v50, v51
	v_cmp_gt_i32_e32 vcc, 0, v42
	v_mov_b32_e32 v56, 0
	s_nop 1
	v_cndmask_b32_e32 v240, v240, v56, vcc
	v_cndmask_b32_e32 v241, v241, v56, vcc
	v_cndmask_b32_e32 v242, v242, v56, vcc
	v_cndmask_b32_e32 v243, v243, v56, vcc
	v_lshlrev_b32_e32 v37, 10, v46
	v_add_u32_e32 v37, v211, v37
	ds_write_b128 v37, v[240:243]
	s_waitcnt vmcnt(4)
	v_lshlrev_b32_e32 v50, 16, v8
	v_and_b32_e32 v51, 0xffff0000, v8
	v_lshlrev_b32_e32 v52, 16, v12
	v_and_b32_e32 v53, 0xffff0000, v12
	v_mul_f32_e32 v54, 0xbfb8aa3b, v52
	v_exp_f32_e32 v54, v54
	s_nop 0
	v_add_f32_e32 v54, 0x3f800000, v54
	v_rcp_f32_e32 v54, v54
	s_nop 0
	v_mul_f32_e32 v50, v50, v54
	v_mul_f32_e32 v55, 0xbfb8aa3b, v53
	v_exp_f32_e32 v55, v55
	s_nop 0
	v_add_f32_e32 v55, 0x3f800000, v55
	v_rcp_f32_e32 v55, v55
	s_nop 0
	v_mul_f32_e32 v51, v51, v55
	v_cvt_pk_bf16_f32 v240, v50, v51
	v_lshlrev_b32_e32 v50, 16, v9
	v_and_b32_e32 v51, 0xffff0000, v9
	v_lshlrev_b32_e32 v52, 16, v13
	v_and_b32_e32 v53, 0xffff0000, v13
	v_mul_f32_e32 v54, 0xbfb8aa3b, v52
	v_exp_f32_e32 v54, v54
	s_nop 0
	v_add_f32_e32 v54, 0x3f800000, v54
	v_rcp_f32_e32 v54, v54
	s_nop 0
	v_mul_f32_e32 v50, v50, v54
	v_mul_f32_e32 v55, 0xbfb8aa3b, v53
	v_exp_f32_e32 v55, v55
	s_nop 0
	v_add_f32_e32 v55, 0x3f800000, v55
	v_rcp_f32_e32 v55, v55
	s_nop 0
	v_mul_f32_e32 v51, v51, v55
	v_cvt_pk_bf16_f32 v241, v50, v51
	v_lshlrev_b32_e32 v50, 16, v10
	v_and_b32_e32 v51, 0xffff0000, v10
	v_lshlrev_b32_e32 v52, 16, v14
	v_and_b32_e32 v53, 0xffff0000, v14
	v_mul_f32_e32 v54, 0xbfb8aa3b, v52
	v_exp_f32_e32 v54, v54
	s_nop 0
	v_add_f32_e32 v54, 0x3f800000, v54
	v_rcp_f32_e32 v54, v54
	s_nop 0
	v_mul_f32_e32 v50, v50, v54
	v_mul_f32_e32 v55, 0xbfb8aa3b, v53
	v_exp_f32_e32 v55, v55
	s_nop 0
	v_add_f32_e32 v55, 0x3f800000, v55
	v_rcp_f32_e32 v55, v55
	s_nop 0
	v_mul_f32_e32 v51, v51, v55
	v_cvt_pk_bf16_f32 v242, v50, v51
	v_lshlrev_b32_e32 v50, 16, v11
	v_and_b32_e32 v51, 0xffff0000, v11
	v_lshlrev_b32_e32 v52, 16, v15
	v_and_b32_e32 v53, 0xffff0000, v15
	v_mul_f32_e32 v54, 0xbfb8aa3b, v52
	v_exp_f32_e32 v54, v54
	s_nop 0
	v_add_f32_e32 v54, 0x3f800000, v54
	v_rcp_f32_e32 v54, v54
	s_nop 0
	v_mul_f32_e32 v50, v50, v54
	v_mul_f32_e32 v55, 0xbfb8aa3b, v53
	v_exp_f32_e32 v55, v55
	s_nop 0
	v_add_f32_e32 v55, 0x3f800000, v55
	v_rcp_f32_e32 v55, v55
	s_nop 0
	v_mul_f32_e32 v51, v51, v55
	v_cvt_pk_bf16_f32 v243, v50, v51
	v_cmp_gt_i32_e32 vcc, 0, v43
	v_mov_b32_e32 v56, 0
	s_nop 1
	v_cndmask_b32_e32 v240, v240, v56, vcc
	v_cndmask_b32_e32 v241, v241, v56, vcc
	v_cndmask_b32_e32 v242, v242, v56, vcc
	v_cndmask_b32_e32 v243, v243, v56, vcc
	v_lshlrev_b32_e32 v37, 10, v47
	v_add_u32_e32 v37, v211, v37
	ds_write_b128 v37, v[240:243]
	s_waitcnt vmcnt(2)
; DEVI unsigned pack2(float a, float b) { return (unsigned)f2bf(a) | ((unsigned)f2bf(b) << 16); }
; DEVI float sigmoidf_(float x) { return __builtin_amdgcn_rcpf(1.f + __expf(-x)); }
; DEVI void conv_tile(const Params& p, unsigned char* smem, int ct) {
;     ...
;   for (int it = tid; it < 62 * 64; it += 256) {
;     const int r = it >> 6, c8 = it & 63;
;     const int t = t0 - 30 + r;
;     uint4 pk = {0u, 0u, 0u, 0u};
;     if (t >= 0) {
;       const u16* src = p.proj + ((size_t)b * T + t) * LDP + c8 * 8;
;       const uint4 a = *(const uint4*)src, bb = *(const uint4*)(src + 512);
;       const unsigned au[4] = {a.x, a.y, a.z, a.w}, bu[4] = {bb.x, bb.y, bb.z, bb.w};
;       unsigned o[4];
; #pragma unroll
;       for (int j = 0; j < 4; ++j) {
;         const float a0 = __uint_as_float(au[j] << 16), a1 = __uint_as_float(au[j] & 0xffff0000u);
;         const float b0 = __uint_as_float(bu[j] << 16), b1 = __uint_as_float(bu[j] & 0xffff0000u);
;         o[j] = pack2(a0 * sigmoidf_(b0), a1 * sigmoidf_(b1));
;       }
;       pk.x = o[0]; pk.y = o[1]; pk.z = o[2]; pk.w = o[3];
;     }
;     *(uint4*)(sU + r * 512 + c8 * 8) = pk;
;   }
	v_lshlrev_b32_e32 v50, 16, v16
	v_and_b32_e32 v51, 0xffff0000, v16
	v_lshlrev_b32_e32 v52, 16, v20
	v_and_b32_e32 v53, 0xffff0000, v20
	v_mul_f32_e32 v54, 0xbfb8aa3b, v52
	v_exp_f32_e32 v54, v54
	s_nop 0
	v_add_f32_e32 v54, 0x3f800000, v54
	v_rcp_f32_e32 v54, v54
	s_nop 0
	v_mul_f32_e32 v50, v50, v54
	v_mul_f32_e32 v55, 0xbfb8aa3b, v53
	v_exp_f32_e32 v55, v55
	s_nop 0
	v_add_f32_e32 v55, 0x3f800000, v55
	v_rcp_f32_e32 v55, v55
	s_nop 0
	v_mul_f32_e32 v51, v51, v55
	v_cvt_pk_bf16_f32 v240, v50, v51
	v_lshlrev_b32_e32 v50, 16, v17
	v_and_b32_e32 v51, 0xffff0000, v17
	v_lshlrev_b32_e32 v52, 16, v21
	v_and_b32_e32 v53, 0xffff0000, v21
	v_mul_f32_e32 v54, 0xbfb8aa3b, v52
	v_exp_f32_e32 v54, v54
	s_nop 0
	v_add_f32_e32 v54, 0x3f800000, v54
	v_rcp_f32_e32 v54, v54
	s_nop 0
	v_mul_f32_e32 v50, v50, v54
	v_mul_f32_e32 v55, 0xbfb8aa3b, v53
	v_exp_f32_e32 v55, v55
	s_nop 0
	v_add_f32_e32 v55, 0x3f800000, v55
	v_rcp_f32_e32 v55, v55
	s_nop 0
	v_mul_f32_e32 v51, v51, v55
	v_cvt_pk_bf16_f32 v241, v50, v51
	v_lshlrev_b32_e32 v50, 16, v18
	v_and_b32_e32 v51, 0xffff0000, v18
	v_lshlrev_b32_e32 v52, 16, v22
	v_and_b32_e32 v53, 0xffff0000, v22
	v_mul_f32_e32 v54, 0xbfb8aa3b, v52
	v_exp_f32_e32 v54, v54
	s_nop 0
	v_add_f32_e32 v54, 0x3f800000, v54
	v_rcp_f32_e32 v54, v54
	s_nop 0
	v_mul_f32_e32 v50, v50, v54
	v_mul_f32_e32 v55, 0xbfb8aa3b, v53
	v_exp_f32_e32 v55, v55
	s_nop 0
	v_add_f32_e32 v55, 0x3f800000, v55
	v_rcp_f32_e32 v55, v55
	s_nop 0
	v_mul_f32_e32 v51, v51, v55
	v_cvt_pk_bf16_f32 v242, v50, v51
	v_lshlrev_b32_e32 v50, 16, v19
	v_and_b32_e32 v51, 0xffff0000, v19
	v_lshlrev_b32_e32 v52, 16, v23
	v_and_b32_e32 v53, 0xffff0000, v23
	v_mul_f32_e32 v54, 0xbfb8aa3b, v52
	v_exp_f32_e32 v54, v54
	s_nop 0
	v_add_f32_e32 v54, 0x3f800000, v54
	v_rcp_f32_e32 v54, v54
	s_nop 0
	v_mul_f32_e32 v50, v50, v54
	v_mul_f32_e32 v55, 0xbfb8aa3b, v53
	v_exp_f32_e32 v55, v55
	s_nop 0
	v_add_f32_e32 v55, 0x3f800000, v55
	v_rcp_f32_e32 v55, v55
	s_nop 0
	v_mul_f32_e32 v51, v51, v55
	v_cvt_pk_bf16_f32 v243, v50, v51
	v_cmp_gt_i32_e32 vcc, 0, v44
	v_mov_b32_e32 v56, 0
	s_nop 1
	v_cndmask_b32_e32 v240, v240, v56, vcc
	v_cndmask_b32_e32 v241, v241, v56, vcc
	v_cndmask_b32_e32 v242, v242, v56, vcc
	v_cndmask_b32_e32 v243, v243, v56, vcc
	v_lshlrev_b32_e32 v37, 10, v48
	v_add_u32_e32 v37, v211, v37
	ds_write_b128 v37, v[240:243]
	s_waitcnt vmcnt(0)
	v_lshlrev_b32_e32 v50, 16, v24
	v_and_b32_e32 v51, 0xffff0000, v24
	v_lshlrev_b32_e32 v52, 16, v28
	v_and_b32_e32 v53, 0xffff0000, v28
	v_mul_f32_e32 v54, 0xbfb8aa3b, v52
	v_exp_f32_e32 v54, v54
	s_nop 0
	v_add_f32_e32 v54, 0x3f800000, v54
	v_rcp_f32_e32 v54, v54
	s_nop 0
	v_mul_f32_e32 v50, v50, v54
	v_mul_f32_e32 v55, 0xbfb8aa3b, v53
	v_exp_f32_e32 v55, v55
	s_nop 0
	v_add_f32_e32 v55, 0x3f800000, v55
	v_rcp_f32_e32 v55, v55
	s_nop 0
	v_mul_f32_e32 v51, v51, v55
	v_cvt_pk_bf16_f32 v240, v50, v51
	v_lshlrev_b32_e32 v50, 16, v25
	v_and_b32_e32 v51, 0xffff0000, v25
	v_lshlrev_b32_e32 v52, 16, v29
	v_and_b32_e32 v53, 0xffff0000, v29
	v_mul_f32_e32 v54, 0xbfb8aa3b, v52
	v_exp_f32_e32 v54, v54
	s_nop 0
	v_add_f32_e32 v54, 0x3f800000, v54
	v_rcp_f32_e32 v54, v54
	s_nop 0
	v_mul_f32_e32 v50, v50, v54
	v_mul_f32_e32 v55, 0xbfb8aa3b, v53
	v_exp_f32_e32 v55, v55
	s_nop 0
	v_add_f32_e32 v55, 0x3f800000, v55
	v_rcp_f32_e32 v55, v55
	s_nop 0
	v_mul_f32_e32 v51, v51, v55
	v_cvt_pk_bf16_f32 v241, v50, v51
	v_lshlrev_b32_e32 v50, 16, v26
	v_and_b32_e32 v51, 0xffff0000, v26
	v_lshlrev_b32_e32 v52, 16, v30
	v_and_b32_e32 v53, 0xffff0000, v30
	v_mul_f32_e32 v54, 0xbfb8aa3b, v52
	v_exp_f32_e32 v54, v54
	s_nop 0
	v_add_f32_e32 v54, 0x3f800000, v54
	v_rcp_f32_e32 v54, v54
	s_nop 0
	v_mul_f32_e32 v50, v50, v54
	v_mul_f32_e32 v55, 0xbfb8aa3b, v53
	v_exp_f32_e32 v55, v55
	s_nop 0
	v_add_f32_e32 v55, 0x3f800000, v55
	v_rcp_f32_e32 v55, v55
	s_nop 0
	v_mul_f32_e32 v51, v51, v55
	v_cvt_pk_bf16_f32 v242, v50, v51
	v_lshlrev_b32_e32 v50, 16, v27
	v_and_b32_e32 v51, 0xffff0000, v27
	v_lshlrev_b32_e32 v52, 16, v31
	v_and_b32_e32 v53, 0xffff0000, v31
	v_mul_f32_e32 v54, 0xbfb8aa3b, v52
	v_exp_f32_e32 v54, v54
	s_nop 0
	v_add_f32_e32 v54, 0x3f800000, v54
	v_rcp_f32_e32 v54, v54
	s_nop 0
	v_mul_f32_e32 v50, v50, v54
	v_mul_f32_e32 v55, 0xbfb8aa3b, v53
	v_exp_f32_e32 v55, v55
	s_nop 0
	v_add_f32_e32 v55, 0x3f800000, v55
	v_rcp_f32_e32 v55, v55
	s_nop 0
	v_mul_f32_e32 v51, v51, v55
	v_cvt_pk_bf16_f32 v243, v50, v51
	v_cmp_gt_i32_e32 vcc, 0, v45
	v_mov_b32_e32 v56, 0
	s_nop 1
	v_cndmask_b32_e32 v240, v240, v56, vcc
	v_cndmask_b32_e32 v241, v241, v56, vcc
	v_cndmask_b32_e32 v242, v242, v56, vcc
	v_cndmask_b32_e32 v243, v243, v56, vcc
	v_lshlrev_b32_e32 v37, 10, v49
	v_add_u32_e32 v37, v211, v37
	ds_write_b128 v37, v[240:243]
	v_add_u32_e32 v34, 16, v212
	v_min_u32_e32 v34, 61, v34
	v_add_u32_e32 v35, s22, v34
	v_subrev_u32_e32 v35, 30, v35
	v_max_i32_e32 v38, 0, v35
	v_mul_u32_u24_e32 v36, 0x1240, v38
	v_add_u32_e32 v36, v211, v36
	v_mov_b32_e32 v42, v35
	v_mov_b32_e32 v46, v34
	global_load_dwordx4 v[0:3], v36, s[0:1]
	global_load_dwordx4 v[4:7], v36, s[0:1] offset:1024
	v_add_u32_e32 v34, 20, v212
	v_min_u32_e32 v34, 61, v34
	v_add_u32_e32 v35, s22, v34
	v_subrev_u32_e32 v35, 30, v35
	v_max_i32_e32 v39, 0, v35
	v_mul_u32_u24_e32 v36, 0x1240, v39
	v_add_u32_e32 v36, v211, v36
	v_mov_b32_e32 v43, v35
	v_mov_b32_e32 v47, v34
	global_load_dwordx4 v[8:11], v36, s[0:1]
	global_load_dwordx4 v[12:15], v36, s[0:1] offset:1024
	v_add_u32_e32 v34, 24, v212
	v_min_u32_e32 v34, 61, v34
	v_add_u32_e32 v35, s22, v34
	v_subrev_u32_e32 v35, 30, v35
	v_max_i32_e32 v40, 0, v35
	v_mul_u32_u24_e32 v36, 0x1240, v40
	v_add_u32_e32 v36, v211, v36
	v_mov_b32_e32 v44, v35
	v_mov_b32_e32 v48, v34
	global_load_dwordx4 v[16:19], v36, s[0:1]
	global_load_dwordx4 v[20:23], v36, s[0:1] offset:1024
	v_add_u32_e32 v34, 28, v212
	v_min_u32_e32 v34, 61, v34
	v_add_u32_e32 v35, s22, v34
	v_subrev_u32_e32 v35, 30, v35
	v_max_i32_e32 v41, 0, v35
	v_mul_u32_u24_e32 v36, 0x1240, v41
	v_add_u32_e32 v36, v211, v36
	v_mov_b32_e32 v45, v35
	v_mov_b32_e32 v49, v34
	global_load_dwordx4 v[24:27], v36, s[0:1]
	global_load_dwordx4 v[28:31], v36, s[0:1] offset:1024
	s_waitcnt vmcnt(6)
; DEVI unsigned pack2(float a, float b) { return (unsigned)f2bf(a) | ((unsigned)f2bf(b) << 16); }
; DEVI float sigmoidf_(float x) { return __builtin_amdgcn_rcpf(1.f + __expf(-x)); }
; DEVI void conv_tile(const Params& p, unsigned char* smem, int ct) {
;     ...
;   for (int it = tid; it < 62 * 64; it += 256) {
;     const int r = it >> 6, c8 = it & 63;
;     const int t = t0 - 30 + r;
;     uint4 pk = {0u, 0u, 0u, 0u};
;     if (t >= 0) {
;       const u16* src = p.proj + ((size_t)b * T + t) * LDP + c8 * 8;
;       const uint4 a = *(const uint4*)src, bb = *(const uint4*)(src + 512);
;       const unsigned au[4] = {a.x, a.y, a.z, a.w}, bu[4] = {bb.x, bb.y, bb.z, bb.w};
;       unsigned o[4];
; #pragma unroll
;       for (int j = 0; j < 4; ++j) {
;         const float a0 = __uint_as_float(au[j] << 16), a1 = __uint_as_float(au[j] & 0xffff0000u);
;         const float b0 = __uint_as_float(bu[j] << 16), b1 = __uint_as_float(bu[j] & 0xffff0000u);
;         o[j] = pack2(a0 * sigmoidf_(b0), a1 * sigmoidf_(b1));
;       }
;       pk.x = o[0]; pk.y = o[1]; pk.z = o[2]; pk.w = o[3];
;     }
;     *(uint4*)(sU + r * 512 + c8 * 8) = pk;
;   }
	v_lshlrev_b32_e32 v50, 16, v0
	v_and_b32_e32 v51, 0xffff0000, v0
	v_lshlrev_b32_e32 v52, 16, v4
	v_and_b32_e32 v53, 0xffff0000, v4
	v_mul_f32_e32 v54, 0xbfb8aa3b, v52
	v_exp_f32_e32 v54, v54
	s_nop 0
	v_add_f32_e32 v54, 0x3f800000, v54
	v_rcp_f32_e32 v54, v54
	s_nop 0
	v_mul_f32_e32 v50, v50, v54
	v_mul_f32_e32 v55, 0xbfb8aa3b, v53
	v_exp_f32_e32 v55, v55
	s_nop 0
	v_add_f32_e32 v55, 0x3f800000, v55
	v_rcp_f32_e32 v55, v55
	s_nop 0
	v_mul_f32_e32 v51, v51, v55
	v_cvt_pk_bf16_f32 v240, v50, v51
	v_lshlrev_b32_e32 v50, 16, v1
	v_and_b32_e32 v51, 0xffff0000, v1
	v_lshlrev_b32_e32 v52, 16, v5
	v_and_b32_e32 v53, 0xffff0000, v5
	v_mul_f32_e32 v54, 0xbfb8aa3b, v52
	v_exp_f32_e32 v54, v54
	s_nop 0
	v_add_f32_e32 v54, 0x3f800000, v54
	v_rcp_f32_e32 v54, v54
	s_nop 0
	v_mul_f32_e32 v50, v50, v54
	v_mul_f32_e32 v55, 0xbfb8aa3b, v53
	v_exp_f32_e32 v55, v55
	s_nop 0
	v_add_f32_e32 v55, 0x3f800000, v55
	v_rcp_f32_e32 v55, v55
	s_nop 0
	v_mul_f32_e32 v51, v51, v55
	v_cvt_pk_bf16_f32 v241, v50, v51
	v_lshlrev_b32_e32 v50, 16, v2
	v_and_b32_e32 v51, 0xffff0000, v2
	v_lshlrev_b32_e32 v52, 16, v6
	v_and_b32_e32 v53, 0xffff0000, v6
	v_mul_f32_e32 v54, 0xbfb8aa3b, v52
	v_exp_f32_e32 v54, v54
	s_nop 0
	v_add_f32_e32 v54, 0x3f800000, v54
	v_rcp_f32_e32 v54, v54
	s_nop 0
	v_mul_f32_e32 v50, v50, v54
	v_mul_f32_e32 v55, 0xbfb8aa3b, v53
	v_exp_f32_e32 v55, v55
	s_nop 0
	v_add_f32_e32 v55, 0x3f800000, v55
	v_rcp_f32_e32 v55, v55
	s_nop 0
	v_mul_f32_e32 v51, v51, v55
	v_cvt_pk_bf16_f32 v242, v50, v51
	v_lshlrev_b32_e32 v50, 16, v3
	v_and_b32_e32 v51, 0xffff0000, v3
	v_lshlrev_b32_e32 v52, 16, v7
	v_and_b32_e32 v53, 0xffff0000, v7
	v_mul_f32_e32 v54, 0xbfb8aa3b, v52
	v_exp_f32_e32 v54, v54
	s_nop 0
	v_add_f32_e32 v54, 0x3f800000, v54
	v_rcp_f32_e32 v54, v54
	s_nop 0
	v_mul_f32_e32 v50, v50, v54
	v_mul_f32_e32 v55, 0xbfb8aa3b, v53
	v_exp_f32_e32 v55, v55
	s_nop 0
	v_add_f32_e32 v55, 0x3f800000, v55
	v_rcp_f32_e32 v55, v55
	s_nop 0
	v_mul_f32_e32 v51, v51, v55
	v_cvt_pk_bf16_f32 v243, v50, v51
	v_cmp_gt_i32_e32 vcc, 0, v42
	v_mov_b32_e32 v56, 0
	s_nop 1
	v_cndmask_b32_e32 v240, v240, v56, vcc
	v_cndmask_b32_e32 v241, v241, v56, vcc
	v_cndmask_b32_e32 v242, v242, v56, vcc
	v_cndmask_b32_e32 v243, v243, v56, vcc
	v_lshlrev_b32_e32 v37, 10, v46
	v_add_u32_e32 v37, v211, v37
	ds_write_b128 v37, v[240:243]
	s_waitcnt vmcnt(4)
	v_lshlrev_b32_e32 v50, 16, v8
	v_and_b32_e32 v51, 0xffff0000, v8
	v_lshlrev_b32_e32 v52, 16, v12
	v_and_b32_e32 v53, 0xffff0000, v12
	v_mul_f32_e32 v54, 0xbfb8aa3b, v52
	v_exp_f32_e32 v54, v54
	s_nop 0
	v_add_f32_e32 v54, 0x3f800000, v54
	v_rcp_f32_e32 v54, v54
	s_nop 0
	v_mul_f32_e32 v50, v50, v54
	v_mul_f32_e32 v55, 0xbfb8aa3b, v53
	v_exp_f32_e32 v55, v55
	s_nop 0
	v_add_f32_e32 v55, 0x3f800000, v55
	v_rcp_f32_e32 v55, v55
	s_nop 0
	v_mul_f32_e32 v51, v51, v55
	v_cvt_pk_bf16_f32 v240, v50, v51
	v_lshlrev_b32_e32 v50, 16, v9
	v_and_b32_e32 v51, 0xffff0000, v9
	v_lshlrev_b32_e32 v52, 16, v13
	v_and_b32_e32 v53, 0xffff0000, v13
	v_mul_f32_e32 v54, 0xbfb8aa3b, v52
	v_exp_f32_e32 v54, v54
	s_nop 0
	v_add_f32_e32 v54, 0x3f800000, v54
	v_rcp_f32_e32 v54, v54
	s_nop 0
	v_mul_f32_e32 v50, v50, v54
	v_mul_f32_e32 v55, 0xbfb8aa3b, v53
	v_exp_f32_e32 v55, v55
	s_nop 0
	v_add_f32_e32 v55, 0x3f800000, v55
	v_rcp_f32_e32 v55, v55
	s_nop 0
	v_mul_f32_e32 v51, v51, v55
	v_cvt_pk_bf16_f32 v241, v50, v51
	v_lshlrev_b32_e32 v50, 16, v10
	v_and_b32_e32 v51, 0xffff0000, v10
	v_lshlrev_b32_e32 v52, 16, v14
	v_and_b32_e32 v53, 0xffff0000, v14
	v_mul_f32_e32 v54, 0xbfb8aa3b, v52
	v_exp_f32_e32 v54, v54
	s_nop 0
	v_add_f32_e32 v54, 0x3f800000, v54
	v_rcp_f32_e32 v54, v54
	s_nop 0
	v_mul_f32_e32 v50, v50, v54
	v_mul_f32_e32 v55, 0xbfb8aa3b, v53
	v_exp_f32_e32 v55, v55
	s_nop 0
	v_add_f32_e32 v55, 0x3f800000, v55
	v_rcp_f32_e32 v55, v55
	s_nop 0
	v_mul_f32_e32 v51, v51, v55
	v_cvt_pk_bf16_f32 v242, v50, v51
	v_lshlrev_b32_e32 v50, 16, v11
	v_and_b32_e32 v51, 0xffff0000, v11
	v_lshlrev_b32_e32 v52, 16, v15
	v_and_b32_e32 v53, 0xffff0000, v15
	v_mul_f32_e32 v54, 0xbfb8aa3b, v52
	v_exp_f32_e32 v54, v54
	s_nop 0
	v_add_f32_e32 v54, 0x3f800000, v54
	v_rcp_f32_e32 v54, v54
	s_nop 0
	v_mul_f32_e32 v50, v50, v54
	v_mul_f32_e32 v55, 0xbfb8aa3b, v53
	v_exp_f32_e32 v55, v55
	s_nop 0
	v_add_f32_e32 v55, 0x3f800000, v55
	v_rcp_f32_e32 v55, v55
	s_nop 0
	v_mul_f32_e32 v51, v51, v55
	v_cvt_pk_bf16_f32 v243, v50, v51
	v_cmp_gt_i32_e32 vcc, 0, v43
	v_mov_b32_e32 v56, 0
	s_nop 1
	v_cndmask_b32_e32 v240, v240, v56, vcc
	v_cndmask_b32_e32 v241, v241, v56, vcc
	v_cndmask_b32_e32 v242, v242, v56, vcc
	v_cndmask_b32_e32 v243, v243, v56, vcc
	v_lshlrev_b32_e32 v37, 10, v47
	v_add_u32_e32 v37, v211, v37
	ds_write_b128 v37, v[240:243]
	s_waitcnt vmcnt(2)
; DEVI unsigned pack2(float a, float b) { return (unsigned)f2bf(a) | ((unsigned)f2bf(b) << 16); }
; DEVI float sigmoidf_(float x) { return __builtin_amdgcn_rcpf(1.f + __expf(-x)); }
; DEVI void conv_tile(const Params& p, unsigned char* smem, int ct) {
;     ...
;   for (int it = tid; it < 62 * 64; it += 256) {
;     const int r = it >> 6, c8 = it & 63;
;     const int t = t0 - 30 + r;
;     uint4 pk = {0u, 0u, 0u, 0u};
;     if (t >= 0) {
;       const u16* src = p.proj + ((size_t)b * T + t) * LDP + c8 * 8;
;       const uint4 a = *(const uint4*)src, bb = *(const uint4*)(src + 512);
;       const unsigned au[4] = {a.x, a.y, a.z, a.w}, bu[4] = {bb.x, bb.y, bb.z, bb.w};
;       unsigned o[4];
; #pragma unroll
;       for (int j = 0; j < 4; ++j) {
;         const float a0 = __uint_as_float(au[j] << 16), a1 = __uint_as_float(au[j] & 0xffff0000u);
;         const float b0 = __uint_as_float(bu[j] << 16), b1 = __uint_as_float(bu[j] & 0xffff0000u);
;         o[j] = pack2(a0 * sigmoidf_(b0), a1 * sigmoidf_(b1));
;       }
;       pk.x = o[0]; pk.y = o[1]; pk.z = o[2]; pk.w = o[3];
;     }
;     *(uint4*)(sU + r * 512 + c8 * 8) = pk;
;   }
	v_lshlrev_b32_e32 v50, 16, v16
	v_and_b32_e32 v51, 0xffff0000, v16
	v_lshlrev_b32_e32 v52, 16, v20
	v_and_b32_e32 v53, 0xffff0000, v20
	v_mul_f32_e32 v54, 0xbfb8aa3b, v52
	v_exp_f32_e32 v54, v54
	s_nop 0
	v_add_f32_e32 v54, 0x3f800000, v54
	v_rcp_f32_e32 v54, v54
	s_nop 0
	v_mul_f32_e32 v50, v50, v54
	v_mul_f32_e32 v55, 0xbfb8aa3b, v53
	v_exp_f32_e32 v55, v55
	s_nop 0
	v_add_f32_e32 v55, 0x3f800000, v55
	v_rcp_f32_e32 v55, v55
	s_nop 0
	v_mul_f32_e32 v51, v51, v55
	v_cvt_pk_bf16_f32 v240, v50, v51
	v_lshlrev_b32_e32 v50, 16, v17
	v_and_b32_e32 v51, 0xffff0000, v17
	v_lshlrev_b32_e32 v52, 16, v21
	v_and_b32_e32 v53, 0xffff0000, v21
	v_mul_f32_e32 v54, 0xbfb8aa3b, v52
	v_exp_f32_e32 v54, v54
	s_nop 0
	v_add_f32_e32 v54, 0x3f800000, v54
	v_rcp_f32_e32 v54, v54
	s_nop 0
	v_mul_f32_e32 v50, v50, v54
	v_mul_f32_e32 v55, 0xbfb8aa3b, v53
	v_exp_f32_e32 v55, v55
	s_nop 0
	v_add_f32_e32 v55, 0x3f800000, v55
	v_rcp_f32_e32 v55, v55
	s_nop 0
	v_mul_f32_e32 v51, v51, v55
	v_cvt_pk_bf16_f32 v241, v50, v51
	v_lshlrev_b32_e32 v50, 16, v18
	v_and_b32_e32 v51, 0xffff0000, v18
	v_lshlrev_b32_e32 v52, 16, v22
	v_and_b32_e32 v53, 0xffff0000, v22
	v_mul_f32_e32 v54, 0xbfb8aa3b, v52
	v_exp_f32_e32 v54, v54
	s_nop 0
	v_add_f32_e32 v54, 0x3f800000, v54
	v_rcp_f32_e32 v54, v54
	s_nop 0
	v_mul_f32_e32 v50, v50, v54
	v_mul_f32_e32 v55, 0xbfb8aa3b, v53
	v_exp_f32_e32 v55, v55
	s_nop 0
	v_add_f32_e32 v55, 0x3f800000, v55
	v_rcp_f32_e32 v55, v55
	s_nop 0
	v_mul_f32_e32 v51, v51, v55
	v_cvt_pk_bf16_f32 v242, v50, v51
	v_lshlrev_b32_e32 v50, 16, v19
	v_and_b32_e32 v51, 0xffff0000, v19
	v_lshlrev_b32_e32 v52, 16, v23
	v_and_b32_e32 v53, 0xffff0000, v23
	v_mul_f32_e32 v54, 0xbfb8aa3b, v52
	v_exp_f32_e32 v54, v54
	s_nop 0
	v_add_f32_e32 v54, 0x3f800000, v54
	v_rcp_f32_e32 v54, v54
	s_nop 0
	v_mul_f32_e32 v50, v50, v54
	v_mul_f32_e32 v55, 0xbfb8aa3b, v53
	v_exp_f32_e32 v55, v55
	s_nop 0
	v_add_f32_e32 v55, 0x3f800000, v55
	v_rcp_f32_e32 v55, v55
	s_nop 0
	v_mul_f32_e32 v51, v51, v55
	v_cvt_pk_bf16_f32 v243, v50, v51
	v_cmp_gt_i32_e32 vcc, 0, v44
	v_mov_b32_e32 v56, 0
	s_nop 1
	v_cndmask_b32_e32 v240, v240, v56, vcc
	v_cndmask_b32_e32 v241, v241, v56, vcc
	v_cndmask_b32_e32 v242, v242, v56, vcc
	v_cndmask_b32_e32 v243, v243, v56, vcc
	v_lshlrev_b32_e32 v37, 10, v48
	v_add_u32_e32 v37, v211, v37
	ds_write_b128 v37, v[240:243]
	s_waitcnt vmcnt(0)
	v_lshlrev_b32_e32 v50, 16, v24
	v_and_b32_e32 v51, 0xffff0000, v24
	v_lshlrev_b32_e32 v52, 16, v28
	v_and_b32_e32 v53, 0xffff0000, v28
	v_mul_f32_e32 v54, 0xbfb8aa3b, v52
	v_exp_f32_e32 v54, v54
	s_nop 0
	v_add_f32_e32 v54, 0x3f800000, v54
	v_rcp_f32_e32 v54, v54
	s_nop 0
	v_mul_f32_e32 v50, v50, v54
	v_mul_f32_e32 v55, 0xbfb8aa3b, v53
	v_exp_f32_e32 v55, v55
	s_nop 0
	v_add_f32_e32 v55, 0x3f800000, v55
	v_rcp_f32_e32 v55, v55
	s_nop 0
	v_mul_f32_e32 v51, v51, v55
	v_cvt_pk_bf16_f32 v240, v50, v51
	v_lshlrev_b32_e32 v50, 16, v25
	v_and_b32_e32 v51, 0xffff0000, v25
	v_lshlrev_b32_e32 v52, 16, v29
	v_and_b32_e32 v53, 0xffff0000, v29
	v_mul_f32_e32 v54, 0xbfb8aa3b, v52
	v_exp_f32_e32 v54, v54
	s_nop 0
	v_add_f32_e32 v54, 0x3f800000, v54
	v_rcp_f32_e32 v54, v54
	s_nop 0
	v_mul_f32_e32 v50, v50, v54
	v_mul_f32_e32 v55, 0xbfb8aa3b, v53
	v_exp_f32_e32 v55, v55
	s_nop 0
	v_add_f32_e32 v55, 0x3f800000, v55
	v_rcp_f32_e32 v55, v55
	s_nop 0
	v_mul_f32_e32 v51, v51, v55
	v_cvt_pk_bf16_f32 v241, v50, v51
	v_lshlrev_b32_e32 v50, 16, v26
	v_and_b32_e32 v51, 0xffff0000, v26
	v_lshlrev_b32_e32 v52, 16, v30
	v_and_b32_e32 v53, 0xffff0000, v30
	v_mul_f32_e32 v54, 0xbfb8aa3b, v52
	v_exp_f32_e32 v54, v54
	s_nop 0
	v_add_f32_e32 v54, 0x3f800000, v54
	v_rcp_f32_e32 v54, v54
	s_nop 0
	v_mul_f32_e32 v50, v50, v54
	v_mul_f32_e32 v55, 0xbfb8aa3b, v53
	v_exp_f32_e32 v55, v55
	s_nop 0
	v_add_f32_e32 v55, 0x3f800000, v55
	v_rcp_f32_e32 v55, v55
	s_nop 0
	v_mul_f32_e32 v51, v51, v55
	v_cvt_pk_bf16_f32 v242, v50, v51
	v_lshlrev_b32_e32 v50, 16, v27
	v_and_b32_e32 v51, 0xffff0000, v27
	v_lshlrev_b32_e32 v52, 16, v31
	v_and_b32_e32 v53, 0xffff0000, v31
	v_mul_f32_e32 v54, 0xbfb8aa3b, v52
	v_exp_f32_e32 v54, v54
	s_nop 0
	v_add_f32_e32 v54, 0x3f800000, v54
	v_rcp_f32_e32 v54, v54
	s_nop 0
	v_mul_f32_e32 v50, v50, v54
	v_mul_f32_e32 v55, 0xbfb8aa3b, v53
	v_exp_f32_e32 v55, v55
	s_nop 0
	v_add_f32_e32 v55, 0x3f800000, v55
	v_rcp_f32_e32 v55, v55
	s_nop 0
	v_mul_f32_e32 v51, v51, v55
	v_cvt_pk_bf16_f32 v243, v50, v51
	v_cmp_gt_i32_e32 vcc, 0, v45
	v_mov_b32_e32 v56, 0
	s_nop 1
	v_cndmask_b32_e32 v240, v240, v56, vcc
	v_cndmask_b32_e32 v241, v241, v56, vcc
	v_cndmask_b32_e32 v242, v242, v56, vcc
	v_cndmask_b32_e32 v243, v243, v56, vcc
	v_lshlrev_b32_e32 v37, 10, v49
	v_add_u32_e32 v37, v211, v37
	ds_write_b128 v37, v[240:243]
	v_add_u32_e32 v34, 32, v212
	v_min_u32_e32 v34, 61, v34
	v_add_u32_e32 v35, s22, v34
	v_subrev_u32_e32 v35, 30, v35
	v_max_i32_e32 v38, 0, v35
	v_mul_u32_u24_e32 v36, 0x1240, v38
	v_add_u32_e32 v36, v211, v36
	v_mov_b32_e32 v42, v35
	v_mov_b32_e32 v46, v34
	global_load_dwordx4 v[0:3], v36, s[0:1]
	global_load_dwordx4 v[4:7], v36, s[0:1] offset:1024
	v_add_u32_e32 v34, 36, v212
	v_min_u32_e32 v34, 61, v34
	v_add_u32_e32 v35, s22, v34
	v_subrev_u32_e32 v35, 30, v35
	v_max_i32_e32 v39, 0, v35
	v_mul_u32_u24_e32 v36, 0x1240, v39
	v_add_u32_e32 v36, v211, v36
	v_mov_b32_e32 v43, v35
	v_mov_b32_e32 v47, v34
	global_load_dwordx4 v[8:11], v36, s[0:1]
	global_load_dwordx4 v[12:15], v36, s[0:1] offset:1024
	v_add_u32_e32 v34, 40, v212
	v_min_u32_e32 v34, 61, v34
	v_add_u32_e32 v35, s22, v34
	v_subrev_u32_e32 v35, 30, v35
	v_max_i32_e32 v40, 0, v35
	v_mul_u32_u24_e32 v36, 0x1240, v40
	v_add_u32_e32 v36, v211, v36
	v_mov_b32_e32 v44, v35
	v_mov_b32_e32 v48, v34
	global_load_dwordx4 v[16:19], v36, s[0:1]
	global_load_dwordx4 v[20:23], v36, s[0:1] offset:1024
	v_add_u32_e32 v34, 44, v212
	v_min_u32_e32 v34, 61, v34
	v_add_u32_e32 v35, s22, v34
	v_subrev_u32_e32 v35, 30, v35
	v_max_i32_e32 v41, 0, v35
	v_mul_u32_u24_e32 v36, 0x1240, v41
	v_add_u32_e32 v36, v211, v36
	v_mov_b32_e32 v45, v35
	v_mov_b32_e32 v49, v34
	global_load_dwordx4 v[24:27], v36, s[0:1]
	global_load_dwordx4 v[28:31], v36, s[0:1] offset:1024
	s_waitcnt vmcnt(6)
; DEVI unsigned pack2(float a, float b) { return (unsigned)f2bf(a) | ((unsigned)f2bf(b) << 16); }
; DEVI float sigmoidf_(float x) { return __builtin_amdgcn_rcpf(1.f + __expf(-x)); }
; DEVI void conv_tile(const Params& p, unsigned char* smem, int ct) {
;     ...
;   for (int it = tid; it < 62 * 64; it += 256) {
;     const int r = it >> 6, c8 = it & 63;
;     const int t = t0 - 30 + r;
;     uint4 pk = {0u, 0u, 0u, 0u};
;     if (t >= 0) {
;       const u16* src = p.proj + ((size_t)b * T + t) * LDP + c8 * 8;
;       const uint4 a = *(const uint4*)src, bb = *(const uint4*)(src + 512);
;       const unsigned au[4] = {a.x, a.y, a.z, a.w}, bu[4] = {bb.x, bb.y, bb.z, bb.w};
;       unsigned o[4];
; #pragma unroll
;       for (int j = 0; j < 4; ++j) {
;         const float a0 = __uint_as_float(au[j] << 16), a1 = __uint_as_float(au[j] & 0xffff0000u);
;         const float b0 = __uint_as_float(bu[j] << 16), b1 = __uint_as_float(bu[j] & 0xffff0000u);
;         o[j] = pack2(a0 * sigmoidf_(b0), a1 * sigmoidf_(b1));
;       }
;       pk.x = o[0]; pk.y = o[1]; pk.z = o[2]; pk.w = o[3];
;     }
;     *(uint4*)(sU + r * 512 + c8 * 8) = pk;
;   }
	v_lshlrev_b32_e32 v50, 16, v0
	v_and_b32_e32 v51, 0xffff0000, v0
	v_lshlrev_b32_e32 v52, 16, v4
	v_and_b32_e32 v53, 0xffff0000, v4
	v_mul_f32_e32 v54, 0xbfb8aa3b, v52
	v_exp_f32_e32 v54, v54
	s_nop 0
	v_add_f32_e32 v54, 0x3f800000, v54
	v_rcp_f32_e32 v54, v54
	s_nop 0
	v_mul_f32_e32 v50, v50, v54
	v_mul_f32_e32 v55, 0xbfb8aa3b, v53
	v_exp_f32_e32 v55, v55
	s_nop 0
	v_add_f32_e32 v55, 0x3f800000, v55
	v_rcp_f32_e32 v55, v55
	s_nop 0
	v_mul_f32_e32 v51, v51, v55
	v_cvt_pk_bf16_f32 v240, v50, v51
	v_lshlrev_b32_e32 v50, 16, v1
	v_and_b32_e32 v51, 0xffff0000, v1
	v_lshlrev_b32_e32 v52, 16, v5
	v_and_b32_e32 v53, 0xffff0000, v5
	v_mul_f32_e32 v54, 0xbfb8aa3b, v52
	v_exp_f32_e32 v54, v54
	s_nop 0
	v_add_f32_e32 v54, 0x3f800000, v54
	v_rcp_f32_e32 v54, v54
	s_nop 0
	v_mul_f32_e32 v50, v50, v54
	v_mul_f32_e32 v55, 0xbfb8aa3b, v53
	v_exp_f32_e32 v55, v55
	s_nop 0
	v_add_f32_e32 v55, 0x3f800000, v55
	v_rcp_f32_e32 v55, v55
	s_nop 0
	v_mul_f32_e32 v51, v51, v55
	v_cvt_pk_bf16_f32 v241, v50, v51
	v_lshlrev_b32_e32 v50, 16, v2
	v_and_b32_e32 v51, 0xffff0000, v2
	v_lshlrev_b32_e32 v52, 16, v6
	v_and_b32_e32 v53, 0xffff0000, v6
	v_mul_f32_e32 v54, 0xbfb8aa3b, v52
	v_exp_f32_e32 v54, v54
	s_nop 0
	v_add_f32_e32 v54, 0x3f800000, v54
	v_rcp_f32_e32 v54, v54
	s_nop 0
	v_mul_f32_e32 v50, v50, v54
	v_mul_f32_e32 v55, 0xbfb8aa3b, v53
	v_exp_f32_e32 v55, v55
	s_nop 0
	v_add_f32_e32 v55, 0x3f800000, v55
	v_rcp_f32_e32 v55, v55
	s_nop 0
	v_mul_f32_e32 v51, v51, v55
	v_cvt_pk_bf16_f32 v242, v50, v51
	v_lshlrev_b32_e32 v50, 16, v3
	v_and_b32_e32 v51, 0xffff0000, v3
	v_lshlrev_b32_e32 v52, 16, v7
	v_and_b32_e32 v53, 0xffff0000, v7
	v_mul_f32_e32 v54, 0xbfb8aa3b, v52
	v_exp_f32_e32 v54, v54
	s_nop 0
	v_add_f32_e32 v54, 0x3f800000, v54
	v_rcp_f32_e32 v54, v54
	s_nop 0
	v_mul_f32_e32 v50, v50, v54
	v_mul_f32_e32 v55, 0xbfb8aa3b, v53
	v_exp_f32_e32 v55, v55
	s_nop 0
	v_add_f32_e32 v55, 0x3f800000, v55
	v_rcp_f32_e32 v55, v55
	s_nop 0
	v_mul_f32_e32 v51, v51, v55
	v_cvt_pk_bf16_f32 v243, v50, v51
	v_cmp_gt_i32_e32 vcc, 0, v42
	v_mov_b32_e32 v56, 0
	s_nop 1
	v_cndmask_b32_e32 v240, v240, v56, vcc
	v_cndmask_b32_e32 v241, v241, v56, vcc
	v_cndmask_b32_e32 v242, v242, v56, vcc
	v_cndmask_b32_e32 v243, v243, v56, vcc
	v_lshlrev_b32_e32 v37, 10, v46
	v_add_u32_e32 v37, v211, v37
	ds_write_b128 v37, v[240:243]
	s_waitcnt vmcnt(4)
	v_lshlrev_b32_e32 v50, 16, v8
	v_and_b32_e32 v51, 0xffff0000, v8
	v_lshlrev_b32_e32 v52, 16, v12
	v_and_b32_e32 v53, 0xffff0000, v12
	v_mul_f32_e32 v54, 0xbfb8aa3b, v52
	v_exp_f32_e32 v54, v54
	s_nop 0
	v_add_f32_e32 v54, 0x3f800000, v54
	v_rcp_f32_e32 v54, v54
	s_nop 0
	v_mul_f32_e32 v50, v50, v54
	v_mul_f32_e32 v55, 0xbfb8aa3b, v53
	v_exp_f32_e32 v55, v55
	s_nop 0
	v_add_f32_e32 v55, 0x3f800000, v55
	v_rcp_f32_e32 v55, v55
	s_nop 0
	v_mul_f32_e32 v51, v51, v55
	v_cvt_pk_bf16_f32 v240, v50, v51
	v_lshlrev_b32_e32 v50, 16, v9
	v_and_b32_e32 v51, 0xffff0000, v9
	v_lshlrev_b32_e32 v52, 16, v13
	v_and_b32_e32 v53, 0xffff0000, v13
	v_mul_f32_e32 v54, 0xbfb8aa3b, v52
	v_exp_f32_e32 v54, v54
	s_nop 0
	v_add_f32_e32 v54, 0x3f800000, v54
	v_rcp_f32_e32 v54, v54
	s_nop 0
	v_mul_f32_e32 v50, v50, v54
	v_mul_f32_e32 v55, 0xbfb8aa3b, v53
	v_exp_f32_e32 v55, v55
	s_nop 0
	v_add_f32_e32 v55, 0x3f800000, v55
	v_rcp_f32_e32 v55, v55
	s_nop 0
	v_mul_f32_e32 v51, v51, v55
	v_cvt_pk_bf16_f32 v241, v50, v51
	v_lshlrev_b32_e32 v50, 16, v10
	v_and_b32_e32 v51, 0xffff0000, v10
	v_lshlrev_b32_e32 v52, 16, v14
	v_and_b32_e32 v53, 0xffff0000, v14
	v_mul_f32_e32 v54, 0xbfb8aa3b, v52
	v_exp_f32_e32 v54, v54
	s_nop 0
	v_add_f32_e32 v54, 0x3f800000, v54
	v_rcp_f32_e32 v54, v54
	s_nop 0
	v_mul_f32_e32 v50, v50, v54
	v_mul_f32_e32 v55, 0xbfb8aa3b, v53
	v_exp_f32_e32 v55, v55
	s_nop 0
	v_add_f32_e32 v55, 0x3f800000, v55
	v_rcp_f32_e32 v55, v55
	s_nop 0
	v_mul_f32_e32 v51, v51, v55
	v_cvt_pk_bf16_f32 v242, v50, v51
	v_lshlrev_b32_e32 v50, 16, v11
	v_and_b32_e32 v51, 0xffff0000, v11
	v_lshlrev_b32_e32 v52, 16, v15
	v_and_b32_e32 v53, 0xffff0000, v15
	v_mul_f32_e32 v54, 0xbfb8aa3b, v52
	v_exp_f32_e32 v54, v54
	s_nop 0
	v_add_f32_e32 v54, 0x3f800000, v54
	v_rcp_f32_e32 v54, v54
	s_nop 0
	v_mul_f32_e32 v50, v50, v54
	v_mul_f32_e32 v55, 0xbfb8aa3b, v53
	v_exp_f32_e32 v55, v55
	s_nop 0
	v_add_f32_e32 v55, 0x3f800000, v55
	v_rcp_f32_e32 v55, v55
	s_nop 0
	v_mul_f32_e32 v51, v51, v55
	v_cvt_pk_bf16_f32 v243, v50, v51
	v_cmp_gt_i32_e32 vcc, 0, v43
	v_mov_b32_e32 v56, 0
	s_nop 1
	v_cndmask_b32_e32 v240, v240, v56, vcc
	v_cndmask_b32_e32 v241, v241, v56, vcc
	v_cndmask_b32_e32 v242, v242, v56, vcc
	v_cndmask_b32_e32 v243, v243, v56, vcc
	v_lshlrev_b32_e32 v37, 10, v47
	v_add_u32_e32 v37, v211, v37
	ds_write_b128 v37, v[240:243]
	s_waitcnt vmcnt(2)
; DEVI unsigned pack2(float a, float b) { return (unsigned)f2bf(a) | ((unsigned)f2bf(b) << 16); }
; DEVI float sigmoidf_(float x) { return __builtin_amdgcn_rcpf(1.f + __expf(-x)); }
; DEVI void conv_tile(const Params& p, unsigned char* smem, int ct) {
;     ...
;   for (int it = tid; it < 62 * 64; it += 256) {
;     const int r = it >> 6, c8 = it & 63;
;     const int t = t0 - 30 + r;
;     uint4 pk = {0u, 0u, 0u, 0u};
;     if (t >= 0) {
;       const u16* src = p.proj + ((size_t)b * T + t) * LDP + c8 * 8;
;       const uint4 a = *(const uint4*)src, bb = *(const uint4*)(src + 512);
;       const unsigned au[4] = {a.x, a.y, a.z, a.w}, bu[4] = {bb.x, bb.y, bb.z, bb.w};
;       unsigned o[4];
; #pragma unroll
;       for (int j = 0; j < 4; ++j) {
;         const float a0 = __uint_as_float(au[j] << 16), a1 = __uint_as_float(au[j] & 0xffff0000u);
;         const float b0 = __uint_as_float(bu[j] << 16), b1 = __uint_as_float(bu[j] & 0xffff0000u);
;         o[j] = pack2(a0 * sigmoidf_(b0), a1 * sigmoidf_(b1));
;       }
;       pk.x = o[0]; pk.y = o[1]; pk.z = o[2]; pk.w = o[3];
;     }
;     *(uint4*)(sU + r * 512 + c8 * 8) = pk;
;   }
	v_lshlrev_b32_e32 v50, 16, v16
	v_and_b32_e32 v51, 0xffff0000, v16
	v_lshlrev_b32_e32 v52, 16, v20
	v_and_b32_e32 v53, 0xffff0000, v20
	v_mul_f32_e32 v54, 0xbfb8aa3b, v52
	v_exp_f32_e32 v54, v54
	s_nop 0
	v_add_f32_e32 v54, 0x3f800000, v54
	v_rcp_f32_e32 v54, v54
	s_nop 0
	v_mul_f32_e32 v50, v50, v54
	v_mul_f32_e32 v55, 0xbfb8aa3b, v53
	v_exp_f32_e32 v55, v55
	s_nop 0
	v_add_f32_e32 v55, 0x3f800000, v55
	v_rcp_f32_e32 v55, v55
	s_nop 0
	v_mul_f32_e32 v51, v51, v55
	v_cvt_pk_bf16_f32 v240, v50, v51
	v_lshlrev_b32_e32 v50, 16, v17
	v_and_b32_e32 v51, 0xffff0000, v17
	v_lshlrev_b32_e32 v52, 16, v21
	v_and_b32_e32 v53, 0xffff0000, v21
	v_mul_f32_e32 v54, 0xbfb8aa3b, v52
	v_exp_f32_e32 v54, v54
	s_nop 0
	v_add_f32_e32 v54, 0x3f800000, v54
	v_rcp_f32_e32 v54, v54
	s_nop 0
	v_mul_f32_e32 v50, v50, v54
	v_mul_f32_e32 v55, 0xbfb8aa3b, v53
	v_exp_f32_e32 v55, v55
	s_nop 0
	v_add_f32_e32 v55, 0x3f800000, v55
	v_rcp_f32_e32 v55, v55
	s_nop 0
	v_mul_f32_e32 v51, v51, v55
	v_cvt_pk_bf16_f32 v241, v50, v51
	v_lshlrev_b32_e32 v50, 16, v18
	v_and_b32_e32 v51, 0xffff0000, v18
	v_lshlrev_b32_e32 v52, 16, v22
	v_and_b32_e32 v53, 0xffff0000, v22
	v_mul_f32_e32 v54, 0xbfb8aa3b, v52
	v_exp_f32_e32 v54, v54
	s_nop 0
	v_add_f32_e32 v54, 0x3f800000, v54
	v_rcp_f32_e32 v54, v54
	s_nop 0
	v_mul_f32_e32 v50, v50, v54
	v_mul_f32_e32 v55, 0xbfb8aa3b, v53
	v_exp_f32_e32 v55, v55
	s_nop 0
	v_add_f32_e32 v55, 0x3f800000, v55
	v_rcp_f32_e32 v55, v55
	s_nop 0
	v_mul_f32_e32 v51, v51, v55
	v_cvt_pk_bf16_f32 v242, v50, v51
	v_lshlrev_b32_e32 v50, 16, v19
	v_and_b32_e32 v51, 0xffff0000, v19
	v_lshlrev_b32_e32 v52, 16, v23
	v_and_b32_e32 v53, 0xffff0000, v23
	v_mul_f32_e32 v54, 0xbfb8aa3b, v52
	v_exp_f32_e32 v54, v54
	s_nop 0
	v_add_f32_e32 v54, 0x3f800000, v54
	v_rcp_f32_e32 v54, v54
	s_nop 0
	v_mul_f32_e32 v50, v50, v54
	v_mul_f32_e32 v55, 0xbfb8aa3b, v53
	v_exp_f32_e32 v55, v55
	s_nop 0
	v_add_f32_e32 v55, 0x3f800000, v55
	v_rcp_f32_e32 v55, v55
	s_nop 0
	v_mul_f32_e32 v51, v51, v55
	v_cvt_pk_bf16_f32 v243, v50, v51
	v_cmp_gt_i32_e32 vcc, 0, v44
	v_mov_b32_e32 v56, 0
	s_nop 1
	v_cndmask_b32_e32 v240, v240, v56, vcc
	v_cndmask_b32_e32 v241, v241, v56, vcc
	v_cndmask_b32_e32 v242, v242, v56, vcc
	v_cndmask_b32_e32 v243, v243, v56, vcc
	v_lshlrev_b32_e32 v37, 10, v48
	v_add_u32_e32 v37, v211, v37
	ds_write_b128 v37, v[240:243]
	s_waitcnt vmcnt(0)
	v_lshlrev_b32_e32 v50, 16, v24
	v_and_b32_e32 v51, 0xffff0000, v24
	v_lshlrev_b32_e32 v52, 16, v28
	v_and_b32_e32 v53, 0xffff0000, v28
	v_mul_f32_e32 v54, 0xbfb8aa3b, v52
	v_exp_f32_e32 v54, v54
	s_nop 0
	v_add_f32_e32 v54, 0x3f800000, v54
	v_rcp_f32_e32 v54, v54
	s_nop 0
	v_mul_f32_e32 v50, v50, v54
	v_mul_f32_e32 v55, 0xbfb8aa3b, v53
	v_exp_f32_e32 v55, v55
	s_nop 0
	v_add_f32_e32 v55, 0x3f800000, v55
	v_rcp_f32_e32 v55, v55
	s_nop 0
	v_mul_f32_e32 v51, v51, v55
	v_cvt_pk_bf16_f32 v240, v50, v51
	v_lshlrev_b32_e32 v50, 16, v25
	v_and_b32_e32 v51, 0xffff0000, v25
	v_lshlrev_b32_e32 v52, 16, v29
	v_and_b32_e32 v53, 0xffff0000, v29
	v_mul_f32_e32 v54, 0xbfb8aa3b, v52
	v_exp_f32_e32 v54, v54
	s_nop 0
	v_add_f32_e32 v54, 0x3f800000, v54
	v_rcp_f32_e32 v54, v54
	s_nop 0
	v_mul_f32_e32 v50, v50, v54
	v_mul_f32_e32 v55, 0xbfb8aa3b, v53
	v_exp_f32_e32 v55, v55
	s_nop 0
	v_add_f32_e32 v55, 0x3f800000, v55
	v_rcp_f32_e32 v55, v55
	s_nop 0
	v_mul_f32_e32 v51, v51, v55
	v_cvt_pk_bf16_f32 v241, v50, v51
	v_lshlrev_b32_e32 v50, 16, v26
	v_and_b32_e32 v51, 0xffff0000, v26
	v_lshlrev_b32_e32 v52, 16, v30
	v_and_b32_e32 v53, 0xffff0000, v30
	v_mul_f32_e32 v54, 0xbfb8aa3b, v52
	v_exp_f32_e32 v54, v54
	s_nop 0
	v_add_f32_e32 v54, 0x3f800000, v54
	v_rcp_f32_e32 v54, v54
	s_nop 0
	v_mul_f32_e32 v50, v50, v54
	v_mul_f32_e32 v55, 0xbfb8aa3b, v53
	v_exp_f32_e32 v55, v55
	s_nop 0
	v_add_f32_e32 v55, 0x3f800000, v55
	v_rcp_f32_e32 v55, v55
	s_nop 0
	v_mul_f32_e32 v51, v51, v55
	v_cvt_pk_bf16_f32 v242, v50, v51
	v_lshlrev_b32_e32 v50, 16, v27
	v_and_b32_e32 v51, 0xffff0000, v27
	v_lshlrev_b32_e32 v52, 16, v31
	v_and_b32_e32 v53, 0xffff0000, v31
	v_mul_f32_e32 v54, 0xbfb8aa3b, v52
	v_exp_f32_e32 v54, v54
	s_nop 0
	v_add_f32_e32 v54, 0x3f800000, v54
	v_rcp_f32_e32 v54, v54
	s_nop 0
	v_mul_f32_e32 v50, v50, v54
	v_mul_f32_e32 v55, 0xbfb8aa3b, v53
	v_exp_f32_e32 v55, v55
	s_nop 0
	v_add_f32_e32 v55, 0x3f800000, v55
	v_rcp_f32_e32 v55, v55
	s_nop 0
	v_mul_f32_e32 v51, v51, v55
	v_cvt_pk_bf16_f32 v243, v50, v51
	v_cmp_gt_i32_e32 vcc, 0, v45
	v_mov_b32_e32 v56, 0
	s_nop 1
	v_cndmask_b32_e32 v240, v240, v56, vcc
	v_cndmask_b32_e32 v241, v241, v56, vcc
	v_cndmask_b32_e32 v242, v242, v56, vcc
	v_cndmask_b32_e32 v243, v243, v56, vcc
	v_lshlrev_b32_e32 v37, 10, v49
	v_add_u32_e32 v37, v211, v37
	ds_write_b128 v37, v[240:243]
	v_add_u32_e32 v34, 48, v212
	v_min_u32_e32 v34, 61, v34
	v_add_u32_e32 v35, s22, v34
	v_subrev_u32_e32 v35, 30, v35
	v_max_i32_e32 v38, 0, v35
	v_mul_u32_u24_e32 v36, 0x1240, v38
	v_add_u32_e32 v36, v211, v36
	v_mov_b32_e32 v42, v35
	v_mov_b32_e32 v46, v34
	global_load_dwordx4 v[0:3], v36, s[0:1]
	global_load_dwordx4 v[4:7], v36, s[0:1] offset:1024
	v_add_u32_e32 v34, 52, v212
	v_min_u32_e32 v34, 61, v34
	v_add_u32_e32 v35, s22, v34
	v_subrev_u32_e32 v35, 30, v35
	v_max_i32_e32 v39, 0, v35
	v_mul_u32_u24_e32 v36, 0x1240, v39
	v_add_u32_e32 v36, v211, v36
	v_mov_b32_e32 v43, v35
	v_mov_b32_e32 v47, v34
	global_load_dwordx4 v[8:11], v36, s[0:1]
	global_load_dwordx4 v[12:15], v36, s[0:1] offset:1024
	v_add_u32_e32 v34, 56, v212
	v_min_u32_e32 v34, 61, v34
	v_add_u32_e32 v35, s22, v34
	v_subrev_u32_e32 v35, 30, v35
	v_max_i32_e32 v40, 0, v35
	v_mul_u32_u24_e32 v36, 0x1240, v40
	v_add_u32_e32 v36, v211, v36
	v_mov_b32_e32 v44, v35
	v_mov_b32_e32 v48, v34
	global_load_dwordx4 v[16:19], v36, s[0:1]
	global_load_dwordx4 v[20:23], v36, s[0:1] offset:1024
	v_add_u32_e32 v34, 60, v212
	v_min_u32_e32 v34, 61, v34
	v_add_u32_e32 v35, s22, v34
	v_subrev_u32_e32 v35, 30, v35
	v_max_i32_e32 v41, 0, v35
	v_mul_u32_u24_e32 v36, 0x1240, v41
	v_add_u32_e32 v36, v211, v36
	v_mov_b32_e32 v45, v35
	v_mov_b32_e32 v49, v34
	global_load_dwordx4 v[24:27], v36, s[0:1]
	global_load_dwordx4 v[28:31], v36, s[0:1] offset:1024
	s_waitcnt vmcnt(6)
; DEVI unsigned pack2(float a, float b) { return (unsigned)f2bf(a) | ((unsigned)f2bf(b) << 16); }
; DEVI float sigmoidf_(float x) { return __builtin_amdgcn_rcpf(1.f + __expf(-x)); }
; DEVI void conv_tile(const Params& p, unsigned char* smem, int ct) {
;     ...
;   for (int it = tid; it < 62 * 64; it += 256) {
;     const int r = it >> 6, c8 = it & 63;
;     const int t = t0 - 30 + r;
;     uint4 pk = {0u, 0u, 0u, 0u};
;     if (t >= 0) {
;       const u16* src = p.proj + ((size_t)b * T + t) * LDP + c8 * 8;
;       const uint4 a = *(const uint4*)src, bb = *(const uint4*)(src + 512);
;       const unsigned au[4] = {a.x, a.y, a.z, a.w}, bu[4] = {bb.x, bb.y, bb.z, bb.w};
;       unsigned o[4];
; #pragma unroll
;       for (int j = 0; j < 4; ++j) {
;         const float a0 = __uint_as_float(au[j] << 16), a1 = __uint_as_float(au[j] & 0xffff0000u);
;         const float b0 = __uint_as_float(bu[j] << 16), b1 = __uint_as_float(bu[j] & 0xffff0000u);
;         o[j] = pack2(a0 * sigmoidf_(b0), a1 * sigmoidf_(b1));
;       }
;       pk.x = o[0]; pk.y = o[1]; pk.z = o[2]; pk.w = o[3];
;     }
;     *(uint4*)(sU + r * 512 + c8 * 8) = pk;
;   }
	v_lshlrev_b32_e32 v50, 16, v0
	v_and_b32_e32 v51, 0xffff0000, v0
	v_lshlrev_b32_e32 v52, 16, v4
	v_and_b32_e32 v53, 0xffff0000, v4
	v_mul_f32_e32 v54, 0xbfb8aa3b, v52
	v_exp_f32_e32 v54, v54
	s_nop 0
	v_add_f32_e32 v54, 0x3f800000, v54
	v_rcp_f32_e32 v54, v54
	s_nop 0
	v_mul_f32_e32 v50, v50, v54
	v_mul_f32_e32 v55, 0xbfb8aa3b, v53
	v_exp_f32_e32 v55, v55
	s_nop 0
	v_add_f32_e32 v55, 0x3f800000, v55
	v_rcp_f32_e32 v55, v55
	s_nop 0
	v_mul_f32_e32 v51, v51, v55
	v_cvt_pk_bf16_f32 v240, v50, v51
	v_lshlrev_b32_e32 v50, 16, v1
	v_and_b32_e32 v51, 0xffff0000, v1
	v_lshlrev_b32_e32 v52, 16, v5
	v_and_b32_e32 v53, 0xffff0000, v5
	v_mul_f32_e32 v54, 0xbfb8aa3b, v52
	v_exp_f32_e32 v54, v54
	s_nop 0
	v_add_f32_e32 v54, 0x3f800000, v54
	v_rcp_f32_e32 v54, v54
	s_nop 0
	v_mul_f32_e32 v50, v50, v54
	v_mul_f32_e32 v55, 0xbfb8aa3b, v53
	v_exp_f32_e32 v55, v55
	s_nop 0
	v_add_f32_e32 v55, 0x3f800000, v55
	v_rcp_f32_e32 v55, v55
	s_nop 0
	v_mul_f32_e32 v51, v51, v55
	v_cvt_pk_bf16_f32 v241, v50, v51
	v_lshlrev_b32_e32 v50, 16, v2
	v_and_b32_e32 v51, 0xffff0000, v2
	v_lshlrev_b32_e32 v52, 16, v6
	v_and_b32_e32 v53, 0xffff0000, v6
	v_mul_f32_e32 v54, 0xbfb8aa3b, v52
	v_exp_f32_e32 v54, v54
	s_nop 0
	v_add_f32_e32 v54, 0x3f800000, v54
	v_rcp_f32_e32 v54, v54
	s_nop 0
	v_mul_f32_e32 v50, v50, v54
	v_mul_f32_e32 v55, 0xbfb8aa3b, v53
	v_exp_f32_e32 v55, v55
	s_nop 0
	v_add_f32_e32 v55, 0x3f800000, v55
	v_rcp_f32_e32 v55, v55
	s_nop 0
	v_mul_f32_e32 v51, v51, v55
	v_cvt_pk_bf16_f32 v242, v50, v51
	v_lshlrev_b32_e32 v50, 16, v3
	v_and_b32_e32 v51, 0xffff0000, v3
	v_lshlrev_b32_e32 v52, 16, v7
	v_and_b32_e32 v53, 0xffff0000, v7
	v_mul_f32_e32 v54, 0xbfb8aa3b, v52
	v_exp_f32_e32 v54, v54
	s_nop 0
	v_add_f32_e32 v54, 0x3f800000, v54
	v_rcp_f32_e32 v54, v54
	s_nop 0
	v_mul_f32_e32 v50, v50, v54
	v_mul_f32_e32 v55, 0xbfb8aa3b, v53
	v_exp_f32_e32 v55, v55
	s_nop 0
	v_add_f32_e32 v55, 0x3f800000, v55
	v_rcp_f32_e32 v55, v55
	s_nop 0
	v_mul_f32_e32 v51, v51, v55
	v_cvt_pk_bf16_f32 v243, v50, v51
	v_cmp_gt_i32_e32 vcc, 0, v42
	v_mov_b32_e32 v56, 0
	s_nop 1
	v_cndmask_b32_e32 v240, v240, v56, vcc
	v_cndmask_b32_e32 v241, v241, v56, vcc
	v_cndmask_b32_e32 v242, v242, v56, vcc
	v_cndmask_b32_e32 v243, v243, v56, vcc
	v_lshlrev_b32_e32 v37, 10, v46
	v_add_u32_e32 v37, v211, v37
	ds_write_b128 v37, v[240:243]
	s_waitcnt vmcnt(4)
	v_lshlrev_b32_e32 v50, 16, v8
	v_and_b32_e32 v51, 0xffff0000, v8
	v_lshlrev_b32_e32 v52, 16, v12
	v_and_b32_e32 v53, 0xffff0000, v12
	v_mul_f32_e32 v54, 0xbfb8aa3b, v52
	v_exp_f32_e32 v54, v54
	s_nop 0
	v_add_f32_e32 v54, 0x3f800000, v54
	v_rcp_f32_e32 v54, v54
	s_nop 0
	v_mul_f32_e32 v50, v50, v54
	v_mul_f32_e32 v55, 0xbfb8aa3b, v53
	v_exp_f32_e32 v55, v55
	s_nop 0
	v_add_f32_e32 v55, 0x3f800000, v55
	v_rcp_f32_e32 v55, v55
	s_nop 0
	v_mul_f32_e32 v51, v51, v55
	v_cvt_pk_bf16_f32 v240, v50, v51
	v_lshlrev_b32_e32 v50, 16, v9
	v_and_b32_e32 v51, 0xffff0000, v9
	v_lshlrev_b32_e32 v52, 16, v13
	v_and_b32_e32 v53, 0xffff0000, v13
	v_mul_f32_e32 v54, 0xbfb8aa3b, v52
	v_exp_f32_e32 v54, v54
	s_nop 0
	v_add_f32_e32 v54, 0x3f800000, v54
	v_rcp_f32_e32 v54, v54
	s_nop 0
	v_mul_f32_e32 v50, v50, v54
	v_mul_f32_e32 v55, 0xbfb8aa3b, v53
	v_exp_f32_e32 v55, v55
	s_nop 0
	v_add_f32_e32 v55, 0x3f800000, v55
	v_rcp_f32_e32 v55, v55
	s_nop 0
	v_mul_f32_e32 v51, v51, v55
	v_cvt_pk_bf16_f32 v241, v50, v51
	v_lshlrev_b32_e32 v50, 16, v10
	v_and_b32_e32 v51, 0xffff0000, v10
	v_lshlrev_b32_e32 v52, 16, v14
	v_and_b32_e32 v53, 0xffff0000, v14
	v_mul_f32_e32 v54, 0xbfb8aa3b, v52
	v_exp_f32_e32 v54, v54
	s_nop 0
	v_add_f32_e32 v54, 0x3f800000, v54
	v_rcp_f32_e32 v54, v54
	s_nop 0
	v_mul_f32_e32 v50, v50, v54
	v_mul_f32_e32 v55, 0xbfb8aa3b, v53
	v_exp_f32_e32 v55, v55
	s_nop 0
	v_add_f32_e32 v55, 0x3f800000, v55
	v_rcp_f32_e32 v55, v55
	s_nop 0
	v_mul_f32_e32 v51, v51, v55
	v_cvt_pk_bf16_f32 v242, v50, v51
	v_lshlrev_b32_e32 v50, 16, v11
	v_and_b32_e32 v51, 0xffff0000, v11
	v_lshlrev_b32_e32 v52, 16, v15
	v_and_b32_e32 v53, 0xffff0000, v15
	v_mul_f32_e32 v54, 0xbfb8aa3b, v52
	v_exp_f32_e32 v54, v54
	s_nop 0
	v_add_f32_e32 v54, 0x3f800000, v54
	v_rcp_f32_e32 v54, v54
	s_nop 0
	v_mul_f32_e32 v50, v50, v54
	v_mul_f32_e32 v55, 0xbfb8aa3b, v53
	v_exp_f32_e32 v55, v55
	s_nop 0
	v_add_f32_e32 v55, 0x3f800000, v55
	v_rcp_f32_e32 v55, v55
	s_nop 0
	v_mul_f32_e32 v51, v51, v55
	v_cvt_pk_bf16_f32 v243, v50, v51
	v_cmp_gt_i32_e32 vcc, 0, v43
	v_mov_b32_e32 v56, 0
	s_nop 1
	v_cndmask_b32_e32 v240, v240, v56, vcc
	v_cndmask_b32_e32 v241, v241, v56, vcc
	v_cndmask_b32_e32 v242, v242, v56, vcc
	v_cndmask_b32_e32 v243, v243, v56, vcc
	v_lshlrev_b32_e32 v37, 10, v47
	v_add_u32_e32 v37, v211, v37
	ds_write_b128 v37, v[240:243]
	s_waitcnt vmcnt(2)
; DEVI unsigned pack2(float a, float b) { return (unsigned)f2bf(a) | ((unsigned)f2bf(b) << 16); }
; DEVI float sigmoidf_(float x) { return __builtin_amdgcn_rcpf(1.f + __expf(-x)); }
; DEVI void conv_tile(const Params& p, unsigned char* smem, int ct) {
;     ...
;   for (int it = tid; it < 62 * 64; it += 256) {
;     const int r = it >> 6, c8 = it & 63;
;     const int t = t0 - 30 + r;
;     uint4 pk = {0u, 0u, 0u, 0u};
;     if (t >= 0) {
;       const u16* src = p.proj + ((size_t)b * T + t) * LDP + c8 * 8;
;       const uint4 a = *(const uint4*)src, bb = *(const uint4*)(src + 512);
;       const unsigned au[4] = {a.x, a.y, a.z, a.w}, bu[4] = {bb.x, bb.y, bb.z, bb.w};
;       unsigned o[4];
; #pragma unroll
;       for (int j = 0; j < 4; ++j) {
;         const float a0 = __uint_as_float(au[j] << 16), a1 = __uint_as_float(au[j] & 0xffff0000u);
;         const float b0 = __uint_as_float(bu[j] << 16), b1 = __uint_as_float(bu[j] & 0xffff0000u);
;         o[j] = pack2(a0 * sigmoidf_(b0), a1 * sigmoidf_(b1));
;       }
;       pk.x = o[0]; pk.y = o[1]; pk.z = o[2]; pk.w = o[3];
;     }
;     *(uint4*)(sU + r * 512 + c8 * 8) = pk;
;   }
	v_lshlrev_b32_e32 v50, 16, v16
	v_and_b32_e32 v51, 0xffff0000, v16
	v_lshlrev_b32_e32 v52, 16, v20
	v_and_b32_e32 v53, 0xffff0000, v20
	v_mul_f32_e32 v54, 0xbfb8aa3b, v52
	v_exp_f32_e32 v54, v54
	s_nop 0
	v_add_f32_e32 v54, 0x3f800000, v54
	v_rcp_f32_e32 v54, v54
	s_nop 0
	v_mul_f32_e32 v50, v50, v54
	v_mul_f32_e32 v55, 0xbfb8aa3b, v53
	v_exp_f32_e32 v55, v55
	s_nop 0
	v_add_f32_e32 v55, 0x3f800000, v55
	v_rcp_f32_e32 v55, v55
	s_nop 0
	v_mul_f32_e32 v51, v51, v55
	v_cvt_pk_bf16_f32 v240, v50, v51
	v_lshlrev_b32_e32 v50, 16, v17
	v_and_b32_e32 v51, 0xffff0000, v17
	v_lshlrev_b32_e32 v52, 16, v21
	v_and_b32_e32 v53, 0xffff0000, v21
	v_mul_f32_e32 v54, 0xbfb8aa3b, v52
	v_exp_f32_e32 v54, v54
	s_nop 0
	v_add_f32_e32 v54, 0x3f800000, v54
	v_rcp_f32_e32 v54, v54
	s_nop 0
	v_mul_f32_e32 v50, v50, v54
	v_mul_f32_e32 v55, 0xbfb8aa3b, v53
	v_exp_f32_e32 v55, v55
	s_nop 0
	v_add_f32_e32 v55, 0x3f800000, v55
	v_rcp_f32_e32 v55, v55
	s_nop 0
	v_mul_f32_e32 v51, v51, v55
	v_cvt_pk_bf16_f32 v241, v50, v51
	v_lshlrev_b32_e32 v50, 16, v18
	v_and_b32_e32 v51, 0xffff0000, v18
	v_lshlrev_b32_e32 v52, 16, v22
	v_and_b32_e32 v53, 0xffff0000, v22
	v_mul_f32_e32 v54, 0xbfb8aa3b, v52
	v_exp_f32_e32 v54, v54
	s_nop 0
	v_add_f32_e32 v54, 0x3f800000, v54
	v_rcp_f32_e32 v54, v54
	s_nop 0
	v_mul_f32_e32 v50, v50, v54
	v_mul_f32_e32 v55, 0xbfb8aa3b, v53
	v_exp_f32_e32 v55, v55
	s_nop 0
	v_add_f32_e32 v55, 0x3f800000, v55
	v_rcp_f32_e32 v55, v55
	s_nop 0
	v_mul_f32_e32 v51, v51, v55
	v_cvt_pk_bf16_f32 v242, v50, v51
	v_lshlrev_b32_e32 v50, 16, v19
	v_and_b32_e32 v51, 0xffff0000, v19
	v_lshlrev_b32_e32 v52, 16, v23
	v_and_b32_e32 v53, 0xffff0000, v23
	v_mul_f32_e32 v54, 0xbfb8aa3b, v52
	v_exp_f32_e32 v54, v54
	s_nop 0
	v_add_f32_e32 v54, 0x3f800000, v54
	v_rcp_f32_e32 v54, v54
	s_nop 0
	v_mul_f32_e32 v50, v50, v54
	v_mul_f32_e32 v55, 0xbfb8aa3b, v53
	v_exp_f32_e32 v55, v55
	s_nop 0
	v_add_f32_e32 v55, 0x3f800000, v55
	v_rcp_f32_e32 v55, v55
	s_nop 0
	v_mul_f32_e32 v51, v51, v55
	v_cvt_pk_bf16_f32 v243, v50, v51
	v_cmp_gt_i32_e32 vcc, 0, v44
	v_mov_b32_e32 v56, 0
	s_nop 1
	v_cndmask_b32_e32 v240, v240, v56, vcc
	v_cndmask_b32_e32 v241, v241, v56, vcc
	v_cndmask_b32_e32 v242, v242, v56, vcc
	v_cndmask_b32_e32 v243, v243, v56, vcc
	v_lshlrev_b32_e32 v37, 10, v48
	v_add_u32_e32 v37, v211, v37
	ds_write_b128 v37, v[240:243]
	s_waitcnt vmcnt(0)
	v_lshlrev_b32_e32 v50, 16, v24
	v_and_b32_e32 v51, 0xffff0000, v24
	v_lshlrev_b32_e32 v52, 16, v28
	v_and_b32_e32 v53, 0xffff0000, v28
	v_mul_f32_e32 v54, 0xbfb8aa3b, v52
	v_exp_f32_e32 v54, v54
	s_nop 0
	v_add_f32_e32 v54, 0x3f800000, v54
	v_rcp_f32_e32 v54, v54
	s_nop 0
	v_mul_f32_e32 v50, v50, v54
	v_mul_f32_e32 v55, 0xbfb8aa3b, v53
	v_exp_f32_e32 v55, v55
	s_nop 0
	v_add_f32_e32 v55, 0x3f800000, v55
	v_rcp_f32_e32 v55, v55
	s_nop 0
	v_mul_f32_e32 v51, v51, v55
	v_cvt_pk_bf16_f32 v240, v50, v51
	v_lshlrev_b32_e32 v50, 16, v25
	v_and_b32_e32 v51, 0xffff0000, v25
	v_lshlrev_b32_e32 v52, 16, v29
	v_and_b32_e32 v53, 0xffff0000, v29
	v_mul_f32_e32 v54, 0xbfb8aa3b, v52
	v_exp_f32_e32 v54, v54
	s_nop 0
	v_add_f32_e32 v54, 0x3f800000, v54
	v_rcp_f32_e32 v54, v54
	s_nop 0
	v_mul_f32_e32 v50, v50, v54
	v_mul_f32_e32 v55, 0xbfb8aa3b, v53
	v_exp_f32_e32 v55, v55
	s_nop 0
	v_add_f32_e32 v55, 0x3f800000, v55
	v_rcp_f32_e32 v55, v55
	s_nop 0
	v_mul_f32_e32 v51, v51, v55
	v_cvt_pk_bf16_f32 v241, v50, v51
	v_lshlrev_b32_e32 v50, 16, v26
	v_and_b32_e32 v51, 0xffff0000, v26
	v_lshlrev_b32_e32 v52, 16, v30
	v_and_b32_e32 v53, 0xffff0000, v30
	v_mul_f32_e32 v54, 0xbfb8aa3b, v52
	v_exp_f32_e32 v54, v54
	s_nop 0
	v_add_f32_e32 v54, 0x3f800000, v54
	v_rcp_f32_e32 v54, v54
	s_nop 0
	v_mul_f32_e32 v50, v50, v54
	v_mul_f32_e32 v55, 0xbfb8aa3b, v53
	v_exp_f32_e32 v55, v55
	s_nop 0
	v_add_f32_e32 v55, 0x3f800000, v55
	v_rcp_f32_e32 v55, v55
	s_nop 0
	v_mul_f32_e32 v51, v51, v55
	v_cvt_pk_bf16_f32 v242, v50, v51
	v_lshlrev_b32_e32 v50, 16, v27
	v_and_b32_e32 v51, 0xffff0000, v27
	v_lshlrev_b32_e32 v52, 16, v31
	v_and_b32_e32 v53, 0xffff0000, v31
	v_mul_f32_e32 v54, 0xbfb8aa3b, v52
	v_exp_f32_e32 v54, v54
	s_nop 0
	v_add_f32_e32 v54, 0x3f800000, v54
	v_rcp_f32_e32 v54, v54
	s_nop 0
	v_mul_f32_e32 v50, v50, v54
	v_mul_f32_e32 v55, 0xbfb8aa3b, v53
	v_exp_f32_e32 v55, v55
	s_nop 0
	v_add_f32_e32 v55, 0x3f800000, v55
	v_rcp_f32_e32 v55, v55
	s_nop 0
	v_mul_f32_e32 v51, v51, v55
	v_cvt_pk_bf16_f32 v243, v50, v51
	v_cmp_gt_i32_e32 vcc, 0, v45
	v_mov_b32_e32 v56, 0
	s_nop 1
	v_cndmask_b32_e32 v240, v240, v56, vcc
	v_cndmask_b32_e32 v241, v241, v56, vcc
	v_cndmask_b32_e32 v242, v242, v56, vcc
	v_cndmask_b32_e32 v243, v243, v56, vcc
	v_lshlrev_b32_e32 v37, 10, v49
	v_add_u32_e32 v37, v211, v37
	ds_write_b128 v37, v[240:243]
	s_waitcnt vmcnt(0) lgkmcnt(0)
	s_barrier
; DEVI void conv_tile(const Params& p, unsigned char* smem, int ct) {
;     ...
;   float ya[32], yb[32];
; #pragma unroll
;   for (int tt = 0; tt < 32; ++tt) {
;     float y0 = bd0, y1 = bd1;
; #pragma unroll
;     for (int j = 0; j < 31; ++j) {
;       const unsigned uu = *(const unsigned*)(sU + (tt + j) * 512 + c);
;       y0 += w0[j] * __uint_as_float(uu << 16);
;       y1 += w1[j] * __uint_as_float(uu & 0xffff0000u);
;     }
;     ya[tt] = y0; yb[tt] = y1;
	v_mov_b32_e32 v128, v192
	v_mov_b32_e32 v129, v193
	v_mov_b32_e32 v130, v192
	v_mov_b32_e32 v131, v193
	v_mov_b32_e32 v132, v192
	v_mov_b32_e32 v133, v193
	v_mov_b32_e32 v134, v192
	v_mov_b32_e32 v135, v193
	v_mov_b32_e32 v136, v192
	v_mov_b32_e32 v137, v193
	v_mov_b32_e32 v138, v192
	v_mov_b32_e32 v139, v193
	v_mov_b32_e32 v140, v192
	v_mov_b32_e32 v141, v193
	v_mov_b32_e32 v142, v192
	v_mov_b32_e32 v143, v193
	v_mov_b32_e32 v144, v192
	v_mov_b32_e32 v145, v193
	v_mov_b32_e32 v146, v192
	v_mov_b32_e32 v147, v193
	v_mov_b32_e32 v148, v192
	v_mov_b32_e32 v149, v193
	v_mov_b32_e32 v150, v192
	v_mov_b32_e32 v151, v193
	v_mov_b32_e32 v152, v192
	v_mov_b32_e32 v153, v193
	v_mov_b32_e32 v154, v192
	v_mov_b32_e32 v155, v193
	v_mov_b32_e32 v156, v192
	v_mov_b32_e32 v157, v193
	v_mov_b32_e32 v158, v192
	v_mov_b32_e32 v159, v193
	v_mov_b32_e32 v160, v192
	v_mov_b32_e32 v161, v193
	v_mov_b32_e32 v162, v192
	v_mov_b32_e32 v163, v193
	v_mov_b32_e32 v164, v192
	v_mov_b32_e32 v165, v193
	v_mov_b32_e32 v166, v192
	v_mov_b32_e32 v167, v193
	v_mov_b32_e32 v168, v192
	v_mov_b32_e32 v169, v193
	v_mov_b32_e32 v170, v192
	v_mov_b32_e32 v171, v193
	v_mov_b32_e32 v172, v192
	v_mov_b32_e32 v173, v193
	v_mov_b32_e32 v174, v192
	v_mov_b32_e32 v175, v193
	v_mov_b32_e32 v176, v192
	v_mov_b32_e32 v177, v193
	v_mov_b32_e32 v178, v192
	v_mov_b32_e32 v179, v193
	v_mov_b32_e32 v180, v192
	v_mov_b32_e32 v181, v193
	v_mov_b32_e32 v182, v192
	v_mov_b32_e32 v183, v193
	v_mov_b32_e32 v184, v192
	v_mov_b32_e32 v185, v193
	v_mov_b32_e32 v186, v192
	v_mov_b32_e32 v187, v193
	v_mov_b32_e32 v188, v192
	v_mov_b32_e32 v189, v193
	v_mov_b32_e32 v190, v192
	v_mov_b32_e32 v191, v193
	ds_read_b32 v0, v209
	ds_read_b32 v1, v209 offset:1024
	ds_read_b32 v2, v209 offset:2048
	ds_read_b32 v3, v209 offset:3072
	ds_read_b32 v4, v209 offset:4096
	ds_read_b32 v5, v209 offset:5120
	ds_read_b32 v6, v209 offset:6144
	ds_read_b32 v7, v209 offset:7168
	ds_read_b32 v8, v209 offset:8192
	ds_read_b32 v9, v209 offset:9216
	ds_read_b32 v10, v209 offset:10240
	ds_read_b32 v11, v209 offset:11264
	ds_read_b32 v12, v209 offset:12288
	ds_read_b32 v13, v209 offset:13312
	ds_read_b32 v14, v209 offset:14336
	ds_read_b32 v15, v209 offset:15360
	s_waitcnt lgkmcnt(15)
	v_lshlrev_b32_e32 v50, 16, v0
	v_and_b32_e32 v51, 0xffff0000, v0
	v_pk_fma_f32 v[128:129], v[66:67], v[50:51], v[128:129]
	s_waitcnt lgkmcnt(14)
	v_lshlrev_b32_e32 v52, 16, v1
	v_and_b32_e32 v53, 0xffff0000, v1
	v_pk_fma_f32 v[128:129], v[68:69], v[52:53], v[128:129]
	v_pk_fma_f32 v[130:131], v[66:67], v[52:53], v[130:131]
	s_waitcnt lgkmcnt(13)
	v_lshlrev_b32_e32 v54, 16, v2
	v_and_b32_e32 v55, 0xffff0000, v2
	v_pk_fma_f32 v[128:129], v[70:71], v[54:55], v[128:129]
	v_pk_fma_f32 v[130:131], v[68:69], v[54:55], v[130:131]
	v_pk_fma_f32 v[132:133], v[66:67], v[54:55], v[132:133]
	s_waitcnt lgkmcnt(12)
	v_lshlrev_b32_e32 v56, 16, v3
	v_and_b32_e32 v57, 0xffff0000, v3
	v_pk_fma_f32 v[128:129], v[72:73], v[56:57], v[128:129]
	v_pk_fma_f32 v[130:131], v[70:71], v[56:57], v[130:131]
	v_pk_fma_f32 v[132:133], v[68:69], v[56:57], v[132:133]
	v_pk_fma_f32 v[134:135], v[66:67], v[56:57], v[134:135]
	s_waitcnt lgkmcnt(11)
	v_lshlrev_b32_e32 v50, 16, v4
	v_and_b32_e32 v51, 0xffff0000, v4
	v_pk_fma_f32 v[128:129], v[74:75], v[50:51], v[128:129]
	v_pk_fma_f32 v[130:131], v[72:73], v[50:51], v[130:131]
	v_pk_fma_f32 v[132:133], v[70:71], v[50:51], v[132:133]
	v_pk_fma_f32 v[134:135], v[68:69], v[50:51], v[134:135]
	v_pk_fma_f32 v[136:137], v[66:67], v[50:51], v[136:137]
	s_waitcnt lgkmcnt(10)
	v_lshlrev_b32_e32 v52, 16, v5
	v_and_b32_e32 v53, 0xffff0000, v5
	v_pk_fma_f32 v[128:129], v[76:77], v[52:53], v[128:129]
	v_pk_fma_f32 v[130:131], v[74:75], v[52:53], v[130:131]
	v_pk_fma_f32 v[132:133], v[72:73], v[52:53], v[132:133]
	v_pk_fma_f32 v[134:135], v[70:71], v[52:53], v[134:135]
	v_pk_fma_f32 v[136:137], v[68:69], v[52:53], v[136:137]
	v_pk_fma_f32 v[138:139], v[66:67], v[52:53], v[138:139]
	s_waitcnt lgkmcnt(9)
	v_lshlrev_b32_e32 v54, 16, v6
	v_and_b32_e32 v55, 0xffff0000, v6
	v_pk_fma_f32 v[128:129], v[78:79], v[54:55], v[128:129]
	v_pk_fma_f32 v[130:131], v[76:77], v[54:55], v[130:131]
	v_pk_fma_f32 v[132:133], v[74:75], v[54:55], v[132:133]
	v_pk_fma_f32 v[134:135], v[72:73], v[54:55], v[134:135]
	v_pk_fma_f32 v[136:137], v[70:71], v[54:55], v[136:137]
	v_pk_fma_f32 v[138:139], v[68:69], v[54:55], v[138:139]
	v_pk_fma_f32 v[140:141], v[66:67], v[54:55], v[140:141]
	s_waitcnt lgkmcnt(8)
	v_lshlrev_b32_e32 v56, 16, v7
	v_and_b32_e32 v57, 0xffff0000, v7
	v_pk_fma_f32 v[128:129], v[80:81], v[56:57], v[128:129]
	v_pk_fma_f32 v[130:131], v[78:79], v[56:57], v[130:131]
	v_pk_fma_f32 v[132:133], v[76:77], v[56:57], v[132:133]
	v_pk_fma_f32 v[134:135], v[74:75], v[56:57], v[134:135]
	v_pk_fma_f32 v[136:137], v[72:73], v[56:57], v[136:137]
	v_pk_fma_f32 v[138:139], v[70:71], v[56:57], v[138:139]
	v_pk_fma_f32 v[140:141], v[68:69], v[56:57], v[140:141]
	v_pk_fma_f32 v[142:143], v[66:67], v[56:57], v[142:143]
	s_waitcnt lgkmcnt(7)
	v_lshlrev_b32_e32 v50, 16, v8
	v_and_b32_e32 v51, 0xffff0000, v8
	v_pk_fma_f32 v[128:129], v[82:83], v[50:51], v[128:129]
	v_pk_fma_f32 v[130:131], v[80:81], v[50:51], v[130:131]
	v_pk_fma_f32 v[132:133], v[78:79], v[50:51], v[132:133]
	v_pk_fma_f32 v[134:135], v[76:77], v[50:51], v[134:135]
	v_pk_fma_f32 v[136:137], v[74:75], v[50:51], v[136:137]
	v_pk_fma_f32 v[138:139], v[72:73], v[50:51], v[138:139]
	v_pk_fma_f32 v[140:141], v[70:71], v[50:51], v[140:141]
	v_pk_fma_f32 v[142:143], v[68:69], v[50:51], v[142:143]
	v_pk_fma_f32 v[144:145], v[66:67], v[50:51], v[144:145]
	s_waitcnt lgkmcnt(6)
; DEVI void conv_tile(const Params& p, unsigned char* smem, int ct) {
;     ...
;   float ya[32], yb[32];
; #pragma unroll
;   for (int tt = 0; tt < 32; ++tt) {
;     float y0 = bd0, y1 = bd1;
; #pragma unroll
;     for (int j = 0; j < 31; ++j) {
;       const unsigned uu = *(const unsigned*)(sU + (tt + j) * 512 + c);
;       y0 += w0[j] * __uint_as_float(uu << 16);
;       y1 += w1[j] * __uint_as_float(uu & 0xffff0000u);
;     }
;     ya[tt] = y0; yb[tt] = y1;
	v_lshlrev_b32_e32 v52, 16, v9
	v_and_b32_e32 v53, 0xffff0000, v9
	v_pk_fma_f32 v[128:129], v[84:85], v[52:53], v[128:129]
	v_pk_fma_f32 v[130:131], v[82:83], v[52:53], v[130:131]
	v_pk_fma_f32 v[132:133], v[80:81], v[52:53], v[132:133]
	v_pk_fma_f32 v[134:135], v[78:79], v[52:53], v[134:135]
	v_pk_fma_f32 v[136:137], v[76:77], v[52:53], v[136:137]
	v_pk_fma_f32 v[138:139], v[74:75], v[52:53], v[138:139]
	v_pk_fma_f32 v[140:141], v[72:73], v[52:53], v[140:141]
	v_pk_fma_f32 v[142:143], v[70:71], v[52:53], v[142:143]
	v_pk_fma_f32 v[144:145], v[68:69], v[52:53], v[144:145]
	v_pk_fma_f32 v[146:147], v[66:67], v[52:53], v[146:147]
	s_waitcnt lgkmcnt(5)
	v_lshlrev_b32_e32 v54, 16, v10
	v_and_b32_e32 v55, 0xffff0000, v10
	v_pk_fma_f32 v[128:129], v[86:87], v[54:55], v[128:129]
	v_pk_fma_f32 v[130:131], v[84:85], v[54:55], v[130:131]
	v_pk_fma_f32 v[132:133], v[82:83], v[54:55], v[132:133]
	v_pk_fma_f32 v[134:135], v[80:81], v[54:55], v[134:135]
	v_pk_fma_f32 v[136:137], v[78:79], v[54:55], v[136:137]
	v_pk_fma_f32 v[138:139], v[76:77], v[54:55], v[138:139]
	v_pk_fma_f32 v[140:141], v[74:75], v[54:55], v[140:141]
	v_pk_fma_f32 v[142:143], v[72:73], v[54:55], v[142:143]
	v_pk_fma_f32 v[144:145], v[70:71], v[54:55], v[144:145]
	v_pk_fma_f32 v[146:147], v[68:69], v[54:55], v[146:147]
	v_pk_fma_f32 v[148:149], v[66:67], v[54:55], v[148:149]
	s_waitcnt lgkmcnt(4)
	v_lshlrev_b32_e32 v56, 16, v11
	v_and_b32_e32 v57, 0xffff0000, v11
	v_pk_fma_f32 v[128:129], v[88:89], v[56:57], v[128:129]
	v_pk_fma_f32 v[130:131], v[86:87], v[56:57], v[130:131]
	v_pk_fma_f32 v[132:133], v[84:85], v[56:57], v[132:133]
	v_pk_fma_f32 v[134:135], v[82:83], v[56:57], v[134:135]
	v_pk_fma_f32 v[136:137], v[80:81], v[56:57], v[136:137]
	v_pk_fma_f32 v[138:139], v[78:79], v[56:57], v[138:139]
	v_pk_fma_f32 v[140:141], v[76:77], v[56:57], v[140:141]
	v_pk_fma_f32 v[142:143], v[74:75], v[56:57], v[142:143]
	v_pk_fma_f32 v[144:145], v[72:73], v[56:57], v[144:145]
	v_pk_fma_f32 v[146:147], v[70:71], v[56:57], v[146:147]
	v_pk_fma_f32 v[148:149], v[68:69], v[56:57], v[148:149]
	v_pk_fma_f32 v[150:151], v[66:67], v[56:57], v[150:151]
	s_waitcnt lgkmcnt(3)
	v_lshlrev_b32_e32 v50, 16, v12
	v_and_b32_e32 v51, 0xffff0000, v12
	v_pk_fma_f32 v[128:129], v[90:91], v[50:51], v[128:129]
	v_pk_fma_f32 v[130:131], v[88:89], v[50:51], v[130:131]
	v_pk_fma_f32 v[132:133], v[86:87], v[50:51], v[132:133]
	v_pk_fma_f32 v[134:135], v[84:85], v[50:51], v[134:135]
	v_pk_fma_f32 v[136:137], v[82:83], v[50:51], v[136:137]
	v_pk_fma_f32 v[138:139], v[80:81], v[50:51], v[138:139]
	v_pk_fma_f32 v[140:141], v[78:79], v[50:51], v[140:141]
	v_pk_fma_f32 v[142:143], v[76:77], v[50:51], v[142:143]
	v_pk_fma_f32 v[144:145], v[74:75], v[50:51], v[144:145]
	v_pk_fma_f32 v[146:147], v[72:73], v[50:51], v[146:147]
	v_pk_fma_f32 v[148:149], v[70:71], v[50:51], v[148:149]
	v_pk_fma_f32 v[150:151], v[68:69], v[50:51], v[150:151]
	v_pk_fma_f32 v[152:153], v[66:67], v[50:51], v[152:153]
	s_waitcnt lgkmcnt(2)
	v_lshlrev_b32_e32 v52, 16, v13
	v_and_b32_e32 v53, 0xffff0000, v13
	v_pk_fma_f32 v[128:129], v[92:93], v[52:53], v[128:129]
	v_pk_fma_f32 v[130:131], v[90:91], v[52:53], v[130:131]
	v_pk_fma_f32 v[132:133], v[88:89], v[52:53], v[132:133]
	v_pk_fma_f32 v[134:135], v[86:87], v[52:53], v[134:135]
	v_pk_fma_f32 v[136:137], v[84:85], v[52:53], v[136:137]
	v_pk_fma_f32 v[138:139], v[82:83], v[52:53], v[138:139]
	v_pk_fma_f32 v[140:141], v[80:81], v[52:53], v[140:141]
	v_pk_fma_f32 v[142:143], v[78:79], v[52:53], v[142:143]
	v_pk_fma_f32 v[144:145], v[76:77], v[52:53], v[144:145]
	v_pk_fma_f32 v[146:147], v[74:75], v[52:53], v[146:147]
	v_pk_fma_f32 v[148:149], v[72:73], v[52:53], v[148:149]
	v_pk_fma_f32 v[150:151], v[70:71], v[52:53], v[150:151]
	v_pk_fma_f32 v[152:153], v[68:69], v[52:53], v[152:153]
	v_pk_fma_f32 v[154:155], v[66:67], v[52:53], v[154:155]
	s_waitcnt lgkmcnt(1)
	v_lshlrev_b32_e32 v54, 16, v14
	v_and_b32_e32 v55, 0xffff0000, v14
	v_pk_fma_f32 v[128:129], v[94:95], v[54:55], v[128:129]
	v_pk_fma_f32 v[130:131], v[92:93], v[54:55], v[130:131]
	v_pk_fma_f32 v[132:133], v[90:91], v[54:55], v[132:133]
	v_pk_fma_f32 v[134:135], v[88:89], v[54:55], v[134:135]
	v_pk_fma_f32 v[136:137], v[86:87], v[54:55], v[136:137]
	v_pk_fma_f32 v[138:139], v[84:85], v[54:55], v[138:139]
	v_pk_fma_f32 v[140:141], v[82:83], v[54:55], v[140:141]
	v_pk_fma_f32 v[142:143], v[80:81], v[54:55], v[142:143]
	v_pk_fma_f32 v[144:145], v[78:79], v[54:55], v[144:145]
	v_pk_fma_f32 v[146:147], v[76:77], v[54:55], v[146:147]
	v_pk_fma_f32 v[148:149], v[74:75], v[54:55], v[148:149]
	v_pk_fma_f32 v[150:151], v[72:73], v[54:55], v[150:151]
	v_pk_fma_f32 v[152:153], v[70:71], v[54:55], v[152:153]
	v_pk_fma_f32 v[154:155], v[68:69], v[54:55], v[154:155]
	v_pk_fma_f32 v[156:157], v[66:67], v[54:55], v[156:157]
	s_waitcnt lgkmcnt(0)
	v_lshlrev_b32_e32 v56, 16, v15
	v_and_b32_e32 v57, 0xffff0000, v15
	v_pk_fma_f32 v[128:129], v[96:97], v[56:57], v[128:129]
	v_pk_fma_f32 v[130:131], v[94:95], v[56:57], v[130:131]
	v_pk_fma_f32 v[132:133], v[92:93], v[56:57], v[132:133]
	v_pk_fma_f32 v[134:135], v[90:91], v[56:57], v[134:135]
	v_pk_fma_f32 v[136:137], v[88:89], v[56:57], v[136:137]
	v_pk_fma_f32 v[138:139], v[86:87], v[56:57], v[138:139]
	v_pk_fma_f32 v[140:141], v[84:85], v[56:57], v[140:141]
	v_pk_fma_f32 v[142:143], v[82:83], v[56:57], v[142:143]
	v_pk_fma_f32 v[144:145], v[80:81], v[56:57], v[144:145]
	v_pk_fma_f32 v[146:147], v[78:79], v[56:57], v[146:147]
	v_pk_fma_f32 v[148:149], v[76:77], v[56:57], v[148:149]
	v_pk_fma_f32 v[150:151], v[74:75], v[56:57], v[150:151]
	v_pk_fma_f32 v[152:153], v[72:73], v[56:57], v[152:153]
	v_pk_fma_f32 v[154:155], v[70:71], v[56:57], v[154:155]
	v_pk_fma_f32 v[156:157], v[68:69], v[56:57], v[156:157]
	v_pk_fma_f32 v[158:159], v[66:67], v[56:57], v[158:159]
	ds_read_b32 v0, v209 offset:16384
	ds_read_b32 v1, v209 offset:17408
	ds_read_b32 v2, v209 offset:18432
	ds_read_b32 v3, v209 offset:19456
	ds_read_b32 v4, v209 offset:20480
	ds_read_b32 v5, v209 offset:21504
	ds_read_b32 v6, v209 offset:22528
	ds_read_b32 v7, v209 offset:23552
	ds_read_b32 v8, v209 offset:24576
	ds_read_b32 v9, v209 offset:25600
	ds_read_b32 v10, v209 offset:26624
	ds_read_b32 v11, v209 offset:27648
	ds_read_b32 v12, v209 offset:28672
	ds_read_b32 v13, v209 offset:29696
	ds_read_b32 v14, v209 offset:30720
	ds_read_b32 v15, v209 offset:31744
	s_waitcnt lgkmcnt(15)
; DEVI void conv_tile(const Params& p, unsigned char* smem, int ct) {
;     ...
;   float ya[32], yb[32];
; #pragma unroll
;   for (int tt = 0; tt < 32; ++tt) {
;     float y0 = bd0, y1 = bd1;
; #pragma unroll
;     for (int j = 0; j < 31; ++j) {
;       const unsigned uu = *(const unsigned*)(sU + (tt + j) * 512 + c);
;       y0 += w0[j] * __uint_as_float(uu << 16);
;       y1 += w1[j] * __uint_as_float(uu & 0xffff0000u);
;     }
;     ya[tt] = y0; yb[tt] = y1;
	v_lshlrev_b32_e32 v50, 16, v0
	v_and_b32_e32 v51, 0xffff0000, v0
	v_pk_fma_f32 v[128:129], v[98:99], v[50:51], v[128:129]
	v_pk_fma_f32 v[130:131], v[96:97], v[50:51], v[130:131]
	v_pk_fma_f32 v[132:133], v[94:95], v[50:51], v[132:133]
	v_pk_fma_f32 v[134:135], v[92:93], v[50:51], v[134:135]
	v_pk_fma_f32 v[136:137], v[90:91], v[50:51], v[136:137]
	v_pk_fma_f32 v[138:139], v[88:89], v[50:51], v[138:139]
	v_pk_fma_f32 v[140:141], v[86:87], v[50:51], v[140:141]
	v_pk_fma_f32 v[142:143], v[84:85], v[50:51], v[142:143]
	v_pk_fma_f32 v[144:145], v[82:83], v[50:51], v[144:145]
	v_pk_fma_f32 v[146:147], v[80:81], v[50:51], v[146:147]
	v_pk_fma_f32 v[148:149], v[78:79], v[50:51], v[148:149]
	v_pk_fma_f32 v[150:151], v[76:77], v[50:51], v[150:151]
	v_pk_fma_f32 v[152:153], v[74:75], v[50:51], v[152:153]
	v_pk_fma_f32 v[154:155], v[72:73], v[50:51], v[154:155]
	v_pk_fma_f32 v[156:157], v[70:71], v[50:51], v[156:157]
	v_pk_fma_f32 v[158:159], v[68:69], v[50:51], v[158:159]
	v_pk_fma_f32 v[160:161], v[66:67], v[50:51], v[160:161]
	s_waitcnt lgkmcnt(14)
	v_lshlrev_b32_e32 v52, 16, v1
	v_and_b32_e32 v53, 0xffff0000, v1
	v_pk_fma_f32 v[128:129], v[100:101], v[52:53], v[128:129]
	v_pk_fma_f32 v[130:131], v[98:99], v[52:53], v[130:131]
	v_pk_fma_f32 v[132:133], v[96:97], v[52:53], v[132:133]
	v_pk_fma_f32 v[134:135], v[94:95], v[52:53], v[134:135]
	v_pk_fma_f32 v[136:137], v[92:93], v[52:53], v[136:137]
	v_pk_fma_f32 v[138:139], v[90:91], v[52:53], v[138:139]
	v_pk_fma_f32 v[140:141], v[88:89], v[52:53], v[140:141]
	v_pk_fma_f32 v[142:143], v[86:87], v[52:53], v[142:143]
	v_pk_fma_f32 v[144:145], v[84:85], v[52:53], v[144:145]
	v_pk_fma_f32 v[146:147], v[82:83], v[52:53], v[146:147]
	v_pk_fma_f32 v[148:149], v[80:81], v[52:53], v[148:149]
	v_pk_fma_f32 v[150:151], v[78:79], v[52:53], v[150:151]
	v_pk_fma_f32 v[152:153], v[76:77], v[52:53], v[152:153]
	v_pk_fma_f32 v[154:155], v[74:75], v[52:53], v[154:155]
	v_pk_fma_f32 v[156:157], v[72:73], v[52:53], v[156:157]
	v_pk_fma_f32 v[158:159], v[70:71], v[52:53], v[158:159]
	v_pk_fma_f32 v[160:161], v[68:69], v[52:53], v[160:161]
	v_pk_fma_f32 v[162:163], v[66:67], v[52:53], v[162:163]
	s_waitcnt lgkmcnt(13)
	v_lshlrev_b32_e32 v54, 16, v2
	v_and_b32_e32 v55, 0xffff0000, v2
	v_pk_fma_f32 v[128:129], v[102:103], v[54:55], v[128:129]
	v_pk_fma_f32 v[130:131], v[100:101], v[54:55], v[130:131]
	v_pk_fma_f32 v[132:133], v[98:99], v[54:55], v[132:133]
	v_pk_fma_f32 v[134:135], v[96:97], v[54:55], v[134:135]
	v_pk_fma_f32 v[136:137], v[94:95], v[54:55], v[136:137]
	v_pk_fma_f32 v[138:139], v[92:93], v[54:55], v[138:139]
	v_pk_fma_f32 v[140:141], v[90:91], v[54:55], v[140:141]
	v_pk_fma_f32 v[142:143], v[88:89], v[54:55], v[142:143]
	v_pk_fma_f32 v[144:145], v[86:87], v[54:55], v[144:145]
	v_pk_fma_f32 v[146:147], v[84:85], v[54:55], v[146:147]
	v_pk_fma_f32 v[148:149], v[82:83], v[54:55], v[148:149]
	v_pk_fma_f32 v[150:151], v[80:81], v[54:55], v[150:151]
	v_pk_fma_f32 v[152:153], v[78:79], v[54:55], v[152:153]
	v_pk_fma_f32 v[154:155], v[76:77], v[54:55], v[154:155]
	v_pk_fma_f32 v[156:157], v[74:75], v[54:55], v[156:157]
	v_pk_fma_f32 v[158:159], v[72:73], v[54:55], v[158:159]
	v_pk_fma_f32 v[160:161], v[70:71], v[54:55], v[160:161]
	v_pk_fma_f32 v[162:163], v[68:69], v[54:55], v[162:163]
	v_pk_fma_f32 v[164:165], v[66:67], v[54:55], v[164:165]
	s_waitcnt lgkmcnt(12)
	v_lshlrev_b32_e32 v56, 16, v3
	v_and_b32_e32 v57, 0xffff0000, v3
	v_pk_fma_f32 v[128:129], v[104:105], v[56:57], v[128:129]
	v_pk_fma_f32 v[130:131], v[102:103], v[56:57], v[130:131]
	v_pk_fma_f32 v[132:133], v[100:101], v[56:57], v[132:133]
	v_pk_fma_f32 v[134:135], v[98:99], v[56:57], v[134:135]
	v_pk_fma_f32 v[136:137], v[96:97], v[56:57], v[136:137]
	v_pk_fma_f32 v[138:139], v[94:95], v[56:57], v[138:139]
	v_pk_fma_f32 v[140:141], v[92:93], v[56:57], v[140:141]
	v_pk_fma_f32 v[142:143], v[90:91], v[56:57], v[142:143]
	v_pk_fma_f32 v[144:145], v[88:89], v[56:57], v[144:145]
	v_pk_fma_f32 v[146:147], v[86:87], v[56:57], v[146:147]
	v_pk_fma_f32 v[148:149], v[84:85], v[56:57], v[148:149]
	v_pk_fma_f32 v[150:151], v[82:83], v[56:57], v[150:151]
	v_pk_fma_f32 v[152:153], v[80:81], v[56:57], v[152:153]
	v_pk_fma_f32 v[154:155], v[78:79], v[56:57], v[154:155]
	v_pk_fma_f32 v[156:157], v[76:77], v[56:57], v[156:157]
	v_pk_fma_f32 v[158:159], v[74:75], v[56:57], v[158:159]
	v_pk_fma_f32 v[160:161], v[72:73], v[56:57], v[160:161]
	v_pk_fma_f32 v[162:163], v[70:71], v[56:57], v[162:163]
	v_pk_fma_f32 v[164:165], v[68:69], v[56:57], v[164:165]
	v_pk_fma_f32 v[166:167], v[66:67], v[56:57], v[166:167]
	s_waitcnt lgkmcnt(11)
	v_lshlrev_b32_e32 v50, 16, v4
	v_and_b32_e32 v51, 0xffff0000, v4
	v_pk_fma_f32 v[128:129], v[106:107], v[50:51], v[128:129]
	v_pk_fma_f32 v[130:131], v[104:105], v[50:51], v[130:131]
	v_pk_fma_f32 v[132:133], v[102:103], v[50:51], v[132:133]
	v_pk_fma_f32 v[134:135], v[100:101], v[50:51], v[134:135]
	v_pk_fma_f32 v[136:137], v[98:99], v[50:51], v[136:137]
	v_pk_fma_f32 v[138:139], v[96:97], v[50:51], v[138:139]
	v_pk_fma_f32 v[140:141], v[94:95], v[50:51], v[140:141]
	v_pk_fma_f32 v[142:143], v[92:93], v[50:51], v[142:143]
	v_pk_fma_f32 v[144:145], v[90:91], v[50:51], v[144:145]
	v_pk_fma_f32 v[146:147], v[88:89], v[50:51], v[146:147]
	v_pk_fma_f32 v[148:149], v[86:87], v[50:51], v[148:149]
	v_pk_fma_f32 v[150:151], v[84:85], v[50:51], v[150:151]
	v_pk_fma_f32 v[152:153], v[82:83], v[50:51], v[152:153]
	v_pk_fma_f32 v[154:155], v[80:81], v[50:51], v[154:155]
	v_pk_fma_f32 v[156:157], v[78:79], v[50:51], v[156:157]
	v_pk_fma_f32 v[158:159], v[76:77], v[50:51], v[158:159]
	v_pk_fma_f32 v[160:161], v[74:75], v[50:51], v[160:161]
	v_pk_fma_f32 v[162:163], v[72:73], v[50:51], v[162:163]
	v_pk_fma_f32 v[164:165], v[70:71], v[50:51], v[164:165]
	v_pk_fma_f32 v[166:167], v[68:69], v[50:51], v[166:167]
	v_pk_fma_f32 v[168:169], v[66:67], v[50:51], v[168:169]
	s_waitcnt lgkmcnt(10)
; DEVI void conv_tile(const Params& p, unsigned char* smem, int ct) {
;     ...
;   float ya[32], yb[32];
; #pragma unroll
;   for (int tt = 0; tt < 32; ++tt) {
;     float y0 = bd0, y1 = bd1;
; #pragma unroll
;     for (int j = 0; j < 31; ++j) {
;       const unsigned uu = *(const unsigned*)(sU + (tt + j) * 512 + c);
;       y0 += w0[j] * __uint_as_float(uu << 16);
;       y1 += w1[j] * __uint_as_float(uu & 0xffff0000u);
;     }
;     ya[tt] = y0; yb[tt] = y1;
	v_lshlrev_b32_e32 v52, 16, v5
	v_and_b32_e32 v53, 0xffff0000, v5
	v_pk_fma_f32 v[128:129], v[108:109], v[52:53], v[128:129]
	v_pk_fma_f32 v[130:131], v[106:107], v[52:53], v[130:131]
	v_pk_fma_f32 v[132:133], v[104:105], v[52:53], v[132:133]
	v_pk_fma_f32 v[134:135], v[102:103], v[52:53], v[134:135]
	v_pk_fma_f32 v[136:137], v[100:101], v[52:53], v[136:137]
	v_pk_fma_f32 v[138:139], v[98:99], v[52:53], v[138:139]
	v_pk_fma_f32 v[140:141], v[96:97], v[52:53], v[140:141]
	v_pk_fma_f32 v[142:143], v[94:95], v[52:53], v[142:143]
	v_pk_fma_f32 v[144:145], v[92:93], v[52:53], v[144:145]
	v_pk_fma_f32 v[146:147], v[90:91], v[52:53], v[146:147]
	v_pk_fma_f32 v[148:149], v[88:89], v[52:53], v[148:149]
	v_pk_fma_f32 v[150:151], v[86:87], v[52:53], v[150:151]
	v_pk_fma_f32 v[152:153], v[84:85], v[52:53], v[152:153]
	v_pk_fma_f32 v[154:155], v[82:83], v[52:53], v[154:155]
	v_pk_fma_f32 v[156:157], v[80:81], v[52:53], v[156:157]
	v_pk_fma_f32 v[158:159], v[78:79], v[52:53], v[158:159]
	v_pk_fma_f32 v[160:161], v[76:77], v[52:53], v[160:161]
	v_pk_fma_f32 v[162:163], v[74:75], v[52:53], v[162:163]
	v_pk_fma_f32 v[164:165], v[72:73], v[52:53], v[164:165]
	v_pk_fma_f32 v[166:167], v[70:71], v[52:53], v[166:167]
	v_pk_fma_f32 v[168:169], v[68:69], v[52:53], v[168:169]
	v_pk_fma_f32 v[170:171], v[66:67], v[52:53], v[170:171]
	s_waitcnt lgkmcnt(9)
	v_lshlrev_b32_e32 v54, 16, v6
	v_and_b32_e32 v55, 0xffff0000, v6
	v_pk_fma_f32 v[128:129], v[110:111], v[54:55], v[128:129]
	v_pk_fma_f32 v[130:131], v[108:109], v[54:55], v[130:131]
	v_pk_fma_f32 v[132:133], v[106:107], v[54:55], v[132:133]
	v_pk_fma_f32 v[134:135], v[104:105], v[54:55], v[134:135]
	v_pk_fma_f32 v[136:137], v[102:103], v[54:55], v[136:137]
	v_pk_fma_f32 v[138:139], v[100:101], v[54:55], v[138:139]
	v_pk_fma_f32 v[140:141], v[98:99], v[54:55], v[140:141]
	v_pk_fma_f32 v[142:143], v[96:97], v[54:55], v[142:143]
	v_pk_fma_f32 v[144:145], v[94:95], v[54:55], v[144:145]
	v_pk_fma_f32 v[146:147], v[92:93], v[54:55], v[146:147]
	v_pk_fma_f32 v[148:149], v[90:91], v[54:55], v[148:149]
	v_pk_fma_f32 v[150:151], v[88:89], v[54:55], v[150:151]
	v_pk_fma_f32 v[152:153], v[86:87], v[54:55], v[152:153]
	v_pk_fma_f32 v[154:155], v[84:85], v[54:55], v[154:155]
	v_pk_fma_f32 v[156:157], v[82:83], v[54:55], v[156:157]
	v_pk_fma_f32 v[158:159], v[80:81], v[54:55], v[158:159]
	v_pk_fma_f32 v[160:161], v[78:79], v[54:55], v[160:161]
	v_pk_fma_f32 v[162:163], v[76:77], v[54:55], v[162:163]
	v_pk_fma_f32 v[164:165], v[74:75], v[54:55], v[164:165]
	v_pk_fma_f32 v[166:167], v[72:73], v[54:55], v[166:167]
	v_pk_fma_f32 v[168:169], v[70:71], v[54:55], v[168:169]
	v_pk_fma_f32 v[170:171], v[68:69], v[54:55], v[170:171]
	v_pk_fma_f32 v[172:173], v[66:67], v[54:55], v[172:173]
	s_waitcnt lgkmcnt(8)
	v_lshlrev_b32_e32 v56, 16, v7
	v_and_b32_e32 v57, 0xffff0000, v7
	v_pk_fma_f32 v[128:129], v[112:113], v[56:57], v[128:129]
	v_pk_fma_f32 v[130:131], v[110:111], v[56:57], v[130:131]
	v_pk_fma_f32 v[132:133], v[108:109], v[56:57], v[132:133]
	v_pk_fma_f32 v[134:135], v[106:107], v[56:57], v[134:135]
	v_pk_fma_f32 v[136:137], v[104:105], v[56:57], v[136:137]
	v_pk_fma_f32 v[138:139], v[102:103], v[56:57], v[138:139]
	v_pk_fma_f32 v[140:141], v[100:101], v[56:57], v[140:141]
	v_pk_fma_f32 v[142:143], v[98:99], v[56:57], v[142:143]
	v_pk_fma_f32 v[144:145], v[96:97], v[56:57], v[144:145]
	v_pk_fma_f32 v[146:147], v[94:95], v[56:57], v[146:147]
	v_pk_fma_f32 v[148:149], v[92:93], v[56:57], v[148:149]
	v_pk_fma_f32 v[150:151], v[90:91], v[56:57], v[150:151]
	v_pk_fma_f32 v[152:153], v[88:89], v[56:57], v[152:153]
	v_pk_fma_f32 v[154:155], v[86:87], v[56:57], v[154:155]
	v_pk_fma_f32 v[156:157], v[84:85], v[56:57], v[156:157]
	v_pk_fma_f32 v[158:159], v[82:83], v[56:57], v[158:159]
	v_pk_fma_f32 v[160:161], v[80:81], v[56:57], v[160:161]
	v_pk_fma_f32 v[162:163], v[78:79], v[56:57], v[162:163]
	v_pk_fma_f32 v[164:165], v[76:77], v[56:57], v[164:165]
	v_pk_fma_f32 v[166:167], v[74:75], v[56:57], v[166:167]
	v_pk_fma_f32 v[168:169], v[72:73], v[56:57], v[168:169]
	v_pk_fma_f32 v[170:171], v[70:71], v[56:57], v[170:171]
	v_pk_fma_f32 v[172:173], v[68:69], v[56:57], v[172:173]
	v_pk_fma_f32 v[174:175], v[66:67], v[56:57], v[174:175]
	s_waitcnt lgkmcnt(7)
	v_lshlrev_b32_e32 v50, 16, v8
	v_and_b32_e32 v51, 0xffff0000, v8
	v_pk_fma_f32 v[128:129], v[114:115], v[50:51], v[128:129]
	v_pk_fma_f32 v[130:131], v[112:113], v[50:51], v[130:131]
	v_pk_fma_f32 v[132:133], v[110:111], v[50:51], v[132:133]
	v_pk_fma_f32 v[134:135], v[108:109], v[50:51], v[134:135]
	v_pk_fma_f32 v[136:137], v[106:107], v[50:51], v[136:137]
	v_pk_fma_f32 v[138:139], v[104:105], v[50:51], v[138:139]
	v_pk_fma_f32 v[140:141], v[102:103], v[50:51], v[140:141]
	v_pk_fma_f32 v[142:143], v[100:101], v[50:51], v[142:143]
	v_pk_fma_f32 v[144:145], v[98:99], v[50:51], v[144:145]
	v_pk_fma_f32 v[146:147], v[96:97], v[50:51], v[146:147]
	v_pk_fma_f32 v[148:149], v[94:95], v[50:51], v[148:149]
	v_pk_fma_f32 v[150:151], v[92:93], v[50:51], v[150:151]
	v_pk_fma_f32 v[152:153], v[90:91], v[50:51], v[152:153]
	v_pk_fma_f32 v[154:155], v[88:89], v[50:51], v[154:155]
	v_pk_fma_f32 v[156:157], v[86:87], v[50:51], v[156:157]
	v_pk_fma_f32 v[158:159], v[84:85], v[50:51], v[158:159]
	v_pk_fma_f32 v[160:161], v[82:83], v[50:51], v[160:161]
	v_pk_fma_f32 v[162:163], v[80:81], v[50:51], v[162:163]
	v_pk_fma_f32 v[164:165], v[78:79], v[50:51], v[164:165]
	v_pk_fma_f32 v[166:167], v[76:77], v[50:51], v[166:167]
	v_pk_fma_f32 v[168:169], v[74:75], v[50:51], v[168:169]
	v_pk_fma_f32 v[170:171], v[72:73], v[50:51], v[170:171]
	v_pk_fma_f32 v[172:173], v[70:71], v[50:51], v[172:173]
	v_pk_fma_f32 v[174:175], v[68:69], v[50:51], v[174:175]
	v_pk_fma_f32 v[176:177], v[66:67], v[50:51], v[176:177]
	s_waitcnt lgkmcnt(6)
; DEVI void conv_tile(const Params& p, unsigned char* smem, int ct) {
;     ...
;   float ya[32], yb[32];
; #pragma unroll
;   for (int tt = 0; tt < 32; ++tt) {
;     float y0 = bd0, y1 = bd1;
; #pragma unroll
;     for (int j = 0; j < 31; ++j) {
;       const unsigned uu = *(const unsigned*)(sU + (tt + j) * 512 + c);
;       y0 += w0[j] * __uint_as_float(uu << 16);
;       y1 += w1[j] * __uint_as_float(uu & 0xffff0000u);
;     }
;     ya[tt] = y0; yb[tt] = y1;
	v_lshlrev_b32_e32 v52, 16, v9
	v_and_b32_e32 v53, 0xffff0000, v9
	v_pk_fma_f32 v[128:129], v[116:117], v[52:53], v[128:129]
	v_pk_fma_f32 v[130:131], v[114:115], v[52:53], v[130:131]
	v_pk_fma_f32 v[132:133], v[112:113], v[52:53], v[132:133]
	v_pk_fma_f32 v[134:135], v[110:111], v[52:53], v[134:135]
	v_pk_fma_f32 v[136:137], v[108:109], v[52:53], v[136:137]
	v_pk_fma_f32 v[138:139], v[106:107], v[52:53], v[138:139]
	v_pk_fma_f32 v[140:141], v[104:105], v[52:53], v[140:141]
	v_pk_fma_f32 v[142:143], v[102:103], v[52:53], v[142:143]
	v_pk_fma_f32 v[144:145], v[100:101], v[52:53], v[144:145]
	v_pk_fma_f32 v[146:147], v[98:99], v[52:53], v[146:147]
	v_pk_fma_f32 v[148:149], v[96:97], v[52:53], v[148:149]
	v_pk_fma_f32 v[150:151], v[94:95], v[52:53], v[150:151]
	v_pk_fma_f32 v[152:153], v[92:93], v[52:53], v[152:153]
	v_pk_fma_f32 v[154:155], v[90:91], v[52:53], v[154:155]
	v_pk_fma_f32 v[156:157], v[88:89], v[52:53], v[156:157]
	v_pk_fma_f32 v[158:159], v[86:87], v[52:53], v[158:159]
	v_pk_fma_f32 v[160:161], v[84:85], v[52:53], v[160:161]
	v_pk_fma_f32 v[162:163], v[82:83], v[52:53], v[162:163]
	v_pk_fma_f32 v[164:165], v[80:81], v[52:53], v[164:165]
	v_pk_fma_f32 v[166:167], v[78:79], v[52:53], v[166:167]
	v_pk_fma_f32 v[168:169], v[76:77], v[52:53], v[168:169]
	v_pk_fma_f32 v[170:171], v[74:75], v[52:53], v[170:171]
	v_pk_fma_f32 v[172:173], v[72:73], v[52:53], v[172:173]
	v_pk_fma_f32 v[174:175], v[70:71], v[52:53], v[174:175]
	v_pk_fma_f32 v[176:177], v[68:69], v[52:53], v[176:177]
	v_pk_fma_f32 v[178:179], v[66:67], v[52:53], v[178:179]
	s_waitcnt lgkmcnt(5)
	v_lshlrev_b32_e32 v54, 16, v10
	v_and_b32_e32 v55, 0xffff0000, v10
	v_pk_fma_f32 v[128:129], v[118:119], v[54:55], v[128:129]
	v_pk_fma_f32 v[130:131], v[116:117], v[54:55], v[130:131]
	v_pk_fma_f32 v[132:133], v[114:115], v[54:55], v[132:133]
	v_pk_fma_f32 v[134:135], v[112:113], v[54:55], v[134:135]
	v_pk_fma_f32 v[136:137], v[110:111], v[54:55], v[136:137]
	v_pk_fma_f32 v[138:139], v[108:109], v[54:55], v[138:139]
	v_pk_fma_f32 v[140:141], v[106:107], v[54:55], v[140:141]
	v_pk_fma_f32 v[142:143], v[104:105], v[54:55], v[142:143]
	v_pk_fma_f32 v[144:145], v[102:103], v[54:55], v[144:145]
	v_pk_fma_f32 v[146:147], v[100:101], v[54:55], v[146:147]
	v_pk_fma_f32 v[148:149], v[98:99], v[54:55], v[148:149]
	v_pk_fma_f32 v[150:151], v[96:97], v[54:55], v[150:151]
	v_pk_fma_f32 v[152:153], v[94:95], v[54:55], v[152:153]
	v_pk_fma_f32 v[154:155], v[92:93], v[54:55], v[154:155]
	v_pk_fma_f32 v[156:157], v[90:91], v[54:55], v[156:157]
	v_pk_fma_f32 v[158:159], v[88:89], v[54:55], v[158:159]
	v_pk_fma_f32 v[160:161], v[86:87], v[54:55], v[160:161]
	v_pk_fma_f32 v[162:163], v[84:85], v[54:55], v[162:163]
	v_pk_fma_f32 v[164:165], v[82:83], v[54:55], v[164:165]
	v_pk_fma_f32 v[166:167], v[80:81], v[54:55], v[166:167]
	v_pk_fma_f32 v[168:169], v[78:79], v[54:55], v[168:169]
	v_pk_fma_f32 v[170:171], v[76:77], v[54:55], v[170:171]
	v_pk_fma_f32 v[172:173], v[74:75], v[54:55], v[172:173]
	v_pk_fma_f32 v[174:175], v[72:73], v[54:55], v[174:175]
	v_pk_fma_f32 v[176:177], v[70:71], v[54:55], v[176:177]
	v_pk_fma_f32 v[178:179], v[68:69], v[54:55], v[178:179]
	v_pk_fma_f32 v[180:181], v[66:67], v[54:55], v[180:181]
	s_waitcnt lgkmcnt(4)
	v_lshlrev_b32_e32 v56, 16, v11
	v_and_b32_e32 v57, 0xffff0000, v11
	v_pk_fma_f32 v[128:129], v[120:121], v[56:57], v[128:129]
	v_pk_fma_f32 v[130:131], v[118:119], v[56:57], v[130:131]
	v_pk_fma_f32 v[132:133], v[116:117], v[56:57], v[132:133]
	v_pk_fma_f32 v[134:135], v[114:115], v[56:57], v[134:135]
	v_pk_fma_f32 v[136:137], v[112:113], v[56:57], v[136:137]
	v_pk_fma_f32 v[138:139], v[110:111], v[56:57], v[138:139]
	v_pk_fma_f32 v[140:141], v[108:109], v[56:57], v[140:141]
	v_pk_fma_f32 v[142:143], v[106:107], v[56:57], v[142:143]
	v_pk_fma_f32 v[144:145], v[104:105], v[56:57], v[144:145]
	v_pk_fma_f32 v[146:147], v[102:103], v[56:57], v[146:147]
	v_pk_fma_f32 v[148:149], v[100:101], v[56:57], v[148:149]
	v_pk_fma_f32 v[150:151], v[98:99], v[56:57], v[150:151]
	v_pk_fma_f32 v[152:153], v[96:97], v[56:57], v[152:153]
	v_pk_fma_f32 v[154:155], v[94:95], v[56:57], v[154:155]
	v_pk_fma_f32 v[156:157], v[92:93], v[56:57], v[156:157]
	v_pk_fma_f32 v[158:159], v[90:91], v[56:57], v[158:159]
	v_pk_fma_f32 v[160:161], v[88:89], v[56:57], v[160:161]
	v_pk_fma_f32 v[162:163], v[86:87], v[56:57], v[162:163]
	v_pk_fma_f32 v[164:165], v[84:85], v[56:57], v[164:165]
	v_pk_fma_f32 v[166:167], v[82:83], v[56:57], v[166:167]
	v_pk_fma_f32 v[168:169], v[80:81], v[56:57], v[168:169]
	v_pk_fma_f32 v[170:171], v[78:79], v[56:57], v[170:171]
	v_pk_fma_f32 v[172:173], v[76:77], v[56:57], v[172:173]
	v_pk_fma_f32 v[174:175], v[74:75], v[56:57], v[174:175]
	v_pk_fma_f32 v[176:177], v[72:73], v[56:57], v[176:177]
	v_pk_fma_f32 v[178:179], v[70:71], v[56:57], v[178:179]
	v_pk_fma_f32 v[180:181], v[68:69], v[56:57], v[180:181]
	v_pk_fma_f32 v[182:183], v[66:67], v[56:57], v[182:183]
	s_waitcnt lgkmcnt(3)
; DEVI void conv_tile(const Params& p, unsigned char* smem, int ct) {
;     ...
;   float ya[32], yb[32];
; #pragma unroll
;   for (int tt = 0; tt < 32; ++tt) {
;     float y0 = bd0, y1 = bd1;
; #pragma unroll
;     for (int j = 0; j < 31; ++j) {
;       const unsigned uu = *(const unsigned*)(sU + (tt + j) * 512 + c);
;       y0 += w0[j] * __uint_as_float(uu << 16);
;       y1 += w1[j] * __uint_as_float(uu & 0xffff0000u);
;     }
;     ya[tt] = y0; yb[tt] = y1;
	v_lshlrev_b32_e32 v50, 16, v12
	v_and_b32_e32 v51, 0xffff0000, v12
	v_pk_fma_f32 v[128:129], v[122:123], v[50:51], v[128:129]
	v_pk_fma_f32 v[130:131], v[120:121], v[50:51], v[130:131]
	v_pk_fma_f32 v[132:133], v[118:119], v[50:51], v[132:133]
	v_pk_fma_f32 v[134:135], v[116:117], v[50:51], v[134:135]
	v_pk_fma_f32 v[136:137], v[114:115], v[50:51], v[136:137]
	v_pk_fma_f32 v[138:139], v[112:113], v[50:51], v[138:139]
	v_pk_fma_f32 v[140:141], v[110:111], v[50:51], v[140:141]
	v_pk_fma_f32 v[142:143], v[108:109], v[50:51], v[142:143]
	v_pk_fma_f32 v[144:145], v[106:107], v[50:51], v[144:145]
	v_pk_fma_f32 v[146:147], v[104:105], v[50:51], v[146:147]
	v_pk_fma_f32 v[148:149], v[102:103], v[50:51], v[148:149]
	v_pk_fma_f32 v[150:151], v[100:101], v[50:51], v[150:151]
	v_pk_fma_f32 v[152:153], v[98:99], v[50:51], v[152:153]
	v_pk_fma_f32 v[154:155], v[96:97], v[50:51], v[154:155]
	v_pk_fma_f32 v[156:157], v[94:95], v[50:51], v[156:157]
	v_pk_fma_f32 v[158:159], v[92:93], v[50:51], v[158:159]
	v_pk_fma_f32 v[160:161], v[90:91], v[50:51], v[160:161]
	v_pk_fma_f32 v[162:163], v[88:89], v[50:51], v[162:163]
	v_pk_fma_f32 v[164:165], v[86:87], v[50:51], v[164:165]
	v_pk_fma_f32 v[166:167], v[84:85], v[50:51], v[166:167]
	v_pk_fma_f32 v[168:169], v[82:83], v[50:51], v[168:169]
	v_pk_fma_f32 v[170:171], v[80:81], v[50:51], v[170:171]
	v_pk_fma_f32 v[172:173], v[78:79], v[50:51], v[172:173]
	v_pk_fma_f32 v[174:175], v[76:77], v[50:51], v[174:175]
	v_pk_fma_f32 v[176:177], v[74:75], v[50:51], v[176:177]
	v_pk_fma_f32 v[178:179], v[72:73], v[50:51], v[178:179]
	v_pk_fma_f32 v[180:181], v[70:71], v[50:51], v[180:181]
	v_pk_fma_f32 v[182:183], v[68:69], v[50:51], v[182:183]
	v_pk_fma_f32 v[184:185], v[66:67], v[50:51], v[184:185]
	s_waitcnt lgkmcnt(2)
	v_lshlrev_b32_e32 v52, 16, v13
	v_and_b32_e32 v53, 0xffff0000, v13
	v_pk_fma_f32 v[128:129], v[124:125], v[52:53], v[128:129]
	v_pk_fma_f32 v[130:131], v[122:123], v[52:53], v[130:131]
	v_pk_fma_f32 v[132:133], v[120:121], v[52:53], v[132:133]
	v_pk_fma_f32 v[134:135], v[118:119], v[52:53], v[134:135]
	v_pk_fma_f32 v[136:137], v[116:117], v[52:53], v[136:137]
	v_pk_fma_f32 v[138:139], v[114:115], v[52:53], v[138:139]
	v_pk_fma_f32 v[140:141], v[112:113], v[52:53], v[140:141]
	v_pk_fma_f32 v[142:143], v[110:111], v[52:53], v[142:143]
	v_pk_fma_f32 v[144:145], v[108:109], v[52:53], v[144:145]
	v_pk_fma_f32 v[146:147], v[106:107], v[52:53], v[146:147]
	v_pk_fma_f32 v[148:149], v[104:105], v[52:53], v[148:149]
	v_pk_fma_f32 v[150:151], v[102:103], v[52:53], v[150:151]
	v_pk_fma_f32 v[152:153], v[100:101], v[52:53], v[152:153]
	v_pk_fma_f32 v[154:155], v[98:99], v[52:53], v[154:155]
	v_pk_fma_f32 v[156:157], v[96:97], v[52:53], v[156:157]
	v_pk_fma_f32 v[158:159], v[94:95], v[52:53], v[158:159]
	v_pk_fma_f32 v[160:161], v[92:93], v[52:53], v[160:161]
	v_pk_fma_f32 v[162:163], v[90:91], v[52:53], v[162:163]
	v_pk_fma_f32 v[164:165], v[88:89], v[52:53], v[164:165]
	v_pk_fma_f32 v[166:167], v[86:87], v[52:53], v[166:167]
	v_pk_fma_f32 v[168:169], v[84:85], v[52:53], v[168:169]
	v_pk_fma_f32 v[170:171], v[82:83], v[52:53], v[170:171]
	v_pk_fma_f32 v[172:173], v[80:81], v[52:53], v[172:173]
	v_pk_fma_f32 v[174:175], v[78:79], v[52:53], v[174:175]
	v_pk_fma_f32 v[176:177], v[76:77], v[52:53], v[176:177]
	v_pk_fma_f32 v[178:179], v[74:75], v[52:53], v[178:179]
	v_pk_fma_f32 v[180:181], v[72:73], v[52:53], v[180:181]
	v_pk_fma_f32 v[182:183], v[70:71], v[52:53], v[182:183]
	v_pk_fma_f32 v[184:185], v[68:69], v[52:53], v[184:185]
	v_pk_fma_f32 v[186:187], v[66:67], v[52:53], v[186:187]
	s_waitcnt lgkmcnt(1)
	v_lshlrev_b32_e32 v54, 16, v14
	v_and_b32_e32 v55, 0xffff0000, v14
	v_pk_fma_f32 v[128:129], v[126:127], v[54:55], v[128:129]
	v_pk_fma_f32 v[130:131], v[124:125], v[54:55], v[130:131]
	v_pk_fma_f32 v[132:133], v[122:123], v[54:55], v[132:133]
	v_pk_fma_f32 v[134:135], v[120:121], v[54:55], v[134:135]
	v_pk_fma_f32 v[136:137], v[118:119], v[54:55], v[136:137]
	v_pk_fma_f32 v[138:139], v[116:117], v[54:55], v[138:139]
	v_pk_fma_f32 v[140:141], v[114:115], v[54:55], v[140:141]
	v_pk_fma_f32 v[142:143], v[112:113], v[54:55], v[142:143]
	v_pk_fma_f32 v[144:145], v[110:111], v[54:55], v[144:145]
	v_pk_fma_f32 v[146:147], v[108:109], v[54:55], v[146:147]
	v_pk_fma_f32 v[148:149], v[106:107], v[54:55], v[148:149]
	v_pk_fma_f32 v[150:151], v[104:105], v[54:55], v[150:151]
	v_pk_fma_f32 v[152:153], v[102:103], v[54:55], v[152:153]
	v_pk_fma_f32 v[154:155], v[100:101], v[54:55], v[154:155]
	v_pk_fma_f32 v[156:157], v[98:99], v[54:55], v[156:157]
	v_pk_fma_f32 v[158:159], v[96:97], v[54:55], v[158:159]
	v_pk_fma_f32 v[160:161], v[94:95], v[54:55], v[160:161]
	v_pk_fma_f32 v[162:163], v[92:93], v[54:55], v[162:163]
	v_pk_fma_f32 v[164:165], v[90:91], v[54:55], v[164:165]
	v_pk_fma_f32 v[166:167], v[88:89], v[54:55], v[166:167]
	v_pk_fma_f32 v[168:169], v[86:87], v[54:55], v[168:169]
	v_pk_fma_f32 v[170:171], v[84:85], v[54:55], v[170:171]
	v_pk_fma_f32 v[172:173], v[82:83], v[54:55], v[172:173]
	v_pk_fma_f32 v[174:175], v[80:81], v[54:55], v[174:175]
	v_pk_fma_f32 v[176:177], v[78:79], v[54:55], v[176:177]
	v_pk_fma_f32 v[178:179], v[76:77], v[54:55], v[178:179]
	v_pk_fma_f32 v[180:181], v[74:75], v[54:55], v[180:181]
	v_pk_fma_f32 v[182:183], v[72:73], v[54:55], v[182:183]
	v_pk_fma_f32 v[184:185], v[70:71], v[54:55], v[184:185]
	v_pk_fma_f32 v[186:187], v[68:69], v[54:55], v[186:187]
	v_pk_fma_f32 v[188:189], v[66:67], v[54:55], v[188:189]
	s_waitcnt lgkmcnt(0)
; DEVI void conv_tile(const Params& p, unsigned char* smem, int ct) {
;     ...
;   float ya[32], yb[32];
; #pragma unroll
;   for (int tt = 0; tt < 32; ++tt) {
;     float y0 = bd0, y1 = bd1;
; #pragma unroll
;     for (int j = 0; j < 31; ++j) {
;       const unsigned uu = *(const unsigned*)(sU + (tt + j) * 512 + c);
;       y0 += w0[j] * __uint_as_float(uu << 16);
;       y1 += w1[j] * __uint_as_float(uu & 0xffff0000u);
;     }
;     ya[tt] = y0; yb[tt] = y1;
	v_lshlrev_b32_e32 v56, 16, v15
	v_and_b32_e32 v57, 0xffff0000, v15
	v_pk_fma_f32 v[130:131], v[126:127], v[56:57], v[130:131]
	v_pk_fma_f32 v[132:133], v[124:125], v[56:57], v[132:133]
	v_pk_fma_f32 v[134:135], v[122:123], v[56:57], v[134:135]
	v_pk_fma_f32 v[136:137], v[120:121], v[56:57], v[136:137]
	v_pk_fma_f32 v[138:139], v[118:119], v[56:57], v[138:139]
	v_pk_fma_f32 v[140:141], v[116:117], v[56:57], v[140:141]
	v_pk_fma_f32 v[142:143], v[114:115], v[56:57], v[142:143]
	v_pk_fma_f32 v[144:145], v[112:113], v[56:57], v[144:145]
	v_pk_fma_f32 v[146:147], v[110:111], v[56:57], v[146:147]
	v_pk_fma_f32 v[148:149], v[108:109], v[56:57], v[148:149]
	v_pk_fma_f32 v[150:151], v[106:107], v[56:57], v[150:151]
	v_pk_fma_f32 v[152:153], v[104:105], v[56:57], v[152:153]
	v_pk_fma_f32 v[154:155], v[102:103], v[56:57], v[154:155]
	v_pk_fma_f32 v[156:157], v[100:101], v[56:57], v[156:157]
	v_pk_fma_f32 v[158:159], v[98:99], v[56:57], v[158:159]
	v_pk_fma_f32 v[160:161], v[96:97], v[56:57], v[160:161]
	v_pk_fma_f32 v[162:163], v[94:95], v[56:57], v[162:163]
	v_pk_fma_f32 v[164:165], v[92:93], v[56:57], v[164:165]
	v_pk_fma_f32 v[166:167], v[90:91], v[56:57], v[166:167]
	v_pk_fma_f32 v[168:169], v[88:89], v[56:57], v[168:169]
	v_pk_fma_f32 v[170:171], v[86:87], v[56:57], v[170:171]
	v_pk_fma_f32 v[172:173], v[84:85], v[56:57], v[172:173]
	v_pk_fma_f32 v[174:175], v[82:83], v[56:57], v[174:175]
	v_pk_fma_f32 v[176:177], v[80:81], v[56:57], v[176:177]
	v_pk_fma_f32 v[178:179], v[78:79], v[56:57], v[178:179]
	v_pk_fma_f32 v[180:181], v[76:77], v[56:57], v[180:181]
	v_pk_fma_f32 v[182:183], v[74:75], v[56:57], v[182:183]
	v_pk_fma_f32 v[184:185], v[72:73], v[56:57], v[184:185]
	v_pk_fma_f32 v[186:187], v[70:71], v[56:57], v[186:187]
	v_pk_fma_f32 v[188:189], v[68:69], v[56:57], v[188:189]
	v_pk_fma_f32 v[190:191], v[66:67], v[56:57], v[190:191]
	ds_read_b32 v0, v209 offset:32768
	ds_read_b32 v1, v209 offset:33792
	ds_read_b32 v2, v209 offset:34816
	ds_read_b32 v3, v209 offset:35840
	ds_read_b32 v4, v209 offset:36864
	ds_read_b32 v5, v209 offset:37888
	ds_read_b32 v6, v209 offset:38912
	ds_read_b32 v7, v209 offset:39936
	ds_read_b32 v8, v209 offset:40960
	ds_read_b32 v9, v209 offset:41984
	ds_read_b32 v10, v209 offset:43008
	ds_read_b32 v11, v209 offset:44032
	ds_read_b32 v12, v209 offset:45056
	ds_read_b32 v13, v209 offset:46080
	ds_read_b32 v14, v209 offset:47104
	ds_read_b32 v15, v209 offset:48128
	s_waitcnt lgkmcnt(15)
	v_lshlrev_b32_e32 v50, 16, v0
	v_and_b32_e32 v51, 0xffff0000, v0
	v_pk_fma_f32 v[132:133], v[126:127], v[50:51], v[132:133]
	v_pk_fma_f32 v[134:135], v[124:125], v[50:51], v[134:135]
	v_pk_fma_f32 v[136:137], v[122:123], v[50:51], v[136:137]
	v_pk_fma_f32 v[138:139], v[120:121], v[50:51], v[138:139]
	v_pk_fma_f32 v[140:141], v[118:119], v[50:51], v[140:141]
	v_pk_fma_f32 v[142:143], v[116:117], v[50:51], v[142:143]
	v_pk_fma_f32 v[144:145], v[114:115], v[50:51], v[144:145]
	v_pk_fma_f32 v[146:147], v[112:113], v[50:51], v[146:147]
	v_pk_fma_f32 v[148:149], v[110:111], v[50:51], v[148:149]
	v_pk_fma_f32 v[150:151], v[108:109], v[50:51], v[150:151]
	v_pk_fma_f32 v[152:153], v[106:107], v[50:51], v[152:153]
	v_pk_fma_f32 v[154:155], v[104:105], v[50:51], v[154:155]
	v_pk_fma_f32 v[156:157], v[102:103], v[50:51], v[156:157]
	v_pk_fma_f32 v[158:159], v[100:101], v[50:51], v[158:159]
	v_pk_fma_f32 v[160:161], v[98:99], v[50:51], v[160:161]
	v_pk_fma_f32 v[162:163], v[96:97], v[50:51], v[162:163]
	v_pk_fma_f32 v[164:165], v[94:95], v[50:51], v[164:165]
	v_pk_fma_f32 v[166:167], v[92:93], v[50:51], v[166:167]
	v_pk_fma_f32 v[168:169], v[90:91], v[50:51], v[168:169]
	v_pk_fma_f32 v[170:171], v[88:89], v[50:51], v[170:171]
	v_pk_fma_f32 v[172:173], v[86:87], v[50:51], v[172:173]
	v_pk_fma_f32 v[174:175], v[84:85], v[50:51], v[174:175]
	v_pk_fma_f32 v[176:177], v[82:83], v[50:51], v[176:177]
	v_pk_fma_f32 v[178:179], v[80:81], v[50:51], v[178:179]
	v_pk_fma_f32 v[180:181], v[78:79], v[50:51], v[180:181]
	v_pk_fma_f32 v[182:183], v[76:77], v[50:51], v[182:183]
	v_pk_fma_f32 v[184:185], v[74:75], v[50:51], v[184:185]
	v_pk_fma_f32 v[186:187], v[72:73], v[50:51], v[186:187]
	v_pk_fma_f32 v[188:189], v[70:71], v[50:51], v[188:189]
	v_pk_fma_f32 v[190:191], v[68:69], v[50:51], v[190:191]
	s_waitcnt lgkmcnt(14)
	v_lshlrev_b32_e32 v52, 16, v1
	v_and_b32_e32 v53, 0xffff0000, v1
	v_pk_fma_f32 v[134:135], v[126:127], v[52:53], v[134:135]
	v_pk_fma_f32 v[136:137], v[124:125], v[52:53], v[136:137]
	v_pk_fma_f32 v[138:139], v[122:123], v[52:53], v[138:139]
	v_pk_fma_f32 v[140:141], v[120:121], v[52:53], v[140:141]
	v_pk_fma_f32 v[142:143], v[118:119], v[52:53], v[142:143]
	v_pk_fma_f32 v[144:145], v[116:117], v[52:53], v[144:145]
	v_pk_fma_f32 v[146:147], v[114:115], v[52:53], v[146:147]
	v_pk_fma_f32 v[148:149], v[112:113], v[52:53], v[148:149]
	v_pk_fma_f32 v[150:151], v[110:111], v[52:53], v[150:151]
	v_pk_fma_f32 v[152:153], v[108:109], v[52:53], v[152:153]
	v_pk_fma_f32 v[154:155], v[106:107], v[52:53], v[154:155]
	v_pk_fma_f32 v[156:157], v[104:105], v[52:53], v[156:157]
	v_pk_fma_f32 v[158:159], v[102:103], v[52:53], v[158:159]
	v_pk_fma_f32 v[160:161], v[100:101], v[52:53], v[160:161]
	v_pk_fma_f32 v[162:163], v[98:99], v[52:53], v[162:163]
	v_pk_fma_f32 v[164:165], v[96:97], v[52:53], v[164:165]
	v_pk_fma_f32 v[166:167], v[94:95], v[52:53], v[166:167]
	v_pk_fma_f32 v[168:169], v[92:93], v[52:53], v[168:169]
	v_pk_fma_f32 v[170:171], v[90:91], v[52:53], v[170:171]
	v_pk_fma_f32 v[172:173], v[88:89], v[52:53], v[172:173]
	v_pk_fma_f32 v[174:175], v[86:87], v[52:53], v[174:175]
	v_pk_fma_f32 v[176:177], v[84:85], v[52:53], v[176:177]
	v_pk_fma_f32 v[178:179], v[82:83], v[52:53], v[178:179]
	v_pk_fma_f32 v[180:181], v[80:81], v[52:53], v[180:181]
	v_pk_fma_f32 v[182:183], v[78:79], v[52:53], v[182:183]
	v_pk_fma_f32 v[184:185], v[76:77], v[52:53], v[184:185]
	v_pk_fma_f32 v[186:187], v[74:75], v[52:53], v[186:187]
	v_pk_fma_f32 v[188:189], v[72:73], v[52:53], v[188:189]
	v_pk_fma_f32 v[190:191], v[70:71], v[52:53], v[190:191]
	s_waitcnt lgkmcnt(13)
; DEVI void conv_tile(const Params& p, unsigned char* smem, int ct) {
;     ...
;   for (int tt = 0; tt < 32; ++tt) {
;     float y0 = bd0, y1 = bd1;
; #pragma unroll
;     for (int j = 0; j < 31; ++j) {
;       const unsigned uu = *(const unsigned*)(sU + (tt + j) * 512 + c);
;       y0 += w0[j] * __uint_as_float(uu << 16);
;       y1 += w1[j] * __uint_as_float(uu & 0xffff0000u);
;     }
;     ya[tt] = y0; yb[tt] = y1;
	v_lshlrev_b32_e32 v54, 16, v2
	v_and_b32_e32 v55, 0xffff0000, v2
	v_pk_fma_f32 v[136:137], v[126:127], v[54:55], v[136:137]
	v_pk_fma_f32 v[138:139], v[124:125], v[54:55], v[138:139]
	v_pk_fma_f32 v[140:141], v[122:123], v[54:55], v[140:141]
	v_pk_fma_f32 v[142:143], v[120:121], v[54:55], v[142:143]
	v_pk_fma_f32 v[144:145], v[118:119], v[54:55], v[144:145]
	v_pk_fma_f32 v[146:147], v[116:117], v[54:55], v[146:147]
	v_pk_fma_f32 v[148:149], v[114:115], v[54:55], v[148:149]
	v_pk_fma_f32 v[150:151], v[112:113], v[54:55], v[150:151]
	v_pk_fma_f32 v[152:153], v[110:111], v[54:55], v[152:153]
	v_pk_fma_f32 v[154:155], v[108:109], v[54:55], v[154:155]
	v_pk_fma_f32 v[156:157], v[106:107], v[54:55], v[156:157]
	v_pk_fma_f32 v[158:159], v[104:105], v[54:55], v[158:159]
	v_pk_fma_f32 v[160:161], v[102:103], v[54:55], v[160:161]
	v_pk_fma_f32 v[162:163], v[100:101], v[54:55], v[162:163]
	v_pk_fma_f32 v[164:165], v[98:99], v[54:55], v[164:165]
	v_pk_fma_f32 v[166:167], v[96:97], v[54:55], v[166:167]
	v_pk_fma_f32 v[168:169], v[94:95], v[54:55], v[168:169]
	v_pk_fma_f32 v[170:171], v[92:93], v[54:55], v[170:171]
	v_pk_fma_f32 v[172:173], v[90:91], v[54:55], v[172:173]
	v_pk_fma_f32 v[174:175], v[88:89], v[54:55], v[174:175]
	v_pk_fma_f32 v[176:177], v[86:87], v[54:55], v[176:177]
	v_pk_fma_f32 v[178:179], v[84:85], v[54:55], v[178:179]
	v_pk_fma_f32 v[180:181], v[82:83], v[54:55], v[180:181]
	v_pk_fma_f32 v[182:183], v[80:81], v[54:55], v[182:183]
	v_pk_fma_f32 v[184:185], v[78:79], v[54:55], v[184:185]
	v_pk_fma_f32 v[186:187], v[76:77], v[54:55], v[186:187]
	v_pk_fma_f32 v[188:189], v[74:75], v[54:55], v[188:189]
	v_pk_fma_f32 v[190:191], v[72:73], v[54:55], v[190:191]
	s_waitcnt lgkmcnt(12)
	v_lshlrev_b32_e32 v56, 16, v3
	v_and_b32_e32 v57, 0xffff0000, v3
	v_pk_fma_f32 v[138:139], v[126:127], v[56:57], v[138:139]
	v_pk_fma_f32 v[140:141], v[124:125], v[56:57], v[140:141]
	v_pk_fma_f32 v[142:143], v[122:123], v[56:57], v[142:143]
	v_pk_fma_f32 v[144:145], v[120:121], v[56:57], v[144:145]
	v_pk_fma_f32 v[146:147], v[118:119], v[56:57], v[146:147]
	v_pk_fma_f32 v[148:149], v[116:117], v[56:57], v[148:149]
	v_pk_fma_f32 v[150:151], v[114:115], v[56:57], v[150:151]
	v_pk_fma_f32 v[152:153], v[112:113], v[56:57], v[152:153]
	v_pk_fma_f32 v[154:155], v[110:111], v[56:57], v[154:155]
	v_pk_fma_f32 v[156:157], v[108:109], v[56:57], v[156:157]
	v_pk_fma_f32 v[158:159], v[106:107], v[56:57], v[158:159]
	v_pk_fma_f32 v[160:161], v[104:105], v[56:57], v[160:161]
	v_pk_fma_f32 v[162:163], v[102:103], v[56:57], v[162:163]
	v_pk_fma_f32 v[164:165], v[100:101], v[56:57], v[164:165]
	v_pk_fma_f32 v[166:167], v[98:99], v[56:57], v[166:167]
	v_pk_fma_f32 v[168:169], v[96:97], v[56:57], v[168:169]
	v_pk_fma_f32 v[170:171], v[94:95], v[56:57], v[170:171]
	v_pk_fma_f32 v[172:173], v[92:93], v[56:57], v[172:173]
	v_pk_fma_f32 v[174:175], v[90:91], v[56:57], v[174:175]
	v_pk_fma_f32 v[176:177], v[88:89], v[56:57], v[176:177]
	v_pk_fma_f32 v[178:179], v[86:87], v[56:57], v[178:179]
	v_pk_fma_f32 v[180:181], v[84:85], v[56:57], v[180:181]
	v_pk_fma_f32 v[182:183], v[82:83], v[56:57], v[182:183]
	v_pk_fma_f32 v[184:185], v[80:81], v[56:57], v[184:185]
	v_pk_fma_f32 v[186:187], v[78:79], v[56:57], v[186:187]
	v_pk_fma_f32 v[188:189], v[76:77], v[56:57], v[188:189]
	v_pk_fma_f32 v[190:191], v[74:75], v[56:57], v[190:191]
	s_waitcnt lgkmcnt(11)
	v_lshlrev_b32_e32 v50, 16, v4
	v_and_b32_e32 v51, 0xffff0000, v4
	v_pk_fma_f32 v[140:141], v[126:127], v[50:51], v[140:141]
	v_pk_fma_f32 v[142:143], v[124:125], v[50:51], v[142:143]
	v_pk_fma_f32 v[144:145], v[122:123], v[50:51], v[144:145]
	v_pk_fma_f32 v[146:147], v[120:121], v[50:51], v[146:147]
	v_pk_fma_f32 v[148:149], v[118:119], v[50:51], v[148:149]
	v_pk_fma_f32 v[150:151], v[116:117], v[50:51], v[150:151]
	v_pk_fma_f32 v[152:153], v[114:115], v[50:51], v[152:153]
	v_pk_fma_f32 v[154:155], v[112:113], v[50:51], v[154:155]
	v_pk_fma_f32 v[156:157], v[110:111], v[50:51], v[156:157]
	v_pk_fma_f32 v[158:159], v[108:109], v[50:51], v[158:159]
	v_pk_fma_f32 v[160:161], v[106:107], v[50:51], v[160:161]
	v_pk_fma_f32 v[162:163], v[104:105], v[50:51], v[162:163]
	v_pk_fma_f32 v[164:165], v[102:103], v[50:51], v[164:165]
	v_pk_fma_f32 v[166:167], v[100:101], v[50:51], v[166:167]
	v_pk_fma_f32 v[168:169], v[98:99], v[50:51], v[168:169]
	v_pk_fma_f32 v[170:171], v[96:97], v[50:51], v[170:171]
	v_pk_fma_f32 v[172:173], v[94:95], v[50:51], v[172:173]
	v_pk_fma_f32 v[174:175], v[92:93], v[50:51], v[174:175]
	v_pk_fma_f32 v[176:177], v[90:91], v[50:51], v[176:177]
	v_pk_fma_f32 v[178:179], v[88:89], v[50:51], v[178:179]
	v_pk_fma_f32 v[180:181], v[86:87], v[50:51], v[180:181]
	v_pk_fma_f32 v[182:183], v[84:85], v[50:51], v[182:183]
	v_pk_fma_f32 v[184:185], v[82:83], v[50:51], v[184:185]
	v_pk_fma_f32 v[186:187], v[80:81], v[50:51], v[186:187]
	v_pk_fma_f32 v[188:189], v[78:79], v[50:51], v[188:189]
	v_pk_fma_f32 v[190:191], v[76:77], v[50:51], v[190:191]
	s_waitcnt lgkmcnt(10)
; DEVI void conv_tile(const Params& p, unsigned char* smem, int ct) {
;     ...
;   for (int tt = 0; tt < 32; ++tt) {
;     float y0 = bd0, y1 = bd1;
; #pragma unroll
;     for (int j = 0; j < 31; ++j) {
;       const unsigned uu = *(const unsigned*)(sU + (tt + j) * 512 + c);
;       y0 += w0[j] * __uint_as_float(uu << 16);
;       y1 += w1[j] * __uint_as_float(uu & 0xffff0000u);
;     }
;     ya[tt] = y0; yb[tt] = y1;
	v_lshlrev_b32_e32 v52, 16, v5
	v_and_b32_e32 v53, 0xffff0000, v5
	v_pk_fma_f32 v[142:143], v[126:127], v[52:53], v[142:143]
	v_pk_fma_f32 v[144:145], v[124:125], v[52:53], v[144:145]
	v_pk_fma_f32 v[146:147], v[122:123], v[52:53], v[146:147]
	v_pk_fma_f32 v[148:149], v[120:121], v[52:53], v[148:149]
	v_pk_fma_f32 v[150:151], v[118:119], v[52:53], v[150:151]
	v_pk_fma_f32 v[152:153], v[116:117], v[52:53], v[152:153]
	v_pk_fma_f32 v[154:155], v[114:115], v[52:53], v[154:155]
	v_pk_fma_f32 v[156:157], v[112:113], v[52:53], v[156:157]
	v_pk_fma_f32 v[158:159], v[110:111], v[52:53], v[158:159]
	v_pk_fma_f32 v[160:161], v[108:109], v[52:53], v[160:161]
	v_pk_fma_f32 v[162:163], v[106:107], v[52:53], v[162:163]
	v_pk_fma_f32 v[164:165], v[104:105], v[52:53], v[164:165]
	v_pk_fma_f32 v[166:167], v[102:103], v[52:53], v[166:167]
	v_pk_fma_f32 v[168:169], v[100:101], v[52:53], v[168:169]
	v_pk_fma_f32 v[170:171], v[98:99], v[52:53], v[170:171]
	v_pk_fma_f32 v[172:173], v[96:97], v[52:53], v[172:173]
	v_pk_fma_f32 v[174:175], v[94:95], v[52:53], v[174:175]
	v_pk_fma_f32 v[176:177], v[92:93], v[52:53], v[176:177]
	v_pk_fma_f32 v[178:179], v[90:91], v[52:53], v[178:179]
	v_pk_fma_f32 v[180:181], v[88:89], v[52:53], v[180:181]
	v_pk_fma_f32 v[182:183], v[86:87], v[52:53], v[182:183]
	v_pk_fma_f32 v[184:185], v[84:85], v[52:53], v[184:185]
	v_pk_fma_f32 v[186:187], v[82:83], v[52:53], v[186:187]
	v_pk_fma_f32 v[188:189], v[80:81], v[52:53], v[188:189]
	v_pk_fma_f32 v[190:191], v[78:79], v[52:53], v[190:191]
	s_waitcnt lgkmcnt(9)
	v_lshlrev_b32_e32 v54, 16, v6
	v_and_b32_e32 v55, 0xffff0000, v6
	v_pk_fma_f32 v[144:145], v[126:127], v[54:55], v[144:145]
	v_pk_fma_f32 v[146:147], v[124:125], v[54:55], v[146:147]
	v_pk_fma_f32 v[148:149], v[122:123], v[54:55], v[148:149]
	v_pk_fma_f32 v[150:151], v[120:121], v[54:55], v[150:151]
	v_pk_fma_f32 v[152:153], v[118:119], v[54:55], v[152:153]
	v_pk_fma_f32 v[154:155], v[116:117], v[54:55], v[154:155]
	v_pk_fma_f32 v[156:157], v[114:115], v[54:55], v[156:157]
	v_pk_fma_f32 v[158:159], v[112:113], v[54:55], v[158:159]
	v_pk_fma_f32 v[160:161], v[110:111], v[54:55], v[160:161]
	v_pk_fma_f32 v[162:163], v[108:109], v[54:55], v[162:163]
	v_pk_fma_f32 v[164:165], v[106:107], v[54:55], v[164:165]
	v_pk_fma_f32 v[166:167], v[104:105], v[54:55], v[166:167]
	v_pk_fma_f32 v[168:169], v[102:103], v[54:55], v[168:169]
	v_pk_fma_f32 v[170:171], v[100:101], v[54:55], v[170:171]
	v_pk_fma_f32 v[172:173], v[98:99], v[54:55], v[172:173]
	v_pk_fma_f32 v[174:175], v[96:97], v[54:55], v[174:175]
	v_pk_fma_f32 v[176:177], v[94:95], v[54:55], v[176:177]
	v_pk_fma_f32 v[178:179], v[92:93], v[54:55], v[178:179]
	v_pk_fma_f32 v[180:181], v[90:91], v[54:55], v[180:181]
	v_pk_fma_f32 v[182:183], v[88:89], v[54:55], v[182:183]
	v_pk_fma_f32 v[184:185], v[86:87], v[54:55], v[184:185]
	v_pk_fma_f32 v[186:187], v[84:85], v[54:55], v[186:187]
	v_pk_fma_f32 v[188:189], v[82:83], v[54:55], v[188:189]
	v_pk_fma_f32 v[190:191], v[80:81], v[54:55], v[190:191]
	s_waitcnt lgkmcnt(8)
	v_lshlrev_b32_e32 v56, 16, v7
	v_and_b32_e32 v57, 0xffff0000, v7
	v_pk_fma_f32 v[146:147], v[126:127], v[56:57], v[146:147]
	v_pk_fma_f32 v[148:149], v[124:125], v[56:57], v[148:149]
	v_pk_fma_f32 v[150:151], v[122:123], v[56:57], v[150:151]
	v_pk_fma_f32 v[152:153], v[120:121], v[56:57], v[152:153]
	v_pk_fma_f32 v[154:155], v[118:119], v[56:57], v[154:155]
	v_pk_fma_f32 v[156:157], v[116:117], v[56:57], v[156:157]
	v_pk_fma_f32 v[158:159], v[114:115], v[56:57], v[158:159]
	v_pk_fma_f32 v[160:161], v[112:113], v[56:57], v[160:161]
	v_pk_fma_f32 v[162:163], v[110:111], v[56:57], v[162:163]
	v_pk_fma_f32 v[164:165], v[108:109], v[56:57], v[164:165]
	v_pk_fma_f32 v[166:167], v[106:107], v[56:57], v[166:167]
	v_pk_fma_f32 v[168:169], v[104:105], v[56:57], v[168:169]
	v_pk_fma_f32 v[170:171], v[102:103], v[56:57], v[170:171]
	v_pk_fma_f32 v[172:173], v[100:101], v[56:57], v[172:173]
	v_pk_fma_f32 v[174:175], v[98:99], v[56:57], v[174:175]
	v_pk_fma_f32 v[176:177], v[96:97], v[56:57], v[176:177]
	v_pk_fma_f32 v[178:179], v[94:95], v[56:57], v[178:179]
	v_pk_fma_f32 v[180:181], v[92:93], v[56:57], v[180:181]
	v_pk_fma_f32 v[182:183], v[90:91], v[56:57], v[182:183]
	v_pk_fma_f32 v[184:185], v[88:89], v[56:57], v[184:185]
	v_pk_fma_f32 v[186:187], v[86:87], v[56:57], v[186:187]
	v_pk_fma_f32 v[188:189], v[84:85], v[56:57], v[188:189]
	v_pk_fma_f32 v[190:191], v[82:83], v[56:57], v[190:191]
	s_waitcnt lgkmcnt(7)
	v_lshlrev_b32_e32 v50, 16, v8
	v_and_b32_e32 v51, 0xffff0000, v8
	v_pk_fma_f32 v[148:149], v[126:127], v[50:51], v[148:149]
	v_pk_fma_f32 v[150:151], v[124:125], v[50:51], v[150:151]
	v_pk_fma_f32 v[152:153], v[122:123], v[50:51], v[152:153]
	v_pk_fma_f32 v[154:155], v[120:121], v[50:51], v[154:155]
	v_pk_fma_f32 v[156:157], v[118:119], v[50:51], v[156:157]
	v_pk_fma_f32 v[158:159], v[116:117], v[50:51], v[158:159]
	v_pk_fma_f32 v[160:161], v[114:115], v[50:51], v[160:161]
	v_pk_fma_f32 v[162:163], v[112:113], v[50:51], v[162:163]
	v_pk_fma_f32 v[164:165], v[110:111], v[50:51], v[164:165]
	v_pk_fma_f32 v[166:167], v[108:109], v[50:51], v[166:167]
	v_pk_fma_f32 v[168:169], v[106:107], v[50:51], v[168:169]
	v_pk_fma_f32 v[170:171], v[104:105], v[50:51], v[170:171]
	v_pk_fma_f32 v[172:173], v[102:103], v[50:51], v[172:173]
	v_pk_fma_f32 v[174:175], v[100:101], v[50:51], v[174:175]
	v_pk_fma_f32 v[176:177], v[98:99], v[50:51], v[176:177]
	v_pk_fma_f32 v[178:179], v[96:97], v[50:51], v[178:179]
	v_pk_fma_f32 v[180:181], v[94:95], v[50:51], v[180:181]
	v_pk_fma_f32 v[182:183], v[92:93], v[50:51], v[182:183]
	v_pk_fma_f32 v[184:185], v[90:91], v[50:51], v[184:185]
	v_pk_fma_f32 v[186:187], v[88:89], v[50:51], v[186:187]
	v_pk_fma_f32 v[188:189], v[86:87], v[50:51], v[188:189]
	v_pk_fma_f32 v[190:191], v[84:85], v[50:51], v[190:191]
	s_waitcnt lgkmcnt(6)
; DEVI void conv_tile(const Params& p, unsigned char* smem, int ct) {
;     ...
;   for (int tt = 0; tt < 32; ++tt) {
;     float y0 = bd0, y1 = bd1;
; #pragma unroll
;     for (int j = 0; j < 31; ++j) {
;       const unsigned uu = *(const unsigned*)(sU + (tt + j) * 512 + c);
;       y0 += w0[j] * __uint_as_float(uu << 16);
;       y1 += w1[j] * __uint_as_float(uu & 0xffff0000u);
;     }
;     ya[tt] = y0; yb[tt] = y1;
	v_lshlrev_b32_e32 v52, 16, v9
	v_and_b32_e32 v53, 0xffff0000, v9
	v_pk_fma_f32 v[150:151], v[126:127], v[52:53], v[150:151]
	v_pk_fma_f32 v[152:153], v[124:125], v[52:53], v[152:153]
	v_pk_fma_f32 v[154:155], v[122:123], v[52:53], v[154:155]
	v_pk_fma_f32 v[156:157], v[120:121], v[52:53], v[156:157]
	v_pk_fma_f32 v[158:159], v[118:119], v[52:53], v[158:159]
	v_pk_fma_f32 v[160:161], v[116:117], v[52:53], v[160:161]
	v_pk_fma_f32 v[162:163], v[114:115], v[52:53], v[162:163]
	v_pk_fma_f32 v[164:165], v[112:113], v[52:53], v[164:165]
	v_pk_fma_f32 v[166:167], v[110:111], v[52:53], v[166:167]
	v_pk_fma_f32 v[168:169], v[108:109], v[52:53], v[168:169]
	v_pk_fma_f32 v[170:171], v[106:107], v[52:53], v[170:171]
	v_pk_fma_f32 v[172:173], v[104:105], v[52:53], v[172:173]
	v_pk_fma_f32 v[174:175], v[102:103], v[52:53], v[174:175]
	v_pk_fma_f32 v[176:177], v[100:101], v[52:53], v[176:177]
	v_pk_fma_f32 v[178:179], v[98:99], v[52:53], v[178:179]
	v_pk_fma_f32 v[180:181], v[96:97], v[52:53], v[180:181]
	v_pk_fma_f32 v[182:183], v[94:95], v[52:53], v[182:183]
	v_pk_fma_f32 v[184:185], v[92:93], v[52:53], v[184:185]
	v_pk_fma_f32 v[186:187], v[90:91], v[52:53], v[186:187]
	v_pk_fma_f32 v[188:189], v[88:89], v[52:53], v[188:189]
	v_pk_fma_f32 v[190:191], v[86:87], v[52:53], v[190:191]
	s_waitcnt lgkmcnt(5)
	v_lshlrev_b32_e32 v54, 16, v10
	v_and_b32_e32 v55, 0xffff0000, v10
	v_pk_fma_f32 v[152:153], v[126:127], v[54:55], v[152:153]
	v_pk_fma_f32 v[154:155], v[124:125], v[54:55], v[154:155]
	v_pk_fma_f32 v[156:157], v[122:123], v[54:55], v[156:157]
	v_pk_fma_f32 v[158:159], v[120:121], v[54:55], v[158:159]
	v_pk_fma_f32 v[160:161], v[118:119], v[54:55], v[160:161]
	v_pk_fma_f32 v[162:163], v[116:117], v[54:55], v[162:163]
	v_pk_fma_f32 v[164:165], v[114:115], v[54:55], v[164:165]
	v_pk_fma_f32 v[166:167], v[112:113], v[54:55], v[166:167]
	v_pk_fma_f32 v[168:169], v[110:111], v[54:55], v[168:169]
	v_pk_fma_f32 v[170:171], v[108:109], v[54:55], v[170:171]
	v_pk_fma_f32 v[172:173], v[106:107], v[54:55], v[172:173]
	v_pk_fma_f32 v[174:175], v[104:105], v[54:55], v[174:175]
	v_pk_fma_f32 v[176:177], v[102:103], v[54:55], v[176:177]
	v_pk_fma_f32 v[178:179], v[100:101], v[54:55], v[178:179]
	v_pk_fma_f32 v[180:181], v[98:99], v[54:55], v[180:181]
	v_pk_fma_f32 v[182:183], v[96:97], v[54:55], v[182:183]
	v_pk_fma_f32 v[184:185], v[94:95], v[54:55], v[184:185]
	v_pk_fma_f32 v[186:187], v[92:93], v[54:55], v[186:187]
	v_pk_fma_f32 v[188:189], v[90:91], v[54:55], v[188:189]
	v_pk_fma_f32 v[190:191], v[88:89], v[54:55], v[190:191]
	s_waitcnt lgkmcnt(4)
	v_lshlrev_b32_e32 v56, 16, v11
	v_and_b32_e32 v57, 0xffff0000, v11
	v_pk_fma_f32 v[154:155], v[126:127], v[56:57], v[154:155]
	v_pk_fma_f32 v[156:157], v[124:125], v[56:57], v[156:157]
	v_pk_fma_f32 v[158:159], v[122:123], v[56:57], v[158:159]
	v_pk_fma_f32 v[160:161], v[120:121], v[56:57], v[160:161]
	v_pk_fma_f32 v[162:163], v[118:119], v[56:57], v[162:163]
	v_pk_fma_f32 v[164:165], v[116:117], v[56:57], v[164:165]
	v_pk_fma_f32 v[166:167], v[114:115], v[56:57], v[166:167]
	v_pk_fma_f32 v[168:169], v[112:113], v[56:57], v[168:169]
	v_pk_fma_f32 v[170:171], v[110:111], v[56:57], v[170:171]
	v_pk_fma_f32 v[172:173], v[108:109], v[56:57], v[172:173]
	v_pk_fma_f32 v[174:175], v[106:107], v[56:57], v[174:175]
	v_pk_fma_f32 v[176:177], v[104:105], v[56:57], v[176:177]
	v_pk_fma_f32 v[178:179], v[102:103], v[56:57], v[178:179]
	v_pk_fma_f32 v[180:181], v[100:101], v[56:57], v[180:181]
	v_pk_fma_f32 v[182:183], v[98:99], v[56:57], v[182:183]
	v_pk_fma_f32 v[184:185], v[96:97], v[56:57], v[184:185]
	v_pk_fma_f32 v[186:187], v[94:95], v[56:57], v[186:187]
	v_pk_fma_f32 v[188:189], v[92:93], v[56:57], v[188:189]
	v_pk_fma_f32 v[190:191], v[90:91], v[56:57], v[190:191]
	s_waitcnt lgkmcnt(3)
	v_lshlrev_b32_e32 v50, 16, v12
	v_and_b32_e32 v51, 0xffff0000, v12
	v_pk_fma_f32 v[156:157], v[126:127], v[50:51], v[156:157]
	v_pk_fma_f32 v[158:159], v[124:125], v[50:51], v[158:159]
	v_pk_fma_f32 v[160:161], v[122:123], v[50:51], v[160:161]
	v_pk_fma_f32 v[162:163], v[120:121], v[50:51], v[162:163]
	v_pk_fma_f32 v[164:165], v[118:119], v[50:51], v[164:165]
	v_pk_fma_f32 v[166:167], v[116:117], v[50:51], v[166:167]
	v_pk_fma_f32 v[168:169], v[114:115], v[50:51], v[168:169]
	v_pk_fma_f32 v[170:171], v[112:113], v[50:51], v[170:171]
	v_pk_fma_f32 v[172:173], v[110:111], v[50:51], v[172:173]
	v_pk_fma_f32 v[174:175], v[108:109], v[50:51], v[174:175]
	v_pk_fma_f32 v[176:177], v[106:107], v[50:51], v[176:177]
	v_pk_fma_f32 v[178:179], v[104:105], v[50:51], v[178:179]
	v_pk_fma_f32 v[180:181], v[102:103], v[50:51], v[180:181]
	v_pk_fma_f32 v[182:183], v[100:101], v[50:51], v[182:183]
	v_pk_fma_f32 v[184:185], v[98:99], v[50:51], v[184:185]
	v_pk_fma_f32 v[186:187], v[96:97], v[50:51], v[186:187]
	v_pk_fma_f32 v[188:189], v[94:95], v[50:51], v[188:189]
	v_pk_fma_f32 v[190:191], v[92:93], v[50:51], v[190:191]
	s_waitcnt lgkmcnt(2)
	v_lshlrev_b32_e32 v52, 16, v13
	v_and_b32_e32 v53, 0xffff0000, v13
	v_pk_fma_f32 v[158:159], v[126:127], v[52:53], v[158:159]
	v_pk_fma_f32 v[160:161], v[124:125], v[52:53], v[160:161]
	v_pk_fma_f32 v[162:163], v[122:123], v[52:53], v[162:163]
	v_pk_fma_f32 v[164:165], v[120:121], v[52:53], v[164:165]
	v_pk_fma_f32 v[166:167], v[118:119], v[52:53], v[166:167]
	v_pk_fma_f32 v[168:169], v[116:117], v[52:53], v[168:169]
	v_pk_fma_f32 v[170:171], v[114:115], v[52:53], v[170:171]
	v_pk_fma_f32 v[172:173], v[112:113], v[52:53], v[172:173]
	v_pk_fma_f32 v[174:175], v[110:111], v[52:53], v[174:175]
	v_pk_fma_f32 v[176:177], v[108:109], v[52:53], v[176:177]
	v_pk_fma_f32 v[178:179], v[106:107], v[52:53], v[178:179]
	v_pk_fma_f32 v[180:181], v[104:105], v[52:53], v[180:181]
	v_pk_fma_f32 v[182:183], v[102:103], v[52:53], v[182:183]
	v_pk_fma_f32 v[184:185], v[100:101], v[52:53], v[184:185]
	v_pk_fma_f32 v[186:187], v[98:99], v[52:53], v[186:187]
	v_pk_fma_f32 v[188:189], v[96:97], v[52:53], v[188:189]
	v_pk_fma_f32 v[190:191], v[94:95], v[52:53], v[190:191]
	s_waitcnt lgkmcnt(1)
; DEVI void conv_tile(const Params& p, unsigned char* smem, int ct) {
;     ...
;   for (int tt = 0; tt < 32; ++tt) {
;     float y0 = bd0, y1 = bd1;
; #pragma unroll
;     for (int j = 0; j < 31; ++j) {
;       const unsigned uu = *(const unsigned*)(sU + (tt + j) * 512 + c);
;       y0 += w0[j] * __uint_as_float(uu << 16);
;       y1 += w1[j] * __uint_as_float(uu & 0xffff0000u);
;     }
;     ya[tt] = y0; yb[tt] = y1;
	v_lshlrev_b32_e32 v54, 16, v14
	v_and_b32_e32 v55, 0xffff0000, v14
	v_pk_fma_f32 v[160:161], v[126:127], v[54:55], v[160:161]
	v_pk_fma_f32 v[162:163], v[124:125], v[54:55], v[162:163]
	v_pk_fma_f32 v[164:165], v[122:123], v[54:55], v[164:165]
	v_pk_fma_f32 v[166:167], v[120:121], v[54:55], v[166:167]
	v_pk_fma_f32 v[168:169], v[118:119], v[54:55], v[168:169]
	v_pk_fma_f32 v[170:171], v[116:117], v[54:55], v[170:171]
	v_pk_fma_f32 v[172:173], v[114:115], v[54:55], v[172:173]
	v_pk_fma_f32 v[174:175], v[112:113], v[54:55], v[174:175]
	v_pk_fma_f32 v[176:177], v[110:111], v[54:55], v[176:177]
	v_pk_fma_f32 v[178:179], v[108:109], v[54:55], v[178:179]
	v_pk_fma_f32 v[180:181], v[106:107], v[54:55], v[180:181]
	v_pk_fma_f32 v[182:183], v[104:105], v[54:55], v[182:183]
	v_pk_fma_f32 v[184:185], v[102:103], v[54:55], v[184:185]
	v_pk_fma_f32 v[186:187], v[100:101], v[54:55], v[186:187]
	v_pk_fma_f32 v[188:189], v[98:99], v[54:55], v[188:189]
	v_pk_fma_f32 v[190:191], v[96:97], v[54:55], v[190:191]
	s_waitcnt lgkmcnt(0)
	v_lshlrev_b32_e32 v56, 16, v15
	v_and_b32_e32 v57, 0xffff0000, v15
	v_pk_fma_f32 v[162:163], v[126:127], v[56:57], v[162:163]
	v_pk_fma_f32 v[164:165], v[124:125], v[56:57], v[164:165]
	v_pk_fma_f32 v[166:167], v[122:123], v[56:57], v[166:167]
	v_pk_fma_f32 v[168:169], v[120:121], v[56:57], v[168:169]
	v_pk_fma_f32 v[170:171], v[118:119], v[56:57], v[170:171]
	v_pk_fma_f32 v[172:173], v[116:117], v[56:57], v[172:173]
	v_pk_fma_f32 v[174:175], v[114:115], v[56:57], v[174:175]
	v_pk_fma_f32 v[176:177], v[112:113], v[56:57], v[176:177]
	v_pk_fma_f32 v[178:179], v[110:111], v[56:57], v[178:179]
	v_pk_fma_f32 v[180:181], v[108:109], v[56:57], v[180:181]
	v_pk_fma_f32 v[182:183], v[106:107], v[56:57], v[182:183]
	v_pk_fma_f32 v[184:185], v[104:105], v[56:57], v[184:185]
	v_pk_fma_f32 v[186:187], v[102:103], v[56:57], v[186:187]
	v_pk_fma_f32 v[188:189], v[100:101], v[56:57], v[188:189]
	v_pk_fma_f32 v[190:191], v[98:99], v[56:57], v[190:191]
	ds_read_b32 v0, v209 offset:49152
	ds_read_b32 v1, v209 offset:50176
	ds_read_b32 v2, v209 offset:51200
	ds_read_b32 v3, v209 offset:52224
	ds_read_b32 v4, v209 offset:53248
	ds_read_b32 v5, v209 offset:54272
	ds_read_b32 v6, v209 offset:55296
	ds_read_b32 v7, v209 offset:56320
	ds_read_b32 v8, v209 offset:57344
	ds_read_b32 v9, v209 offset:58368
	ds_read_b32 v10, v209 offset:59392
	ds_read_b32 v11, v209 offset:60416
	ds_read_b32 v12, v209 offset:61440
	ds_read_b32 v13, v209 offset:62464
	s_waitcnt lgkmcnt(13)
	v_lshlrev_b32_e32 v50, 16, v0
	v_and_b32_e32 v51, 0xffff0000, v0
	v_pk_fma_f32 v[164:165], v[126:127], v[50:51], v[164:165]
	v_pk_fma_f32 v[166:167], v[124:125], v[50:51], v[166:167]
	v_pk_fma_f32 v[168:169], v[122:123], v[50:51], v[168:169]
	v_pk_fma_f32 v[170:171], v[120:121], v[50:51], v[170:171]
	v_pk_fma_f32 v[172:173], v[118:119], v[50:51], v[172:173]
	v_pk_fma_f32 v[174:175], v[116:117], v[50:51], v[174:175]
	v_pk_fma_f32 v[176:177], v[114:115], v[50:51], v[176:177]
	v_pk_fma_f32 v[178:179], v[112:113], v[50:51], v[178:179]
	v_pk_fma_f32 v[180:181], v[110:111], v[50:51], v[180:181]
	v_pk_fma_f32 v[182:183], v[108:109], v[50:51], v[182:183]
	v_pk_fma_f32 v[184:185], v[106:107], v[50:51], v[184:185]
	v_pk_fma_f32 v[186:187], v[104:105], v[50:51], v[186:187]
	v_pk_fma_f32 v[188:189], v[102:103], v[50:51], v[188:189]
	v_pk_fma_f32 v[190:191], v[100:101], v[50:51], v[190:191]
	s_waitcnt lgkmcnt(12)
	v_lshlrev_b32_e32 v52, 16, v1
	v_and_b32_e32 v53, 0xffff0000, v1
	v_pk_fma_f32 v[166:167], v[126:127], v[52:53], v[166:167]
	v_pk_fma_f32 v[168:169], v[124:125], v[52:53], v[168:169]
	v_pk_fma_f32 v[170:171], v[122:123], v[52:53], v[170:171]
	v_pk_fma_f32 v[172:173], v[120:121], v[52:53], v[172:173]
	v_pk_fma_f32 v[174:175], v[118:119], v[52:53], v[174:175]
	v_pk_fma_f32 v[176:177], v[116:117], v[52:53], v[176:177]
	v_pk_fma_f32 v[178:179], v[114:115], v[52:53], v[178:179]
	v_pk_fma_f32 v[180:181], v[112:113], v[52:53], v[180:181]
	v_pk_fma_f32 v[182:183], v[110:111], v[52:53], v[182:183]
	v_pk_fma_f32 v[184:185], v[108:109], v[52:53], v[184:185]
	v_pk_fma_f32 v[186:187], v[106:107], v[52:53], v[186:187]
	v_pk_fma_f32 v[188:189], v[104:105], v[52:53], v[188:189]
	v_pk_fma_f32 v[190:191], v[102:103], v[52:53], v[190:191]
	s_waitcnt lgkmcnt(11)
	v_lshlrev_b32_e32 v54, 16, v2
	v_and_b32_e32 v55, 0xffff0000, v2
	v_pk_fma_f32 v[168:169], v[126:127], v[54:55], v[168:169]
	v_pk_fma_f32 v[170:171], v[124:125], v[54:55], v[170:171]
	v_pk_fma_f32 v[172:173], v[122:123], v[54:55], v[172:173]
	v_pk_fma_f32 v[174:175], v[120:121], v[54:55], v[174:175]
	v_pk_fma_f32 v[176:177], v[118:119], v[54:55], v[176:177]
	v_pk_fma_f32 v[178:179], v[116:117], v[54:55], v[178:179]
	v_pk_fma_f32 v[180:181], v[114:115], v[54:55], v[180:181]
	v_pk_fma_f32 v[182:183], v[112:113], v[54:55], v[182:183]
	v_pk_fma_f32 v[184:185], v[110:111], v[54:55], v[184:185]
	v_pk_fma_f32 v[186:187], v[108:109], v[54:55], v[186:187]
	v_pk_fma_f32 v[188:189], v[106:107], v[54:55], v[188:189]
	v_pk_fma_f32 v[190:191], v[104:105], v[54:55], v[190:191]
	s_waitcnt lgkmcnt(10)
	v_lshlrev_b32_e32 v56, 16, v3
	v_and_b32_e32 v57, 0xffff0000, v3
	v_pk_fma_f32 v[170:171], v[126:127], v[56:57], v[170:171]
	v_pk_fma_f32 v[172:173], v[124:125], v[56:57], v[172:173]
	v_pk_fma_f32 v[174:175], v[122:123], v[56:57], v[174:175]
	v_pk_fma_f32 v[176:177], v[120:121], v[56:57], v[176:177]
	v_pk_fma_f32 v[178:179], v[118:119], v[56:57], v[178:179]
	v_pk_fma_f32 v[180:181], v[116:117], v[56:57], v[180:181]
	v_pk_fma_f32 v[182:183], v[114:115], v[56:57], v[182:183]
	v_pk_fma_f32 v[184:185], v[112:113], v[56:57], v[184:185]
	v_pk_fma_f32 v[186:187], v[110:111], v[56:57], v[186:187]
	v_pk_fma_f32 v[188:189], v[108:109], v[56:57], v[188:189]
	v_pk_fma_f32 v[190:191], v[106:107], v[56:57], v[190:191]
	s_waitcnt lgkmcnt(9)
; DEVI void conv_tile(const Params& p, unsigned char* smem, int ct) {
;     ...
;   for (int tt = 0; tt < 32; ++tt) {
;     float y0 = bd0, y1 = bd1;
; #pragma unroll
;     for (int j = 0; j < 31; ++j) {
;       const unsigned uu = *(const unsigned*)(sU + (tt + j) * 512 + c);
;       y0 += w0[j] * __uint_as_float(uu << 16);
;       y1 += w1[j] * __uint_as_float(uu & 0xffff0000u);
;     }
;     ya[tt] = y0; yb[tt] = y1;
;     float s = y0 + y1, q = y0 * y0 + y1 * y1;
	v_lshlrev_b32_e32 v50, 16, v4
	v_and_b32_e32 v51, 0xffff0000, v4
	v_pk_fma_f32 v[172:173], v[126:127], v[50:51], v[172:173]
	v_pk_fma_f32 v[174:175], v[124:125], v[50:51], v[174:175]
	v_pk_fma_f32 v[176:177], v[122:123], v[50:51], v[176:177]
	v_pk_fma_f32 v[178:179], v[120:121], v[50:51], v[178:179]
	v_pk_fma_f32 v[180:181], v[118:119], v[50:51], v[180:181]
	v_pk_fma_f32 v[182:183], v[116:117], v[50:51], v[182:183]
	v_pk_fma_f32 v[184:185], v[114:115], v[50:51], v[184:185]
	v_pk_fma_f32 v[186:187], v[112:113], v[50:51], v[186:187]
	v_pk_fma_f32 v[188:189], v[110:111], v[50:51], v[188:189]
	v_pk_fma_f32 v[190:191], v[108:109], v[50:51], v[190:191]
	s_waitcnt lgkmcnt(8)
	v_lshlrev_b32_e32 v52, 16, v5
	v_and_b32_e32 v53, 0xffff0000, v5
	v_pk_fma_f32 v[174:175], v[126:127], v[52:53], v[174:175]
	v_pk_fma_f32 v[176:177], v[124:125], v[52:53], v[176:177]
	v_pk_fma_f32 v[178:179], v[122:123], v[52:53], v[178:179]
	v_pk_fma_f32 v[180:181], v[120:121], v[52:53], v[180:181]
	v_pk_fma_f32 v[182:183], v[118:119], v[52:53], v[182:183]
	v_pk_fma_f32 v[184:185], v[116:117], v[52:53], v[184:185]
	v_pk_fma_f32 v[186:187], v[114:115], v[52:53], v[186:187]
	v_pk_fma_f32 v[188:189], v[112:113], v[52:53], v[188:189]
	v_pk_fma_f32 v[190:191], v[110:111], v[52:53], v[190:191]
	s_waitcnt lgkmcnt(7)
	v_lshlrev_b32_e32 v54, 16, v6
	v_and_b32_e32 v55, 0xffff0000, v6
	v_pk_fma_f32 v[176:177], v[126:127], v[54:55], v[176:177]
	v_pk_fma_f32 v[178:179], v[124:125], v[54:55], v[178:179]
	v_pk_fma_f32 v[180:181], v[122:123], v[54:55], v[180:181]
	v_pk_fma_f32 v[182:183], v[120:121], v[54:55], v[182:183]
	v_pk_fma_f32 v[184:185], v[118:119], v[54:55], v[184:185]
	v_pk_fma_f32 v[186:187], v[116:117], v[54:55], v[186:187]
	v_pk_fma_f32 v[188:189], v[114:115], v[54:55], v[188:189]
	v_pk_fma_f32 v[190:191], v[112:113], v[54:55], v[190:191]
	s_waitcnt lgkmcnt(6)
	v_lshlrev_b32_e32 v56, 16, v7
	v_and_b32_e32 v57, 0xffff0000, v7
	v_pk_fma_f32 v[178:179], v[126:127], v[56:57], v[178:179]
	v_pk_fma_f32 v[180:181], v[124:125], v[56:57], v[180:181]
	v_pk_fma_f32 v[182:183], v[122:123], v[56:57], v[182:183]
	v_pk_fma_f32 v[184:185], v[120:121], v[56:57], v[184:185]
	v_pk_fma_f32 v[186:187], v[118:119], v[56:57], v[186:187]
	v_pk_fma_f32 v[188:189], v[116:117], v[56:57], v[188:189]
	v_pk_fma_f32 v[190:191], v[114:115], v[56:57], v[190:191]
	s_waitcnt lgkmcnt(5)
	v_lshlrev_b32_e32 v50, 16, v8
	v_and_b32_e32 v51, 0xffff0000, v8
	v_pk_fma_f32 v[180:181], v[126:127], v[50:51], v[180:181]
	v_pk_fma_f32 v[182:183], v[124:125], v[50:51], v[182:183]
	v_pk_fma_f32 v[184:185], v[122:123], v[50:51], v[184:185]
	v_pk_fma_f32 v[186:187], v[120:121], v[50:51], v[186:187]
	v_pk_fma_f32 v[188:189], v[118:119], v[50:51], v[188:189]
	v_pk_fma_f32 v[190:191], v[116:117], v[50:51], v[190:191]
	s_waitcnt lgkmcnt(4)
	v_lshlrev_b32_e32 v52, 16, v9
	v_and_b32_e32 v53, 0xffff0000, v9
	v_pk_fma_f32 v[182:183], v[126:127], v[52:53], v[182:183]
	v_pk_fma_f32 v[184:185], v[124:125], v[52:53], v[184:185]
	v_pk_fma_f32 v[186:187], v[122:123], v[52:53], v[186:187]
	v_pk_fma_f32 v[188:189], v[120:121], v[52:53], v[188:189]
	v_pk_fma_f32 v[190:191], v[118:119], v[52:53], v[190:191]
	s_waitcnt lgkmcnt(3)
	v_lshlrev_b32_e32 v54, 16, v10
	v_and_b32_e32 v55, 0xffff0000, v10
	v_pk_fma_f32 v[184:185], v[126:127], v[54:55], v[184:185]
	v_pk_fma_f32 v[186:187], v[124:125], v[54:55], v[186:187]
	v_pk_fma_f32 v[188:189], v[122:123], v[54:55], v[188:189]
	v_pk_fma_f32 v[190:191], v[120:121], v[54:55], v[190:191]
	s_waitcnt lgkmcnt(2)
	v_lshlrev_b32_e32 v56, 16, v11
	v_and_b32_e32 v57, 0xffff0000, v11
	v_pk_fma_f32 v[186:187], v[126:127], v[56:57], v[186:187]
	v_pk_fma_f32 v[188:189], v[124:125], v[56:57], v[188:189]
	v_pk_fma_f32 v[190:191], v[122:123], v[56:57], v[190:191]
	s_waitcnt lgkmcnt(1)
	v_lshlrev_b32_e32 v50, 16, v12
	v_and_b32_e32 v51, 0xffff0000, v12
	v_pk_fma_f32 v[188:189], v[126:127], v[50:51], v[188:189]
	v_pk_fma_f32 v[190:191], v[124:125], v[50:51], v[190:191]
	s_waitcnt lgkmcnt(0)
	v_lshlrev_b32_e32 v52, 16, v13
	v_and_b32_e32 v53, 0xffff0000, v13
	v_pk_fma_f32 v[190:191], v[126:127], v[52:53], v[190:191]
	v_add_f32_e32 v66, v128, v129
	v_mul_f32_e32 v98, v128, v128
	v_fmac_f32_e32 v98, v129, v129
	v_add_f32_e32 v67, v130, v131
	v_mul_f32_e32 v99, v130, v130
	v_fmac_f32_e32 v99, v131, v131
	v_add_f32_e32 v68, v132, v133
	v_mul_f32_e32 v100, v132, v132
	v_fmac_f32_e32 v100, v133, v133
	v_add_f32_e32 v69, v134, v135
	v_mul_f32_e32 v101, v134, v134
	v_fmac_f32_e32 v101, v135, v135
	v_add_f32_e32 v70, v136, v137
	v_mul_f32_e32 v102, v136, v136
	v_fmac_f32_e32 v102, v137, v137
	v_add_f32_e32 v71, v138, v139
	v_mul_f32_e32 v103, v138, v138
	v_fmac_f32_e32 v103, v139, v139
	v_add_f32_e32 v72, v140, v141
	v_mul_f32_e32 v104, v140, v140
	v_fmac_f32_e32 v104, v141, v141
	v_add_f32_e32 v73, v142, v143
	v_mul_f32_e32 v105, v142, v142
	v_fmac_f32_e32 v105, v143, v143
	v_add_f32_e32 v74, v144, v145
	v_mul_f32_e32 v106, v144, v144
	v_fmac_f32_e32 v106, v145, v145
	v_add_f32_e32 v75, v146, v147
	v_mul_f32_e32 v107, v146, v146
	v_fmac_f32_e32 v107, v147, v147
	v_add_f32_e32 v76, v148, v149
	v_mul_f32_e32 v108, v148, v148
	v_fmac_f32_e32 v108, v149, v149
	v_add_f32_e32 v77, v150, v151
	v_mul_f32_e32 v109, v150, v150
	v_fmac_f32_e32 v109, v151, v151
	v_add_f32_e32 v78, v152, v153
	v_mul_f32_e32 v110, v152, v152
	v_fmac_f32_e32 v110, v153, v153
	v_add_f32_e32 v79, v154, v155
	v_mul_f32_e32 v111, v154, v154
	v_fmac_f32_e32 v111, v155, v155
	v_add_f32_e32 v80, v156, v157
	v_mul_f32_e32 v112, v156, v156
	v_fmac_f32_e32 v112, v157, v157
	v_add_f32_e32 v81, v158, v159
	v_mul_f32_e32 v113, v158, v158
	v_fmac_f32_e32 v113, v159, v159
; DEVI void conv_tile(const Params& p, unsigned char* smem, int ct) {
;     ...
;     float s = y0 + y1, q = y0 * y0 + y1 * y1;
;     s = wave_sum(s); q = wave_sum(q);
;     if (lane == 0) sRed[tt * 4 + w] = make_float2(s, q);
	v_add_f32_e32 v82, v160, v161
	v_mul_f32_e32 v114, v160, v160
	v_fmac_f32_e32 v114, v161, v161
	v_add_f32_e32 v83, v162, v163
	v_mul_f32_e32 v115, v162, v162
	v_fmac_f32_e32 v115, v163, v163
	v_add_f32_e32 v84, v164, v165
	v_mul_f32_e32 v116, v164, v164
	v_fmac_f32_e32 v116, v165, v165
	v_add_f32_e32 v85, v166, v167
	v_mul_f32_e32 v117, v166, v166
	v_fmac_f32_e32 v117, v167, v167
	v_add_f32_e32 v86, v168, v169
	v_mul_f32_e32 v118, v168, v168
	v_fmac_f32_e32 v118, v169, v169
	v_add_f32_e32 v87, v170, v171
	v_mul_f32_e32 v119, v170, v170
	v_fmac_f32_e32 v119, v171, v171
	v_add_f32_e32 v88, v172, v173
	v_mul_f32_e32 v120, v172, v172
	v_fmac_f32_e32 v120, v173, v173
	v_add_f32_e32 v89, v174, v175
	v_mul_f32_e32 v121, v174, v174
	v_fmac_f32_e32 v121, v175, v175
	v_add_f32_e32 v90, v176, v177
	v_mul_f32_e32 v122, v176, v176
	v_fmac_f32_e32 v122, v177, v177
	v_add_f32_e32 v91, v178, v179
	v_mul_f32_e32 v123, v178, v178
	v_fmac_f32_e32 v123, v179, v179
	v_add_f32_e32 v92, v180, v181
	v_mul_f32_e32 v124, v180, v180
	v_fmac_f32_e32 v124, v181, v181
	v_add_f32_e32 v93, v182, v183
	v_mul_f32_e32 v125, v182, v182
	v_fmac_f32_e32 v125, v183, v183
	v_add_f32_e32 v94, v184, v185
	v_mul_f32_e32 v126, v184, v184
	v_fmac_f32_e32 v126, v185, v185
	v_add_f32_e32 v95, v186, v187
	v_mul_f32_e32 v127, v186, v186
	v_fmac_f32_e32 v127, v187, v187
	v_add_f32_e32 v96, v188, v189
	v_mul_f32_e32 v0, v188, v188
	v_fmac_f32_e32 v0, v189, v189
	v_add_f32_e32 v97, v190, v191
	v_mul_f32_e32 v1, v190, v190
	v_fmac_f32_e32 v1, v191, v191
	s_nop 1
	v_permlane32_swap_b32_e32 v66, v98
	v_permlane32_swap_b32_e32 v67, v99
	v_permlane32_swap_b32_e32 v68, v100
	v_permlane32_swap_b32_e32 v69, v101
	v_permlane32_swap_b32_e32 v70, v102
	v_permlane32_swap_b32_e32 v71, v103
	v_permlane32_swap_b32_e32 v72, v104
	v_permlane32_swap_b32_e32 v73, v105
	v_permlane32_swap_b32_e32 v74, v106
	v_permlane32_swap_b32_e32 v75, v107
	v_permlane32_swap_b32_e32 v76, v108
	v_permlane32_swap_b32_e32 v77, v109
	v_permlane32_swap_b32_e32 v78, v110
	v_permlane32_swap_b32_e32 v79, v111
	v_permlane32_swap_b32_e32 v80, v112
	v_permlane32_swap_b32_e32 v81, v113
	v_permlane32_swap_b32_e32 v82, v114
	v_permlane32_swap_b32_e32 v83, v115
	v_permlane32_swap_b32_e32 v84, v116
	v_permlane32_swap_b32_e32 v85, v117
	v_permlane32_swap_b32_e32 v86, v118
	v_permlane32_swap_b32_e32 v87, v119
	v_permlane32_swap_b32_e32 v88, v120
	v_permlane32_swap_b32_e32 v89, v121
	v_permlane32_swap_b32_e32 v90, v122
	v_permlane32_swap_b32_e32 v91, v123
	v_permlane32_swap_b32_e32 v92, v124
	v_permlane32_swap_b32_e32 v93, v125
	v_permlane32_swap_b32_e32 v94, v126
	v_permlane32_swap_b32_e32 v95, v127
	v_permlane32_swap_b32_e32 v96, v0
	v_permlane32_swap_b32_e32 v97, v1
	v_add_f32_e32 v66, v66, v98
	v_add_f32_e32 v67, v67, v99
	v_add_f32_e32 v68, v68, v100
	v_add_f32_e32 v69, v69, v101
	v_add_f32_e32 v70, v70, v102
	v_add_f32_e32 v71, v71, v103
	v_add_f32_e32 v72, v72, v104
	v_add_f32_e32 v73, v73, v105
	v_add_f32_e32 v74, v74, v106
	v_add_f32_e32 v75, v75, v107
	v_add_f32_e32 v76, v76, v108
	v_add_f32_e32 v77, v77, v109
	v_add_f32_e32 v78, v78, v110
	v_add_f32_e32 v79, v79, v111
	v_add_f32_e32 v80, v80, v112
	v_add_f32_e32 v81, v81, v113
	v_add_f32_e32 v82, v82, v114
	v_add_f32_e32 v83, v83, v115
	v_add_f32_e32 v84, v84, v116
	v_add_f32_e32 v85, v85, v117
	v_add_f32_e32 v86, v86, v118
	v_add_f32_e32 v87, v87, v119
	v_add_f32_e32 v88, v88, v120
	v_add_f32_e32 v89, v89, v121
	v_add_f32_e32 v90, v90, v122
	v_add_f32_e32 v91, v91, v123
	v_add_f32_e32 v92, v92, v124
	v_add_f32_e32 v93, v93, v125
	v_add_f32_e32 v94, v94, v126
	v_add_f32_e32 v95, v95, v127
	v_add_f32_e32 v96, v96, v0
	v_add_f32_e32 v97, v97, v1
	s_mov_b32 s80, 0xffff0000
	s_mov_b32 s81, 0xffff0000
	v_cndmask_b32_e64 v32, v82, v66, s[80:81]
	v_cndmask_b32_e64 v66, v66, v82, s[80:81]
	v_cndmask_b32_e64 v33, v83, v67, s[80:81]
	v_cndmask_b32_e64 v67, v67, v83, s[80:81]
	v_cndmask_b32_e64 v34, v84, v68, s[80:81]
	v_cndmask_b32_e64 v68, v68, v84, s[80:81]
	v_cndmask_b32_e64 v35, v85, v69, s[80:81]
	v_cndmask_b32_e64 v69, v69, v85, s[80:81]
	v_cndmask_b32_e64 v36, v86, v70, s[80:81]
	v_cndmask_b32_e64 v70, v70, v86, s[80:81]
	v_cndmask_b32_e64 v37, v87, v71, s[80:81]
	v_cndmask_b32_e64 v71, v71, v87, s[80:81]
	v_cndmask_b32_e64 v38, v88, v72, s[80:81]
	v_cndmask_b32_e64 v72, v72, v88, s[80:81]
	v_cndmask_b32_e64 v39, v89, v73, s[80:81]
	v_cndmask_b32_e64 v73, v73, v89, s[80:81]
	v_cndmask_b32_e64 v40, v90, v74, s[80:81]
	v_cndmask_b32_e64 v74, v74, v90, s[80:81]
	v_cndmask_b32_e64 v41, v91, v75, s[80:81]
	v_cndmask_b32_e64 v75, v75, v91, s[80:81]
	v_cndmask_b32_e64 v42, v92, v76, s[80:81]
	v_cndmask_b32_e64 v76, v76, v92, s[80:81]
	v_cndmask_b32_e64 v43, v93, v77, s[80:81]
	v_cndmask_b32_e64 v77, v77, v93, s[80:81]
	v_cndmask_b32_e64 v44, v94, v78, s[80:81]
	v_cndmask_b32_e64 v78, v78, v94, s[80:81]
	v_cndmask_b32_e64 v45, v95, v79, s[80:81]
	v_cndmask_b32_e64 v79, v79, v95, s[80:81]
	v_cndmask_b32_e64 v46, v96, v80, s[80:81]
	v_cndmask_b32_e64 v80, v80, v96, s[80:81]
	v_cndmask_b32_e64 v47, v97, v81, s[80:81]
	v_cndmask_b32_e64 v81, v81, v97, s[80:81]
	ds_bpermute_b32 v32, v213, v32
	ds_bpermute_b32 v33, v213, v33
	ds_bpermute_b32 v34, v213, v34
	ds_bpermute_b32 v35, v213, v35
	ds_bpermute_b32 v36, v213, v36
	ds_bpermute_b32 v37, v213, v37
	ds_bpermute_b32 v38, v213, v38
	ds_bpermute_b32 v39, v213, v39
	ds_bpermute_b32 v40, v213, v40
	ds_bpermute_b32 v41, v213, v41
	ds_bpermute_b32 v42, v213, v42
	ds_bpermute_b32 v43, v213, v43
	ds_bpermute_b32 v44, v213, v44
	ds_bpermute_b32 v45, v213, v45
	ds_bpermute_b32 v46, v213, v46
	ds_bpermute_b32 v47, v213, v47
	s_waitcnt lgkmcnt(0)
; DEVI unsigned pack2(float a, float b) { return (unsigned)f2bf(a) | ((unsigned)f2bf(b) << 16); }
; DEVI float sigmoidf_(float x) { return __builtin_amdgcn_rcpf(1.f + __expf(-x)); }
; DEVI void conv_tile(const Params& p, unsigned char* smem, int ct) {
;     ...
;     s = wave_sum(s); q = wave_sum(q);
;     if (lane == 0) sRed[tt * 4 + w] = make_float2(s, q);
;   }
;   __syncthreads();
;   const float g0 = p.ln_g[c], g1 = p.ln_g[c + 1], lb0 = p.ln_b[c], lb1 = p.ln_b[c + 1];
; #pragma unroll
;   for (int tt = 0; tt < 32; ++tt) {
;     const float y0 = ya[tt], y1 = yb[tt];
;     const float2 r0 = sRed[tt * 4 + 0], r1 = sRed[tt * 4 + 1], r2 = sRed[tt * 4 + 2], r3 = sRed[tt * 4 + 3];
;     const float S = r0.x + r1.x + r2.x + r3.x, Q = r0.y + r1.y + r2.y + r3.y;
;     const float mu = S * (1.f / 512.f);
;     const float var = fmaxf(Q * (1.f / 512.f) - mu * mu, 0.f);
;     const float rstd = rsqrtf(var + 1e-6f);
;     const float z0 = (y0 - mu) * rstd * g0 + lb0, z1 = (y1 - mu) * rstd * g1 + lb1;
;     const float o0 = z0 * sigmoidf_(z0), o1 = z1 * sigmoidf_(z1);
;     *(unsigned*)(p.mix + ((size_t)b * T + t0 + tt) * LDA + c) = pack2(o0, o1);
	v_add_f32_e32 v66, v32, v66
	v_add_f32_e32 v67, v33, v67
	v_add_f32_e32 v68, v34, v68
	v_add_f32_e32 v69, v35, v69
	v_add_f32_e32 v70, v36, v70
	v_add_f32_e32 v71, v37, v71
	v_add_f32_e32 v72, v38, v72
	v_add_f32_e32 v73, v39, v73
	v_add_f32_e32 v74, v40, v74
	v_add_f32_e32 v75, v41, v75
	v_add_f32_e32 v76, v42, v76
	v_add_f32_e32 v77, v43, v77
	v_add_f32_e32 v78, v44, v78
	v_add_f32_e32 v79, v45, v79
	v_add_f32_e32 v80, v46, v80
	v_add_f32_e32 v81, v47, v81
	s_mov_b32 s80, 0xff00ff00
	s_mov_b32 s81, 0xff00ff00
	v_cndmask_b32_e64 v32, v74, v66, s[80:81]
	v_cndmask_b32_e64 v66, v66, v74, s[80:81]
	v_cndmask_b32_e64 v33, v75, v67, s[80:81]
	v_cndmask_b32_e64 v67, v67, v75, s[80:81]
	v_cndmask_b32_e64 v34, v76, v68, s[80:81]
	v_cndmask_b32_e64 v68, v68, v76, s[80:81]
	v_cndmask_b32_e64 v35, v77, v69, s[80:81]
	v_cndmask_b32_e64 v69, v69, v77, s[80:81]
	v_cndmask_b32_e64 v36, v78, v70, s[80:81]
	v_cndmask_b32_e64 v70, v70, v78, s[80:81]
	v_cndmask_b32_e64 v37, v79, v71, s[80:81]
	v_cndmask_b32_e64 v71, v71, v79, s[80:81]
	v_cndmask_b32_e64 v38, v80, v72, s[80:81]
	v_cndmask_b32_e64 v72, v72, v80, s[80:81]
	v_cndmask_b32_e64 v39, v81, v73, s[80:81]
	v_cndmask_b32_e64 v73, v73, v81, s[80:81]
	s_nop 1
	v_add_f32_dpp v66, v32, v66 row_ror:8 row_mask:0xf bank_mask:0xf
	v_add_f32_dpp v67, v33, v67 row_ror:8 row_mask:0xf bank_mask:0xf
	v_add_f32_dpp v68, v34, v68 row_ror:8 row_mask:0xf bank_mask:0xf
	v_add_f32_dpp v69, v35, v69 row_ror:8 row_mask:0xf bank_mask:0xf
	v_add_f32_dpp v70, v36, v70 row_ror:8 row_mask:0xf bank_mask:0xf
	v_add_f32_dpp v71, v37, v71 row_ror:8 row_mask:0xf bank_mask:0xf
	v_add_f32_dpp v72, v38, v72 row_ror:8 row_mask:0xf bank_mask:0xf
	v_add_f32_dpp v73, v39, v73 row_ror:8 row_mask:0xf bank_mask:0xf
	s_mov_b32 s80, 0xf0f0f0f0
	s_mov_b32 s81, 0xf0f0f0f0
	v_cndmask_b32_e64 v32, v70, v66, s[80:81]
	v_cndmask_b32_e64 v66, v66, v70, s[80:81]
	v_cndmask_b32_e64 v33, v71, v67, s[80:81]
	v_cndmask_b32_e64 v67, v67, v71, s[80:81]
	v_cndmask_b32_e64 v34, v72, v68, s[80:81]
	v_cndmask_b32_e64 v68, v68, v72, s[80:81]
	v_cndmask_b32_e64 v35, v73, v69, s[80:81]
	v_cndmask_b32_e64 v69, v69, v73, s[80:81]
	ds_bpermute_b32 v32, v214, v32
	ds_bpermute_b32 v33, v214, v33
	ds_bpermute_b32 v34, v214, v34
	ds_bpermute_b32 v35, v214, v35
	s_waitcnt lgkmcnt(0)
	v_add_f32_e32 v66, v32, v66
	v_add_f32_e32 v67, v33, v67
	v_add_f32_e32 v68, v34, v68
	v_add_f32_e32 v69, v35, v69
	s_mov_b32 s80, 0xcccccccc
	s_mov_b32 s81, 0xcccccccc
	v_cndmask_b32_e64 v32, v68, v66, s[80:81]
	v_cndmask_b32_e64 v66, v66, v68, s[80:81]
	v_cndmask_b32_e64 v33, v69, v67, s[80:81]
	v_cndmask_b32_e64 v67, v67, v69, s[80:81]
	s_nop 1
	v_add_f32_dpp v66, v32, v66 quad_perm:[2,3,0,1] row_mask:0xf bank_mask:0xf
	v_add_f32_dpp v67, v33, v67 quad_perm:[2,3,0,1] row_mask:0xf bank_mask:0xf
	s_mov_b32 s80, 0xaaaaaaaa
	s_mov_b32 s81, 0xaaaaaaaa
	v_cndmask_b32_e64 v32, v67, v66, s[80:81]
	v_cndmask_b32_e64 v66, v66, v67, s[80:81]
	s_nop 1
	v_add_f32_dpp v66, v32, v66 quad_perm:[1,0,3,2] row_mask:0xf bank_mask:0xf
	v_and_b32_e32 v33, 31, v210
	v_lshlrev_b32_e32 v33, 5, v33
	v_lshl_add_u32 v33, v212, 3, v33
	v_bfe_u32 v34, v210, 5, 1
	v_lshl_add_u32 v33, v34, 2, v33
	ds_write_b32 v33, v66 offset:63488
	s_waitcnt lgkmcnt(0)
	s_barrier
	v_and_b32_e32 v33, 31, v210
	v_lshlrev_b32_e32 v33, 5, v33
	ds_read_b128 v[36:39], v33 offset:63488
	ds_read_b128 v[40:43], v33 offset:63504
	s_waitcnt lgkmcnt(0)
	v_add_f32_e32 v44, v36, v38
	v_add_f32_e32 v45, v37, v39
	v_add_f32_e32 v44, v40, v44
	v_add_f32_e32 v45, v41, v45
	v_add_f32_e32 v44, v42, v44
	v_add_f32_e32 v45, v43, v45
	v_mul_f32_e32 v46, 0x3b000000, v44
	v_mul_f32_e32 v45, 0x3b000000, v45
	v_fma_f32 v47, v46, v46, -v45
	v_sub_f32_e32 v47, 0, v47
	v_max_f32_e32 v47, 0, v47
	v_add_f32_e32 v47, 0x358637bd, v47
	v_rsq_f32_e32 v47, v47
	s_nop 0
	v_readlane_b32 s82, v46, 0
	v_readlane_b32 s83, v47, 0
	s_nop 1
	v_subrev_f32_e32 v48, s82, v128
	v_mul_f32_e32 v48, s83, v48
	v_fma_f32 v48, v48, v194, v196
	v_mul_f32_e32 v49, 0xbfb8aa3b, v48
	v_exp_f32_e32 v49, v49
	s_nop 0
	v_add_f32_e32 v49, 0x3f800000, v49
	v_rcp_f32_e32 v49, v49
	s_nop 0
	v_mul_f32_e32 v50, v48, v49
	v_subrev_f32_e32 v48, s82, v129
	v_mul_f32_e32 v48, s83, v48
	v_fma_f32 v48, v48, v195, v197
	v_mul_f32_e32 v49, 0xbfb8aa3b, v48
	v_exp_f32_e32 v49, v49
	s_nop 0
	v_add_f32_e32 v49, 0x3f800000, v49
	v_rcp_f32_e32 v49, v49
	s_nop 0
	v_mul_f32_e32 v51, v48, v49
	v_cvt_pk_bf16_f32 v52, v50, v51
	global_store_dword v209, v52, s[2:3]
	s_add_u32 s2, s2, 0x880
	s_addc_u32 s3, s3, 0
	v_readlane_b32 s82, v46, 1
	v_readlane_b32 s83, v47, 1
	s_nop 1
	v_subrev_f32_e32 v48, s82, v130
	v_mul_f32_e32 v48, s83, v48
	v_fma_f32 v48, v48, v194, v196
	v_mul_f32_e32 v49, 0xbfb8aa3b, v48
	v_exp_f32_e32 v49, v49
	s_nop 0
	v_add_f32_e32 v49, 0x3f800000, v49
	v_rcp_f32_e32 v49, v49
	s_nop 0
	v_mul_f32_e32 v50, v48, v49
	v_subrev_f32_e32 v48, s82, v131
	v_mul_f32_e32 v48, s83, v48
	v_fma_f32 v48, v48, v195, v197
	v_mul_f32_e32 v49, 0xbfb8aa3b, v48
	v_exp_f32_e32 v49, v49
	s_nop 0
	v_add_f32_e32 v49, 0x3f800000, v49
	v_rcp_f32_e32 v49, v49
	s_nop 0
	v_mul_f32_e32 v51, v48, v49
	v_cvt_pk_bf16_f32 v52, v50, v51
	global_store_dword v209, v52, s[2:3]
	s_add_u32 s2, s2, 0x880
	s_addc_u32 s3, s3, 0
	v_readlane_b32 s82, v46, 2
	v_readlane_b32 s83, v47, 2
	s_nop 1
	v_subrev_f32_e32 v48, s82, v132
	v_mul_f32_e32 v48, s83, v48
	v_fma_f32 v48, v48, v194, v196
	v_mul_f32_e32 v49, 0xbfb8aa3b, v48
	v_exp_f32_e32 v49, v49
	s_nop 0
	v_add_f32_e32 v49, 0x3f800000, v49
	v_rcp_f32_e32 v49, v49
	s_nop 0
	v_mul_f32_e32 v50, v48, v49
	v_subrev_f32_e32 v48, s82, v133
	v_mul_f32_e32 v48, s83, v48
	v_fma_f32 v48, v48, v195, v197
; DEVI unsigned pack2(float a, float b) { return (unsigned)f2bf(a) | ((unsigned)f2bf(b) << 16); }
; DEVI float sigmoidf_(float x) { return __builtin_amdgcn_rcpf(1.f + __expf(-x)); }
; DEVI void conv_tile(const Params& p, unsigned char* smem, int ct) {
;     ...
;   for (int tt = 0; tt < 32; ++tt) {
;     const float y0 = ya[tt], y1 = yb[tt];
;     const float2 r0 = sRed[tt * 4 + 0], r1 = sRed[tt * 4 + 1], r2 = sRed[tt * 4 + 2], r3 = sRed[tt * 4 + 3];
;     const float S = r0.x + r1.x + r2.x + r3.x, Q = r0.y + r1.y + r2.y + r3.y;
;     const float mu = S * (1.f / 512.f);
;     const float var = fmaxf(Q * (1.f / 512.f) - mu * mu, 0.f);
;     const float rstd = rsqrtf(var + 1e-6f);
;     const float z0 = (y0 - mu) * rstd * g0 + lb0, z1 = (y1 - mu) * rstd * g1 + lb1;
;     const float o0 = z0 * sigmoidf_(z0), o1 = z1 * sigmoidf_(z1);
;     *(unsigned*)(p.mix + ((size_t)b * T + t0 + tt) * LDA + c) = pack2(o0, o1);
;   }
	v_mul_f32_e32 v49, 0xbfb8aa3b, v48
	v_exp_f32_e32 v49, v49
	s_nop 0
	v_add_f32_e32 v49, 0x3f800000, v49
	v_rcp_f32_e32 v49, v49
	s_nop 0
	v_mul_f32_e32 v51, v48, v49
	v_cvt_pk_bf16_f32 v52, v50, v51
	global_store_dword v209, v52, s[2:3]
	s_add_u32 s2, s2, 0x880
	s_addc_u32 s3, s3, 0
	v_readlane_b32 s82, v46, 3
	v_readlane_b32 s83, v47, 3
	s_nop 1
	v_subrev_f32_e32 v48, s82, v134
	v_mul_f32_e32 v48, s83, v48
	v_fma_f32 v48, v48, v194, v196
	v_mul_f32_e32 v49, 0xbfb8aa3b, v48
	v_exp_f32_e32 v49, v49
	s_nop 0
	v_add_f32_e32 v49, 0x3f800000, v49
	v_rcp_f32_e32 v49, v49
	s_nop 0
	v_mul_f32_e32 v50, v48, v49
	v_subrev_f32_e32 v48, s82, v135
	v_mul_f32_e32 v48, s83, v48
	v_fma_f32 v48, v48, v195, v197
	v_mul_f32_e32 v49, 0xbfb8aa3b, v48
	v_exp_f32_e32 v49, v49
	s_nop 0
	v_add_f32_e32 v49, 0x3f800000, v49
	v_rcp_f32_e32 v49, v49
	s_nop 0
	v_mul_f32_e32 v51, v48, v49
	v_cvt_pk_bf16_f32 v52, v50, v51
	global_store_dword v209, v52, s[2:3]
	s_add_u32 s2, s2, 0x880
	s_addc_u32 s3, s3, 0
	v_readlane_b32 s82, v46, 4
	v_readlane_b32 s83, v47, 4
	s_nop 1
	v_subrev_f32_e32 v48, s82, v136
	v_mul_f32_e32 v48, s83, v48
	v_fma_f32 v48, v48, v194, v196
	v_mul_f32_e32 v49, 0xbfb8aa3b, v48
	v_exp_f32_e32 v49, v49
	s_nop 0
	v_add_f32_e32 v49, 0x3f800000, v49
	v_rcp_f32_e32 v49, v49
	s_nop 0
	v_mul_f32_e32 v50, v48, v49
	v_subrev_f32_e32 v48, s82, v137
	v_mul_f32_e32 v48, s83, v48
	v_fma_f32 v48, v48, v195, v197
	v_mul_f32_e32 v49, 0xbfb8aa3b, v48
	v_exp_f32_e32 v49, v49
	s_nop 0
	v_add_f32_e32 v49, 0x3f800000, v49
	v_rcp_f32_e32 v49, v49
	s_nop 0
	v_mul_f32_e32 v51, v48, v49
	v_cvt_pk_bf16_f32 v52, v50, v51
	global_store_dword v209, v52, s[2:3]
	s_add_u32 s2, s2, 0x880
	s_addc_u32 s3, s3, 0
	v_readlane_b32 s82, v46, 5
	v_readlane_b32 s83, v47, 5
	s_nop 1
	v_subrev_f32_e32 v48, s82, v138
	v_mul_f32_e32 v48, s83, v48
	v_fma_f32 v48, v48, v194, v196
	v_mul_f32_e32 v49, 0xbfb8aa3b, v48
	v_exp_f32_e32 v49, v49
	s_nop 0
	v_add_f32_e32 v49, 0x3f800000, v49
	v_rcp_f32_e32 v49, v49
	s_nop 0
	v_mul_f32_e32 v50, v48, v49
	v_subrev_f32_e32 v48, s82, v139
	v_mul_f32_e32 v48, s83, v48
	v_fma_f32 v48, v48, v195, v197
	v_mul_f32_e32 v49, 0xbfb8aa3b, v48
	v_exp_f32_e32 v49, v49
	s_nop 0
	v_add_f32_e32 v49, 0x3f800000, v49
	v_rcp_f32_e32 v49, v49
	s_nop 0
	v_mul_f32_e32 v51, v48, v49
	v_cvt_pk_bf16_f32 v52, v50, v51
	global_store_dword v209, v52, s[2:3]
	s_add_u32 s2, s2, 0x880
	s_addc_u32 s3, s3, 0
	v_readlane_b32 s82, v46, 6
	v_readlane_b32 s83, v47, 6
	s_nop 1
	v_subrev_f32_e32 v48, s82, v140
	v_mul_f32_e32 v48, s83, v48
	v_fma_f32 v48, v48, v194, v196
	v_mul_f32_e32 v49, 0xbfb8aa3b, v48
	v_exp_f32_e32 v49, v49
	s_nop 0
	v_add_f32_e32 v49, 0x3f800000, v49
	v_rcp_f32_e32 v49, v49
	s_nop 0
	v_mul_f32_e32 v50, v48, v49
	v_subrev_f32_e32 v48, s82, v141
	v_mul_f32_e32 v48, s83, v48
	v_fma_f32 v48, v48, v195, v197
	v_mul_f32_e32 v49, 0xbfb8aa3b, v48
	v_exp_f32_e32 v49, v49
	s_nop 0
	v_add_f32_e32 v49, 0x3f800000, v49
	v_rcp_f32_e32 v49, v49
	s_nop 0
	v_mul_f32_e32 v51, v48, v49
	v_cvt_pk_bf16_f32 v52, v50, v51
	global_store_dword v209, v52, s[2:3]
	s_add_u32 s2, s2, 0x880
	s_addc_u32 s3, s3, 0
	v_readlane_b32 s82, v46, 7
	v_readlane_b32 s83, v47, 7
	s_nop 1
	v_subrev_f32_e32 v48, s82, v142
	v_mul_f32_e32 v48, s83, v48
	v_fma_f32 v48, v48, v194, v196
	v_mul_f32_e32 v49, 0xbfb8aa3b, v48
	v_exp_f32_e32 v49, v49
	s_nop 0
	v_add_f32_e32 v49, 0x3f800000, v49
	v_rcp_f32_e32 v49, v49
	s_nop 0
	v_mul_f32_e32 v50, v48, v49
	v_subrev_f32_e32 v48, s82, v143
	v_mul_f32_e32 v48, s83, v48
	v_fma_f32 v48, v48, v195, v197
	v_mul_f32_e32 v49, 0xbfb8aa3b, v48
	v_exp_f32_e32 v49, v49
	s_nop 0
	v_add_f32_e32 v49, 0x3f800000, v49
	v_rcp_f32_e32 v49, v49
	s_nop 0
	v_mul_f32_e32 v51, v48, v49
	v_cvt_pk_bf16_f32 v52, v50, v51
	global_store_dword v209, v52, s[2:3]
	s_add_u32 s2, s2, 0x880
	s_addc_u32 s3, s3, 0
	v_readlane_b32 s82, v46, 8
	v_readlane_b32 s83, v47, 8
	s_nop 1
	v_subrev_f32_e32 v48, s82, v144
	v_mul_f32_e32 v48, s83, v48
	v_fma_f32 v48, v48, v194, v196
	v_mul_f32_e32 v49, 0xbfb8aa3b, v48
	v_exp_f32_e32 v49, v49
	s_nop 0
	v_add_f32_e32 v49, 0x3f800000, v49
	v_rcp_f32_e32 v49, v49
	s_nop 0
	v_mul_f32_e32 v50, v48, v49
	v_subrev_f32_e32 v48, s82, v145
	v_mul_f32_e32 v48, s83, v48
	v_fma_f32 v48, v48, v195, v197
	v_mul_f32_e32 v49, 0xbfb8aa3b, v48
	v_exp_f32_e32 v49, v49
	s_nop 0
	v_add_f32_e32 v49, 0x3f800000, v49
	v_rcp_f32_e32 v49, v49
	s_nop 0
	v_mul_f32_e32 v51, v48, v49
	v_cvt_pk_bf16_f32 v52, v50, v51
	global_store_dword v209, v52, s[2:3]
	s_add_u32 s2, s2, 0x880
	s_addc_u32 s3, s3, 0
	v_readlane_b32 s82, v46, 9
	v_readlane_b32 s83, v47, 9
	s_nop 1
	v_subrev_f32_e32 v48, s82, v146
	v_mul_f32_e32 v48, s83, v48
	v_fma_f32 v48, v48, v194, v196
	v_mul_f32_e32 v49, 0xbfb8aa3b, v48
	v_exp_f32_e32 v49, v49
	s_nop 0
	v_add_f32_e32 v49, 0x3f800000, v49
	v_rcp_f32_e32 v49, v49
	s_nop 0
	v_mul_f32_e32 v50, v48, v49
	v_subrev_f32_e32 v48, s82, v147
	v_mul_f32_e32 v48, s83, v48
	v_fma_f32 v48, v48, v195, v197
	v_mul_f32_e32 v49, 0xbfb8aa3b, v48
	v_exp_f32_e32 v49, v49
	s_nop 0
	v_add_f32_e32 v49, 0x3f800000, v49
	v_rcp_f32_e32 v49, v49
	s_nop 0
	v_mul_f32_e32 v51, v48, v49
	v_cvt_pk_bf16_f32 v52, v50, v51
	global_store_dword v209, v52, s[2:3]
	s_add_u32 s2, s2, 0x880
	s_addc_u32 s3, s3, 0
	v_readlane_b32 s82, v46, 10
	v_readlane_b32 s83, v47, 10
	s_nop 1
	v_subrev_f32_e32 v48, s82, v148
	v_mul_f32_e32 v48, s83, v48
	v_fma_f32 v48, v48, v194, v196
	v_mul_f32_e32 v49, 0xbfb8aa3b, v48
	v_exp_f32_e32 v49, v49
	s_nop 0
	v_add_f32_e32 v49, 0x3f800000, v49
	v_rcp_f32_e32 v49, v49
	s_nop 0
	v_mul_f32_e32 v50, v48, v49
	v_subrev_f32_e32 v48, s82, v149
	v_mul_f32_e32 v48, s83, v48
	v_fma_f32 v48, v48, v195, v197
; DEVI unsigned pack2(float a, float b) { return (unsigned)f2bf(a) | ((unsigned)f2bf(b) << 16); }
; DEVI float sigmoidf_(float x) { return __builtin_amdgcn_rcpf(1.f + __expf(-x)); }
; DEVI void conv_tile(const Params& p, unsigned char* smem, int ct) {
;     ...
;   for (int tt = 0; tt < 32; ++tt) {
;     const float y0 = ya[tt], y1 = yb[tt];
;     const float2 r0 = sRed[tt * 4 + 0], r1 = sRed[tt * 4 + 1], r2 = sRed[tt * 4 + 2], r3 = sRed[tt * 4 + 3];
;     const float S = r0.x + r1.x + r2.x + r3.x, Q = r0.y + r1.y + r2.y + r3.y;
;     const float mu = S * (1.f / 512.f);
;     const float var = fmaxf(Q * (1.f / 512.f) - mu * mu, 0.f);
;     const float rstd = rsqrtf(var + 1e-6f);
;     const float z0 = (y0 - mu) * rstd * g0 + lb0, z1 = (y1 - mu) * rstd * g1 + lb1;
;     const float o0 = z0 * sigmoidf_(z0), o1 = z1 * sigmoidf_(z1);
;     *(unsigned*)(p.mix + ((size_t)b * T + t0 + tt) * LDA + c) = pack2(o0, o1);
;   }
	v_mul_f32_e32 v49, 0xbfb8aa3b, v48
	v_exp_f32_e32 v49, v49
	s_nop 0
	v_add_f32_e32 v49, 0x3f800000, v49
	v_rcp_f32_e32 v49, v49
	s_nop 0
	v_mul_f32_e32 v51, v48, v49
	v_cvt_pk_bf16_f32 v52, v50, v51
	global_store_dword v209, v52, s[2:3]
	s_add_u32 s2, s2, 0x880
	s_addc_u32 s3, s3, 0
	v_readlane_b32 s82, v46, 11
	v_readlane_b32 s83, v47, 11
	s_nop 1
	v_subrev_f32_e32 v48, s82, v150
	v_mul_f32_e32 v48, s83, v48
	v_fma_f32 v48, v48, v194, v196
	v_mul_f32_e32 v49, 0xbfb8aa3b, v48
	v_exp_f32_e32 v49, v49
	s_nop 0
	v_add_f32_e32 v49, 0x3f800000, v49
	v_rcp_f32_e32 v49, v49
	s_nop 0
	v_mul_f32_e32 v50, v48, v49
	v_subrev_f32_e32 v48, s82, v151
	v_mul_f32_e32 v48, s83, v48
	v_fma_f32 v48, v48, v195, v197
	v_mul_f32_e32 v49, 0xbfb8aa3b, v48
	v_exp_f32_e32 v49, v49
	s_nop 0
	v_add_f32_e32 v49, 0x3f800000, v49
	v_rcp_f32_e32 v49, v49
	s_nop 0
	v_mul_f32_e32 v51, v48, v49
	v_cvt_pk_bf16_f32 v52, v50, v51
	global_store_dword v209, v52, s[2:3]
	s_add_u32 s2, s2, 0x880
	s_addc_u32 s3, s3, 0
	v_readlane_b32 s82, v46, 12
	v_readlane_b32 s83, v47, 12
	s_nop 1
	v_subrev_f32_e32 v48, s82, v152
	v_mul_f32_e32 v48, s83, v48
	v_fma_f32 v48, v48, v194, v196
	v_mul_f32_e32 v49, 0xbfb8aa3b, v48
	v_exp_f32_e32 v49, v49
	s_nop 0
	v_add_f32_e32 v49, 0x3f800000, v49
	v_rcp_f32_e32 v49, v49
	s_nop 0
	v_mul_f32_e32 v50, v48, v49
	v_subrev_f32_e32 v48, s82, v153
	v_mul_f32_e32 v48, s83, v48
	v_fma_f32 v48, v48, v195, v197
	v_mul_f32_e32 v49, 0xbfb8aa3b, v48
	v_exp_f32_e32 v49, v49
	s_nop 0
	v_add_f32_e32 v49, 0x3f800000, v49
	v_rcp_f32_e32 v49, v49
	s_nop 0
	v_mul_f32_e32 v51, v48, v49
	v_cvt_pk_bf16_f32 v52, v50, v51
	global_store_dword v209, v52, s[2:3]
	s_add_u32 s2, s2, 0x880
	s_addc_u32 s3, s3, 0
	v_readlane_b32 s82, v46, 13
	v_readlane_b32 s83, v47, 13
	s_nop 1
	v_subrev_f32_e32 v48, s82, v154
	v_mul_f32_e32 v48, s83, v48
	v_fma_f32 v48, v48, v194, v196
	v_mul_f32_e32 v49, 0xbfb8aa3b, v48
	v_exp_f32_e32 v49, v49
	s_nop 0
	v_add_f32_e32 v49, 0x3f800000, v49
	v_rcp_f32_e32 v49, v49
	s_nop 0
	v_mul_f32_e32 v50, v48, v49
	v_subrev_f32_e32 v48, s82, v155
	v_mul_f32_e32 v48, s83, v48
	v_fma_f32 v48, v48, v195, v197
	v_mul_f32_e32 v49, 0xbfb8aa3b, v48
	v_exp_f32_e32 v49, v49
	s_nop 0
	v_add_f32_e32 v49, 0x3f800000, v49
	v_rcp_f32_e32 v49, v49
	s_nop 0
	v_mul_f32_e32 v51, v48, v49
	v_cvt_pk_bf16_f32 v52, v50, v51
	global_store_dword v209, v52, s[2:3]
	s_add_u32 s2, s2, 0x880
	s_addc_u32 s3, s3, 0
	v_readlane_b32 s82, v46, 14
	v_readlane_b32 s83, v47, 14
	s_nop 1
	v_subrev_f32_e32 v48, s82, v156
	v_mul_f32_e32 v48, s83, v48
	v_fma_f32 v48, v48, v194, v196
	v_mul_f32_e32 v49, 0xbfb8aa3b, v48
	v_exp_f32_e32 v49, v49
	s_nop 0
	v_add_f32_e32 v49, 0x3f800000, v49
	v_rcp_f32_e32 v49, v49
	s_nop 0
	v_mul_f32_e32 v50, v48, v49
	v_subrev_f32_e32 v48, s82, v157
	v_mul_f32_e32 v48, s83, v48
	v_fma_f32 v48, v48, v195, v197
	v_mul_f32_e32 v49, 0xbfb8aa3b, v48
	v_exp_f32_e32 v49, v49
	s_nop 0
	v_add_f32_e32 v49, 0x3f800000, v49
	v_rcp_f32_e32 v49, v49
	s_nop 0
	v_mul_f32_e32 v51, v48, v49
	v_cvt_pk_bf16_f32 v52, v50, v51
	global_store_dword v209, v52, s[2:3]
	s_add_u32 s2, s2, 0x880
	s_addc_u32 s3, s3, 0
	v_readlane_b32 s82, v46, 15
	v_readlane_b32 s83, v47, 15
	s_nop 1
	v_subrev_f32_e32 v48, s82, v158
	v_mul_f32_e32 v48, s83, v48
	v_fma_f32 v48, v48, v194, v196
	v_mul_f32_e32 v49, 0xbfb8aa3b, v48
	v_exp_f32_e32 v49, v49
	s_nop 0
	v_add_f32_e32 v49, 0x3f800000, v49
	v_rcp_f32_e32 v49, v49
	s_nop 0
	v_mul_f32_e32 v50, v48, v49
	v_subrev_f32_e32 v48, s82, v159
	v_mul_f32_e32 v48, s83, v48
	v_fma_f32 v48, v48, v195, v197
	v_mul_f32_e32 v49, 0xbfb8aa3b, v48
	v_exp_f32_e32 v49, v49
	s_nop 0
	v_add_f32_e32 v49, 0x3f800000, v49
	v_rcp_f32_e32 v49, v49
	s_nop 0
	v_mul_f32_e32 v51, v48, v49
	v_cvt_pk_bf16_f32 v52, v50, v51
	global_store_dword v209, v52, s[2:3]
	s_add_u32 s2, s2, 0x880
	s_addc_u32 s3, s3, 0
	v_readlane_b32 s82, v46, 16
	v_readlane_b32 s83, v47, 16
	s_nop 1
	v_subrev_f32_e32 v48, s82, v160
	v_mul_f32_e32 v48, s83, v48
	v_fma_f32 v48, v48, v194, v196
	v_mul_f32_e32 v49, 0xbfb8aa3b, v48
	v_exp_f32_e32 v49, v49
	s_nop 0
	v_add_f32_e32 v49, 0x3f800000, v49
	v_rcp_f32_e32 v49, v49
	s_nop 0
	v_mul_f32_e32 v50, v48, v49
	v_subrev_f32_e32 v48, s82, v161
	v_mul_f32_e32 v48, s83, v48
	v_fma_f32 v48, v48, v195, v197
	v_mul_f32_e32 v49, 0xbfb8aa3b, v48
	v_exp_f32_e32 v49, v49
	s_nop 0
	v_add_f32_e32 v49, 0x3f800000, v49
	v_rcp_f32_e32 v49, v49
	s_nop 0
	v_mul_f32_e32 v51, v48, v49
	v_cvt_pk_bf16_f32 v52, v50, v51
	global_store_dword v209, v52, s[2:3]
	s_add_u32 s2, s2, 0x880
	s_addc_u32 s3, s3, 0
	v_readlane_b32 s82, v46, 17
	v_readlane_b32 s83, v47, 17
	s_nop 1
	v_subrev_f32_e32 v48, s82, v162
	v_mul_f32_e32 v48, s83, v48
	v_fma_f32 v48, v48, v194, v196
	v_mul_f32_e32 v49, 0xbfb8aa3b, v48
	v_exp_f32_e32 v49, v49
	s_nop 0
	v_add_f32_e32 v49, 0x3f800000, v49
	v_rcp_f32_e32 v49, v49
	s_nop 0
	v_mul_f32_e32 v50, v48, v49
	v_subrev_f32_e32 v48, s82, v163
	v_mul_f32_e32 v48, s83, v48
	v_fma_f32 v48, v48, v195, v197
	v_mul_f32_e32 v49, 0xbfb8aa3b, v48
	v_exp_f32_e32 v49, v49
	s_nop 0
	v_add_f32_e32 v49, 0x3f800000, v49
	v_rcp_f32_e32 v49, v49
	s_nop 0
	v_mul_f32_e32 v51, v48, v49
	v_cvt_pk_bf16_f32 v52, v50, v51
	global_store_dword v209, v52, s[2:3]
	s_add_u32 s2, s2, 0x880
	s_addc_u32 s3, s3, 0
	v_readlane_b32 s82, v46, 18
	v_readlane_b32 s83, v47, 18
	s_nop 1
	v_subrev_f32_e32 v48, s82, v164
	v_mul_f32_e32 v48, s83, v48
	v_fma_f32 v48, v48, v194, v196
	v_mul_f32_e32 v49, 0xbfb8aa3b, v48
	v_exp_f32_e32 v49, v49
	s_nop 0
	v_add_f32_e32 v49, 0x3f800000, v49
	v_rcp_f32_e32 v49, v49
	s_nop 0
	v_mul_f32_e32 v50, v48, v49
	v_subrev_f32_e32 v48, s82, v165
	v_mul_f32_e32 v48, s83, v48
; DEVI unsigned pack2(float a, float b) { return (unsigned)f2bf(a) | ((unsigned)f2bf(b) << 16); }
; DEVI float sigmoidf_(float x) { return __builtin_amdgcn_rcpf(1.f + __expf(-x)); }
; DEVI void conv_tile(const Params& p, unsigned char* smem, int ct) {
;     ...
;   for (int tt = 0; tt < 32; ++tt) {
;     const float y0 = ya[tt], y1 = yb[tt];
;     const float2 r0 = sRed[tt * 4 + 0], r1 = sRed[tt * 4 + 1], r2 = sRed[tt * 4 + 2], r3 = sRed[tt * 4 + 3];
;     const float S = r0.x + r1.x + r2.x + r3.x, Q = r0.y + r1.y + r2.y + r3.y;
;     const float mu = S * (1.f / 512.f);
;     const float var = fmaxf(Q * (1.f / 512.f) - mu * mu, 0.f);
;     const float rstd = rsqrtf(var + 1e-6f);
;     const float z0 = (y0 - mu) * rstd * g0 + lb0, z1 = (y1 - mu) * rstd * g1 + lb1;
;     const float o0 = z0 * sigmoidf_(z0), o1 = z1 * sigmoidf_(z1);
;     *(unsigned*)(p.mix + ((size_t)b * T + t0 + tt) * LDA + c) = pack2(o0, o1);
;   }
	v_fma_f32 v48, v48, v195, v197
	v_mul_f32_e32 v49, 0xbfb8aa3b, v48
	v_exp_f32_e32 v49, v49
	s_nop 0
	v_add_f32_e32 v49, 0x3f800000, v49
	v_rcp_f32_e32 v49, v49
	s_nop 0
	v_mul_f32_e32 v51, v48, v49
	v_cvt_pk_bf16_f32 v52, v50, v51
	global_store_dword v209, v52, s[2:3]
	s_add_u32 s2, s2, 0x880
	s_addc_u32 s3, s3, 0
	v_readlane_b32 s82, v46, 19
	v_readlane_b32 s83, v47, 19
	s_nop 1
	v_subrev_f32_e32 v48, s82, v166
	v_mul_f32_e32 v48, s83, v48
	v_fma_f32 v48, v48, v194, v196
	v_mul_f32_e32 v49, 0xbfb8aa3b, v48
	v_exp_f32_e32 v49, v49
	s_nop 0
	v_add_f32_e32 v49, 0x3f800000, v49
	v_rcp_f32_e32 v49, v49
	s_nop 0
	v_mul_f32_e32 v50, v48, v49
	v_subrev_f32_e32 v48, s82, v167
	v_mul_f32_e32 v48, s83, v48
	v_fma_f32 v48, v48, v195, v197
	v_mul_f32_e32 v49, 0xbfb8aa3b, v48
	v_exp_f32_e32 v49, v49
	s_nop 0
	v_add_f32_e32 v49, 0x3f800000, v49
	v_rcp_f32_e32 v49, v49
	s_nop 0
	v_mul_f32_e32 v51, v48, v49
	v_cvt_pk_bf16_f32 v52, v50, v51
	global_store_dword v209, v52, s[2:3]
	s_add_u32 s2, s2, 0x880
	s_addc_u32 s3, s3, 0
	v_readlane_b32 s82, v46, 20
	v_readlane_b32 s83, v47, 20
	s_nop 1
	v_subrev_f32_e32 v48, s82, v168
	v_mul_f32_e32 v48, s83, v48
	v_fma_f32 v48, v48, v194, v196
	v_mul_f32_e32 v49, 0xbfb8aa3b, v48
	v_exp_f32_e32 v49, v49
	s_nop 0
	v_add_f32_e32 v49, 0x3f800000, v49
	v_rcp_f32_e32 v49, v49
	s_nop 0
	v_mul_f32_e32 v50, v48, v49
	v_subrev_f32_e32 v48, s82, v169
	v_mul_f32_e32 v48, s83, v48
	v_fma_f32 v48, v48, v195, v197
	v_mul_f32_e32 v49, 0xbfb8aa3b, v48
	v_exp_f32_e32 v49, v49
	s_nop 0
	v_add_f32_e32 v49, 0x3f800000, v49
	v_rcp_f32_e32 v49, v49
	s_nop 0
	v_mul_f32_e32 v51, v48, v49
	v_cvt_pk_bf16_f32 v52, v50, v51
	global_store_dword v209, v52, s[2:3]
	s_add_u32 s2, s2, 0x880
	s_addc_u32 s3, s3, 0
	v_readlane_b32 s82, v46, 21
	v_readlane_b32 s83, v47, 21
	s_nop 1
	v_subrev_f32_e32 v48, s82, v170
	v_mul_f32_e32 v48, s83, v48
	v_fma_f32 v48, v48, v194, v196
	v_mul_f32_e32 v49, 0xbfb8aa3b, v48
	v_exp_f32_e32 v49, v49
	s_nop 0
	v_add_f32_e32 v49, 0x3f800000, v49
	v_rcp_f32_e32 v49, v49
	s_nop 0
	v_mul_f32_e32 v50, v48, v49
	v_subrev_f32_e32 v48, s82, v171
	v_mul_f32_e32 v48, s83, v48
	v_fma_f32 v48, v48, v195, v197
	v_mul_f32_e32 v49, 0xbfb8aa3b, v48
	v_exp_f32_e32 v49, v49
	s_nop 0
	v_add_f32_e32 v49, 0x3f800000, v49
	v_rcp_f32_e32 v49, v49
	s_nop 0
	v_mul_f32_e32 v51, v48, v49
	v_cvt_pk_bf16_f32 v52, v50, v51
	global_store_dword v209, v52, s[2:3]
	s_add_u32 s2, s2, 0x880
	s_addc_u32 s3, s3, 0
	v_readlane_b32 s82, v46, 22
	v_readlane_b32 s83, v47, 22
	s_nop 1
	v_subrev_f32_e32 v48, s82, v172
	v_mul_f32_e32 v48, s83, v48
	v_fma_f32 v48, v48, v194, v196
	v_mul_f32_e32 v49, 0xbfb8aa3b, v48
	v_exp_f32_e32 v49, v49
	s_nop 0
	v_add_f32_e32 v49, 0x3f800000, v49
	v_rcp_f32_e32 v49, v49
	s_nop 0
	v_mul_f32_e32 v50, v48, v49
	v_subrev_f32_e32 v48, s82, v173
	v_mul_f32_e32 v48, s83, v48
	v_fma_f32 v48, v48, v195, v197
	v_mul_f32_e32 v49, 0xbfb8aa3b, v48
	v_exp_f32_e32 v49, v49
	s_nop 0
	v_add_f32_e32 v49, 0x3f800000, v49
	v_rcp_f32_e32 v49, v49
	s_nop 0
	v_mul_f32_e32 v51, v48, v49
	v_cvt_pk_bf16_f32 v52, v50, v51
	global_store_dword v209, v52, s[2:3]
	s_add_u32 s2, s2, 0x880
	s_addc_u32 s3, s3, 0
	v_readlane_b32 s82, v46, 23
	v_readlane_b32 s83, v47, 23
	s_nop 1
	v_subrev_f32_e32 v48, s82, v174
	v_mul_f32_e32 v48, s83, v48
	v_fma_f32 v48, v48, v194, v196
	v_mul_f32_e32 v49, 0xbfb8aa3b, v48
	v_exp_f32_e32 v49, v49
	s_nop 0
	v_add_f32_e32 v49, 0x3f800000, v49
	v_rcp_f32_e32 v49, v49
	s_nop 0
	v_mul_f32_e32 v50, v48, v49
	v_subrev_f32_e32 v48, s82, v175
	v_mul_f32_e32 v48, s83, v48
	v_fma_f32 v48, v48, v195, v197
	v_mul_f32_e32 v49, 0xbfb8aa3b, v48
	v_exp_f32_e32 v49, v49
	s_nop 0
	v_add_f32_e32 v49, 0x3f800000, v49
	v_rcp_f32_e32 v49, v49
	s_nop 0
	v_mul_f32_e32 v51, v48, v49
	v_cvt_pk_bf16_f32 v52, v50, v51
	global_store_dword v209, v52, s[2:3]
	s_add_u32 s2, s2, 0x880
	s_addc_u32 s3, s3, 0
	v_readlane_b32 s82, v46, 24
	v_readlane_b32 s83, v47, 24
	s_nop 1
	v_subrev_f32_e32 v48, s82, v176
	v_mul_f32_e32 v48, s83, v48
	v_fma_f32 v48, v48, v194, v196
	v_mul_f32_e32 v49, 0xbfb8aa3b, v48
	v_exp_f32_e32 v49, v49
	s_nop 0
	v_add_f32_e32 v49, 0x3f800000, v49
	v_rcp_f32_e32 v49, v49
	s_nop 0
	v_mul_f32_e32 v50, v48, v49
	v_subrev_f32_e32 v48, s82, v177
	v_mul_f32_e32 v48, s83, v48
	v_fma_f32 v48, v48, v195, v197
	v_mul_f32_e32 v49, 0xbfb8aa3b, v48
	v_exp_f32_e32 v49, v49
	s_nop 0
	v_add_f32_e32 v49, 0x3f800000, v49
	v_rcp_f32_e32 v49, v49
	s_nop 0
	v_mul_f32_e32 v51, v48, v49
	v_cvt_pk_bf16_f32 v52, v50, v51
	global_store_dword v209, v52, s[2:3]
	s_add_u32 s2, s2, 0x880
	s_addc_u32 s3, s3, 0
	v_readlane_b32 s82, v46, 25
	v_readlane_b32 s83, v47, 25
	s_nop 1
	v_subrev_f32_e32 v48, s82, v178
	v_mul_f32_e32 v48, s83, v48
	v_fma_f32 v48, v48, v194, v196
	v_mul_f32_e32 v49, 0xbfb8aa3b, v48
; DEVI unsigned pack2(float a, float b) { return (unsigned)f2bf(a) | ((unsigned)f2bf(b) << 16); }
; DEVI float sigmoidf_(float x) { return __builtin_amdgcn_rcpf(1.f + __expf(-x)); }
; DEVI void conv_tile(const Params& p, unsigned char* smem, int ct) {
;     ...
;   for (int tt = 0; tt < 32; ++tt) {
;     const float y0 = ya[tt], y1 = yb[tt];
;     const float2 r0 = sRed[tt * 4 + 0], r1 = sRed[tt * 4 + 1], r2 = sRed[tt * 4 + 2], r3 = sRed[tt * 4 + 3];
;     const float S = r0.x + r1.x + r2.x + r3.x, Q = r0.y + r1.y + r2.y + r3.y;
;     const float mu = S * (1.f / 512.f);
;     const float var = fmaxf(Q * (1.f / 512.f) - mu * mu, 0.f);
;     const float rstd = rsqrtf(var + 1e-6f);
;     const float z0 = (y0 - mu) * rstd * g0 + lb0, z1 = (y1 - mu) * rstd * g1 + lb1;
;     const float o0 = z0 * sigmoidf_(z0), o1 = z1 * sigmoidf_(z1);
;     *(unsigned*)(p.mix + ((size_t)b * T + t0 + tt) * LDA + c) = pack2(o0, o1);
;   }
	v_exp_f32_e32 v49, v49
	s_nop 0
	v_add_f32_e32 v49, 0x3f800000, v49
	v_rcp_f32_e32 v49, v49
	s_nop 0
	v_mul_f32_e32 v50, v48, v49
	v_subrev_f32_e32 v48, s82, v179
	v_mul_f32_e32 v48, s83, v48
	v_fma_f32 v48, v48, v195, v197
	v_mul_f32_e32 v49, 0xbfb8aa3b, v48
	v_exp_f32_e32 v49, v49
	s_nop 0
	v_add_f32_e32 v49, 0x3f800000, v49
	v_rcp_f32_e32 v49, v49
	s_nop 0
	v_mul_f32_e32 v51, v48, v49
	v_cvt_pk_bf16_f32 v52, v50, v51
	global_store_dword v209, v52, s[2:3]
	s_add_u32 s2, s2, 0x880
	s_addc_u32 s3, s3, 0
	v_readlane_b32 s82, v46, 26
	v_readlane_b32 s83, v47, 26
	s_nop 1
	v_subrev_f32_e32 v48, s82, v180
	v_mul_f32_e32 v48, s83, v48
	v_fma_f32 v48, v48, v194, v196
	v_mul_f32_e32 v49, 0xbfb8aa3b, v48
	v_exp_f32_e32 v49, v49
	s_nop 0
	v_add_f32_e32 v49, 0x3f800000, v49
	v_rcp_f32_e32 v49, v49
	s_nop 0
	v_mul_f32_e32 v50, v48, v49
	v_subrev_f32_e32 v48, s82, v181
	v_mul_f32_e32 v48, s83, v48
	v_fma_f32 v48, v48, v195, v197
	v_mul_f32_e32 v49, 0xbfb8aa3b, v48
	v_exp_f32_e32 v49, v49
	s_nop 0
	v_add_f32_e32 v49, 0x3f800000, v49
	v_rcp_f32_e32 v49, v49
	s_nop 0
	v_mul_f32_e32 v51, v48, v49
	v_cvt_pk_bf16_f32 v52, v50, v51
	global_store_dword v209, v52, s[2:3]
	s_add_u32 s2, s2, 0x880
	s_addc_u32 s3, s3, 0
	v_readlane_b32 s82, v46, 27
	v_readlane_b32 s83, v47, 27
	s_nop 1
	v_subrev_f32_e32 v48, s82, v182
	v_mul_f32_e32 v48, s83, v48
	v_fma_f32 v48, v48, v194, v196
	v_mul_f32_e32 v49, 0xbfb8aa3b, v48
	v_exp_f32_e32 v49, v49
	s_nop 0
	v_add_f32_e32 v49, 0x3f800000, v49
	v_rcp_f32_e32 v49, v49
	s_nop 0
	v_mul_f32_e32 v50, v48, v49
	v_subrev_f32_e32 v48, s82, v183
	v_mul_f32_e32 v48, s83, v48
	v_fma_f32 v48, v48, v195, v197
	v_mul_f32_e32 v49, 0xbfb8aa3b, v48
	v_exp_f32_e32 v49, v49
	s_nop 0
	v_add_f32_e32 v49, 0x3f800000, v49
	v_rcp_f32_e32 v49, v49
	s_nop 0
	v_mul_f32_e32 v51, v48, v49
	v_cvt_pk_bf16_f32 v52, v50, v51
	global_store_dword v209, v52, s[2:3]
	s_add_u32 s2, s2, 0x880
	s_addc_u32 s3, s3, 0
	v_readlane_b32 s82, v46, 28
	v_readlane_b32 s83, v47, 28
	s_nop 1
	v_subrev_f32_e32 v48, s82, v184
	v_mul_f32_e32 v48, s83, v48
	v_fma_f32 v48, v48, v194, v196
	v_mul_f32_e32 v49, 0xbfb8aa3b, v48
	v_exp_f32_e32 v49, v49
	s_nop 0
	v_add_f32_e32 v49, 0x3f800000, v49
	v_rcp_f32_e32 v49, v49
	s_nop 0
	v_mul_f32_e32 v50, v48, v49
	v_subrev_f32_e32 v48, s82, v185
	v_mul_f32_e32 v48, s83, v48
	v_fma_f32 v48, v48, v195, v197
	v_mul_f32_e32 v49, 0xbfb8aa3b, v48
	v_exp_f32_e32 v49, v49
	s_nop 0
	v_add_f32_e32 v49, 0x3f800000, v49
	v_rcp_f32_e32 v49, v49
	s_nop 0
	v_mul_f32_e32 v51, v48, v49
	v_cvt_pk_bf16_f32 v52, v50, v51
	global_store_dword v209, v52, s[2:3]
	s_add_u32 s2, s2, 0x880
	s_addc_u32 s3, s3, 0
	v_readlane_b32 s82, v46, 29
	v_readlane_b32 s83, v47, 29
	s_nop 1
	v_subrev_f32_e32 v48, s82, v186
	v_mul_f32_e32 v48, s83, v48
	v_fma_f32 v48, v48, v194, v196
	v_mul_f32_e32 v49, 0xbfb8aa3b, v48
	v_exp_f32_e32 v49, v49
	s_nop 0
	v_add_f32_e32 v49, 0x3f800000, v49
	v_rcp_f32_e32 v49, v49
	s_nop 0
	v_mul_f32_e32 v50, v48, v49
	v_subrev_f32_e32 v48, s82, v187
	v_mul_f32_e32 v48, s83, v48
	v_fma_f32 v48, v48, v195, v197
	v_mul_f32_e32 v49, 0xbfb8aa3b, v48
	v_exp_f32_e32 v49, v49
	s_nop 0
	v_add_f32_e32 v49, 0x3f800000, v49
	v_rcp_f32_e32 v49, v49
	s_nop 0
	v_mul_f32_e32 v51, v48, v49
	v_cvt_pk_bf16_f32 v52, v50, v51
	global_store_dword v209, v52, s[2:3]
	s_add_u32 s2, s2, 0x880
	s_addc_u32 s3, s3, 0
	v_readlane_b32 s82, v46, 30
	v_readlane_b32 s83, v47, 30
	s_nop 1
	v_subrev_f32_e32 v48, s82, v188
	v_mul_f32_e32 v48, s83, v48
	v_fma_f32 v48, v48, v194, v196
	v_mul_f32_e32 v49, 0xbfb8aa3b, v48
	v_exp_f32_e32 v49, v49
	s_nop 0
	v_add_f32_e32 v49, 0x3f800000, v49
	v_rcp_f32_e32 v49, v49
	s_nop 0
	v_mul_f32_e32 v50, v48, v49
	v_subrev_f32_e32 v48, s82, v189
	v_mul_f32_e32 v48, s83, v48
	v_fma_f32 v48, v48, v195, v197
	v_mul_f32_e32 v49, 0xbfb8aa3b, v48
	v_exp_f32_e32 v49, v49
	s_nop 0
	v_add_f32_e32 v49, 0x3f800000, v49
	v_rcp_f32_e32 v49, v49
	s_nop 0
	v_mul_f32_e32 v51, v48, v49
	v_cvt_pk_bf16_f32 v52, v50, v51
	global_store_dword v209, v52, s[2:3]
	s_add_u32 s2, s2, 0x880
	s_addc_u32 s3, s3, 0
	v_readlane_b32 s82, v46, 31
	v_readlane_b32 s83, v47, 31
	s_nop 1
	v_subrev_f32_e32 v48, s82, v190
	v_mul_f32_e32 v48, s83, v48
	v_fma_f32 v48, v48, v194, v196
	v_mul_f32_e32 v49, 0xbfb8aa3b, v48
	v_exp_f32_e32 v49, v49
	s_nop 0
	v_add_f32_e32 v49, 0x3f800000, v49
	v_rcp_f32_e32 v49, v49
	s_nop 0
	v_mul_f32_e32 v50, v48, v49
	v_subrev_f32_e32 v48, s82, v191
	v_mul_f32_e32 v48, s83, v48
	v_fma_f32 v48, v48, v195, v197
	v_mul_f32_e32 v49, 0xbfb8aa3b, v48
	v_exp_f32_e32 v49, v49
	s_nop 0
	v_add_f32_e32 v49, 0x3f800000, v49
	v_rcp_f32_e32 v49, v49
	s_nop 0
	v_mul_f32_e32 v51, v48, v49
	v_cvt_pk_bf16_f32 v52, v50, v51
	global_store_dword v209, v52, s[2:3]
	s_branch .LBB0_552
